# GEMM K-loops (P2/P5/P13): 42 LDS-DMA loads switched to the saddr form (SGPR base + 32-bit lane offset), their 64-bit VALU address adds deleted
# baseline (speedup 1.0000x reference)
; #define PG8_STAGE(bufoff, gbase, voff) do { _Pragma("unroll") for (int _i = 0; _i < 2; ++_i) \
;         __builtin_amdgcn_global_load_lds((const unsigned*)((const char*)(gbase) + (voff)[_i]), (LAS unsigned*)(lds + (bufoff) + ldsw + _i * 8192), 16, 0, 0); } while (0)
; #define PG8_WAIT_V(n) asm volatile("s_waitcnt vmcnt(" #n ")" ::: "memory")
; #define PG8_BAR __builtin_amdgcn_s_barrier()
; template <class Epi, class Order>
; __device__ __forceinline__ void gemm_phase(LAS unsigned char* lds, const Gemm g, const Order& S, const Epi& E) {
;     ...
;     for (int i = 0; i < 2; ++i) { int R, C; stage_rc(tid * 16 + i * 8192, R, C); const int Rb = Epi::PERM ? ((R & ~31) + perm32(R & 31)) : R;
;         voffA[i] = (unsigned)(R * g.ld + C) * 2u; voffB[i] = (unsigned)(Rb * g.ld + C) * 2u; }
;     const size_t kstep = (size_t)(BK * 2);
;     const size_t hstep = (size_t)HALF * g.ld * 2;
;     const size_t sstep = (size_t)K * 2;
;     const size_t tstep = 2 * hstep;
;     const unsigned ldsw = (unsigned)wid * 1024u;
;     const int aoff = lds_byte(wr * 64 + fr, fq * 8), boff = lds_byte(wc * 32 + fr, fq * 8);
;     ...
;     PG8_STAGE(PG8_SB(1, 0), cB + kstep, voffB); PG8_STAGE(PG8_SA(1, 0), cA + kstep, voffA); PG8_STAGE(PG8_SB(1, 1), cB + hstep + kstep, voffB);
;     PG8_WAIT_V(6); PG8_BAR;
.LBB0_218:
	s_add_u32 s4, s88, 0xfe00000
	s_addc_u32 s5, s89, 0
	s_lshl_b32 s6, s6, 5
	s_and_b32 s11, s6, 0x60
	s_mov_b64 s[6:7], 0x80
	s_add_i32 m0, s23, 0x18000
	v_lshl_add_u64 v[6:7], v[6:7], 0, s[6:7]
	s_ashr_i32 s66, s28, 31
	s_lshl_b32 s10, s3, 13
	s_lshl_b32 s16, s11, 7
	s_waitcnt vmcnt(4)
	s_barrier
	global_load_lds_dwordx4 v[6:7], off
	v_lshl_add_u64 v[4:5], v[4:5], 0, s[6:7]
	s_add_i32 m0, s23, 0x1a000
	s_add_i32 s67, s23, 0x8000
	s_add_i32 s68, s23, 0xa000
	global_load_lds_dwordx4 v[4:5], off
	v_lshl_add_u64 v[2:3], v[2:3], 0, s[6:7]
	s_mov_b32 m0, s67
	s_add_u32 s8, s42, 0x80080
	global_load_lds_dwordx4 v[2:3], off
	v_lshl_add_u64 v[0:1], v[0:1], 0, s[6:7]
	s_mov_b32 m0, s68
	s_addc_u32 s9, s43, 0
	global_load_lds_dwordx4 v[0:1], off
	s_add_i32 m0, s23, 0x1c000
	s_nop 0
	global_load_lds_dwordx4 v130, s[8:9]
	s_add_i32 m0, s23, 0x1e000
	s_sext_i32_i16 s33, s2
	global_load_lds_dwordx4 v134, s[8:9]
	v_and_b32_e32 v0, 15, v241
	v_lshlrev_b32_e32 v1, 1, v11
	v_lshlrev_b32_e32 v2, 6, v241
	s_movk_i32 s2, 0x3c0
	v_lshlrev_b32_e32 v3, 2, v241
	v_and_or_b32 v2, v2, s2, v1
	v_and_b32_e32 v3, 32, v3
	v_lshl_or_b32 v148, s3, 6, v0
	v_lshl_or_b32 v0, v0, 6, v1
	v_lshlrev_b32_e32 v1, 9, v241
	v_bitop3_b32 v149, s16, v2, v3 bitop3:0xf6
	v_and_b32_e32 v1, 0x70000, v1
	v_lshlrev_b32_e32 v2, 12, v10
	v_or3_b32 v1, v8, v1, v2
	v_add_u32_e32 v136, v1, v9
	v_lshlrev_b32_e32 v1, 5, v12
	s_waitcnt vmcnt(6)
	v_and_b32_e32 v1, 0xf0000, v1
	v_bitop3_b32 v0, v0, s10, v3 bitop3:0xde
	v_or3_b32 v1, v8, v1, v2
	s_add_i32 s70, 0, 0x10000
	s_add_i32 s71, 0, 0x14000
	s_mov_b32 s69, s28
	v_or_b32_e32 v150, s11, v11
	v_mov_b32_e32 v137, v131
	v_add_u32_e32 v138, v1, v9
	v_mov_b32_e32 v139, v131
	v_mov_b64_e32 v[140:141], 0x1760
	v_mov_b64_e32 v[142:143], 0x175f
	v_add_u32_e32 v151, s70, v149
	v_add_u32_e32 v152, 0, v0
	v_add_u32_e32 v153, s71, v149
	s_movk_i32 s72, 0x2c00
	s_barrier

; #define PG8_STAGE(bufoff, gbase, voff) do { _Pragma("unroll") for (int _i = 0; _i < 2; ++_i) \
;         __builtin_amdgcn_global_load_lds((const unsigned*)((const char*)(gbase) + (voff)[_i]), (LAS unsigned*)(lds + (bufoff) + ldsw + _i * 8192), 16, 0, 0); } while (0)
; #define PG8_LDA(dst, b, h) do { _Pragma("unroll") for (int m = 0; m < 4; ++m) _Pragma("unroll") for (int k = 0; k < 2; ++k) dst[m][k] = *(const LAS bf16x8*)(lds + PG8_SA(b, h) + aoff + m * 2048 + k * 1024); } while (0)
; #define PG8_LDB(dst, b, h) do { _Pragma("unroll") for (int n = 0; n < 2; ++n) _Pragma("unroll") for (int k = 0; k < 2; ++k) dst[n][k] = *(const LAS bf16x8*)(lds + PG8_SB(b, h) + boff + n * 2048 + k * 1024); } while (0)
; #define PG8_MMA(ai, bj, At, Bt) do { __builtin_amdgcn_s_setprio(1); _Pragma("unroll") for (int m = 0; m < 4; ++m) _Pragma("unroll") for (int n = 0; n < 2; ++n) _Pragma("unroll") for (int k = 0; k < 2; ++k) \
;         acc[ai][bj][m][n] = __builtin_amdgcn_mfma_f32_16x16x32_bf16(Bt[n][k], At[m][k], acc[ai][bj][m][n], 0, 0, 0); __builtin_amdgcn_s_setprio(0); } while (0)
; #define PG8_WAIT_L(n) asm volatile("s_waitcnt lgkmcnt(" #n ")" ::: "memory")
; #define PG8_BAR __builtin_amdgcn_s_barrier()
; #define PG8_SCHED __builtin_amdgcn_sched_barrier(0)
; template <class Epi, class Order>
; __device__ __forceinline__ void gemm_phase(LAS unsigned char* lds, const Gemm g, const Order& S, const Epi& E) {
;     ...
;             PG8_LDB(B0, 0, 0); PG8_SCHED; PG8_LDA(At, 0, 0); PG8_STAGE(PG8_SA(1, 1), a1 + hstep, voffA);
;             PG8_WAIT_L(8); PG8_BAR; PG8_WAIT_L(0); PG8_MMA(0, 0, At, B0); PG8_BAR; PG8_SCHED;
;             PG8_LDB(B1, 0, 1); PG8_STAGE(PG8_SB(0, 0), b2, voffB);
;             PG8_BAR; PG8_WAIT_L(0); PG8_MMA(0, 1, At, B1); PG8_BAR;
;             PG8_LDA(At, 0, 1); PG8_STAGE(PG8_SA(0, 0), a2, voffA);
;             PG8_BAR; PG8_WAIT_L(0); PG8_MMA(1, 0, At, B0); PG8_BAR; PG8_SCHED;
.LBB0_222:
	ds_read_b128 v[144:147], v151
	ds_read_b128 v[154:157], v151 offset:1024
	ds_read_b128 v[158:161], v151 offset:2048
	ds_read_b128 v[162:165], v151 offset:3072
	s_add_u32 s24, s38, 0xfff80080
	s_addc_u32 s25, s39, -1
	s_cmp_eq_u32 s95, 28
	s_cselect_b32 s45, s11, s25
	s_cselect_b32 s44, s73, s24
	s_cselect_b32 s43, s9, s94
	s_cselect_b32 s42, s84, s85
	v_lshl_add_u64 v[198:199], s[38:39], 0, v[136:137]
	s_add_i32 m0, s23, 0xc000
	ds_read_b128 v[166:169], v152
	ds_read_b128 v[170:173], v152 offset:1024
	ds_read_b128 v[174:177], v152 offset:2048
	ds_read_b128 v[178:181], v152 offset:3072
	ds_read_b128 v[182:185], v152 offset:4096
	ds_read_b128 v[186:189], v152 offset:5120
	ds_read_b128 v[190:193], v152 offset:6144
	ds_read_b128 v[194:197], v152 offset:7168
	global_load_lds_dwordx4 v[198:199], off
	v_lshl_add_u64 v[198:199], s[38:39], 0, v[138:139]
	s_add_i32 m0, s23, 0xe000
	s_nop 0
	global_load_lds_dwordx4 v[198:199], off
	s_waitcnt lgkmcnt(8)
	s_barrier
	s_waitcnt lgkmcnt(0)
	s_setprio 1
	s_waitcnt lgkmcnt(0)
	v_mfma_f32_16x16x32_bf16 v[124:127], v[144:147], v[166:169], v[124:127]
	v_mfma_f32_16x16x32_bf16 v[116:119], v[158:161], v[166:169], v[116:119]
	v_mfma_f32_16x16x32_bf16 v[108:111], v[144:147], v[174:177], v[108:111]
	v_mfma_f32_16x16x32_bf16 v[100:103], v[158:161], v[174:177], v[100:103]
	v_mfma_f32_16x16x32_bf16 v[92:95], v[144:147], v[182:185], v[92:95]
	v_mfma_f32_16x16x32_bf16 v[84:87], v[158:161], v[182:185], v[84:87]
	v_mfma_f32_16x16x32_bf16 v[76:79], v[144:147], v[190:193], v[76:79]
	v_mfma_f32_16x16x32_bf16 v[68:71], v[158:161], v[190:193], v[68:71]
	v_mfma_f32_16x16x32_bf16 v[124:127], v[154:157], v[170:173], v[124:127]
	v_mfma_f32_16x16x32_bf16 v[116:119], v[162:165], v[170:173], v[116:119]
	v_mfma_f32_16x16x32_bf16 v[108:111], v[154:157], v[178:181], v[108:111]
	v_mfma_f32_16x16x32_bf16 v[100:103], v[162:165], v[178:181], v[100:103]
	v_mfma_f32_16x16x32_bf16 v[92:95], v[154:157], v[186:189], v[92:95]
	v_mfma_f32_16x16x32_bf16 v[84:87], v[162:165], v[186:189], v[84:87]
	v_mfma_f32_16x16x32_bf16 v[76:79], v[154:157], v[194:197], v[76:79]
	v_mfma_f32_16x16x32_bf16 v[68:71], v[162:165], v[194:197], v[68:71]
	s_setprio 0
	s_barrier
	s_add_i32 s24, s70, s47
	v_lshl_add_u64 v[214:215], s[42:43], 0, v[130:131]
	s_mov_b32 m0, s24
	ds_read_b128 v[198:201], v153
	ds_read_b128 v[202:205], v153 offset:1024
	ds_read_b128 v[206:209], v153 offset:2048
	ds_read_b128 v[210:213], v153 offset:3072
	global_load_lds_dwordx4 v[214:215], off
	v_lshl_add_u64 v[216:217], s[42:43], 0, v[134:135]
	s_add_i32 m0, s24, 0x2000
	s_nop 0
	global_load_lds_dwordx4 v[216:217], off
	s_barrier
	s_waitcnt lgkmcnt(0)
	s_setprio 1
	s_waitcnt lgkmcnt(0)
	v_mfma_f32_16x16x32_bf16 v[120:123], v[198:201], v[166:169], v[120:123]
	v_mfma_f32_16x16x32_bf16 v[112:115], v[206:209], v[166:169], v[112:115]
	v_mfma_f32_16x16x32_bf16 v[104:107], v[198:201], v[174:177], v[104:107]
	v_mfma_f32_16x16x32_bf16 v[96:99], v[206:209], v[174:177], v[96:99]
	v_mfma_f32_16x16x32_bf16 v[88:91], v[198:201], v[182:185], v[88:91]
	v_mfma_f32_16x16x32_bf16 v[80:83], v[206:209], v[182:185], v[80:83]
	v_mfma_f32_16x16x32_bf16 v[72:75], v[198:201], v[190:193], v[72:75]
	v_mfma_f32_16x16x32_bf16 v[64:67], v[206:209], v[190:193], v[64:67]
	v_mfma_f32_16x16x32_bf16 v[120:123], v[202:205], v[170:173], v[120:123]
	v_mfma_f32_16x16x32_bf16 v[112:115], v[210:213], v[170:173], v[112:115]
	v_mfma_f32_16x16x32_bf16 v[104:107], v[202:205], v[178:181], v[104:107]
	v_mfma_f32_16x16x32_bf16 v[96:99], v[210:213], v[178:181], v[96:99]
	v_mfma_f32_16x16x32_bf16 v[88:91], v[202:205], v[186:189], v[88:91]
	v_mfma_f32_16x16x32_bf16 v[80:83], v[210:213], v[186:189], v[80:83]
	v_mfma_f32_16x16x32_bf16 v[72:75], v[202:205], v[194:197], v[72:75]
	v_mfma_f32_16x16x32_bf16 v[64:67], v[210:213], v[194:197], v[64:67]
	s_setprio 0
	s_mov_b32 m0, s23
	v_lshl_add_u64 v[218:219], s[44:45], 0, v[128:129]
	s_barrier
	ds_read_b128 v[166:169], v152 offset:16384
	ds_read_b128 v[170:173], v152 offset:17408
	ds_read_b128 v[174:177], v152 offset:18432
	ds_read_b128 v[178:181], v152 offset:19456
	ds_read_b128 v[182:185], v152 offset:20480
	ds_read_b128 v[186:189], v152 offset:21504
	ds_read_b128 v[190:193], v152 offset:22528
	ds_read_b128 v[194:197], v152 offset:23552
	global_load_lds_dwordx4 v[218:219], off
	v_lshl_add_u64 v[220:221], s[44:45], 0, v[132:133]
	s_mov_b32 m0, s54
	s_nop 0
	global_load_lds_dwordx4 v[220:221], off
	s_barrier
	s_waitcnt lgkmcnt(0)
	s_setprio 1
	s_waitcnt lgkmcnt(0)
	v_mfma_f32_16x16x32_bf16 v[60:63], v[144:147], v[166:169], v[60:63]
	v_mfma_f32_16x16x32_bf16 v[52:55], v[158:161], v[166:169], v[52:55]
	v_mfma_f32_16x16x32_bf16 v[44:47], v[144:147], v[174:177], v[44:47]
	v_mfma_f32_16x16x32_bf16 v[36:39], v[158:161], v[174:177], v[36:39]
	v_mfma_f32_16x16x32_bf16 v[28:31], v[144:147], v[182:185], v[28:31]
	v_mfma_f32_16x16x32_bf16 v[20:23], v[158:161], v[182:185], v[20:23]
	v_mfma_f32_16x16x32_bf16 v[12:15], v[144:147], v[190:193], v[12:15]
	v_mfma_f32_16x16x32_bf16 v[4:7], v[158:161], v[190:193], v[4:7]
	v_mfma_f32_16x16x32_bf16 v[60:63], v[154:157], v[170:173], v[60:63]
	v_mfma_f32_16x16x32_bf16 v[52:55], v[162:165], v[170:173], v[52:55]
	v_mfma_f32_16x16x32_bf16 v[44:47], v[154:157], v[178:181], v[44:47]
	v_mfma_f32_16x16x32_bf16 v[36:39], v[162:165], v[178:181], v[36:39]
	v_mfma_f32_16x16x32_bf16 v[28:31], v[154:157], v[186:189], v[28:31]
	v_mfma_f32_16x16x32_bf16 v[20:23], v[162:165], v[186:189], v[20:23]
	v_mfma_f32_16x16x32_bf16 v[12:15], v[154:157], v[194:197], v[12:15]
	v_mfma_f32_16x16x32_bf16 v[4:7], v[162:165], v[194:197], v[4:7]
	s_setprio 0
	s_barrier
; #define PG8_STAGE(bufoff, gbase, voff) do { _Pragma("unroll") for (int _i = 0; _i < 2; ++_i) \
;         __builtin_amdgcn_global_load_lds((const unsigned*)((const char*)(gbase) + (voff)[_i]), (LAS unsigned*)(lds + (bufoff) + ldsw + _i * 8192), 16, 0, 0); } while (0)
; #define PG8_LDA(dst, b, h) do { _Pragma("unroll") for (int m = 0; m < 4; ++m) _Pragma("unroll") for (int k = 0; k < 2; ++k) dst[m][k] = *(const LAS bf16x8*)(lds + PG8_SA(b, h) + aoff + m * 2048 + k * 1024); } while (0)
; #define PG8_LDB(dst, b, h) do { _Pragma("unroll") for (int n = 0; n < 2; ++n) _Pragma("unroll") for (int k = 0; k < 2; ++k) dst[n][k] = *(const LAS bf16x8*)(lds + PG8_SB(b, h) + boff + n * 2048 + k * 1024); } while (0)
; #define PG8_MMA(ai, bj, At, Bt) do { __builtin_amdgcn_s_setprio(1); _Pragma("unroll") for (int m = 0; m < 4; ++m) _Pragma("unroll") for (int n = 0; n < 2; ++n) _Pragma("unroll") for (int k = 0; k < 2; ++k) \
;         acc[ai][bj][m][n] = __builtin_amdgcn_mfma_f32_16x16x32_bf16(Bt[n][k], At[m][k], acc[ai][bj][m][n], 0, 0, 0); __builtin_amdgcn_s_setprio(0); } while (0)
; #define PG8_WAIT_V(n) asm volatile("s_waitcnt vmcnt(" #n ")" ::: "memory")
; #define PG8_WAIT_L(n) asm volatile("s_waitcnt lgkmcnt(" #n ")" ::: "memory")
; #define PG8_BAR __builtin_amdgcn_s_barrier()
; #define PG8_SCHED __builtin_amdgcn_sched_barrier(0)
; template <class Epi, class Order>
; __device__ __forceinline__ void gemm_phase(LAS unsigned char* lds, const Gemm g, const Order& S, const Epi& E) {
;     ...
;             PG8_STAGE(PG8_SB(0, 1), b2 + hstep, voffB);
;             PG8_WAIT_V(6); PG8_BAR; PG8_MMA(1, 1, At, B1); PG8_BAR;
;             PG8_LDB(B0, 1, 0); PG8_SCHED; PG8_LDA(At, 1, 0); PG8_STAGE(PG8_SA(0, 1), a2 + hstep, voffA);
;             PG8_WAIT_L(8); PG8_BAR; PG8_WAIT_L(0); PG8_MMA(0, 0, At, B0); PG8_BAR; PG8_SCHED;
;             PG8_LDB(B1, 1, 1); PG8_STAGE(PG8_SB(1, 0), b3, voffB);
;             PG8_BAR; PG8_WAIT_L(0); PG8_MMA(0, 1, At, B1); PG8_BAR;
;             PG8_LDA(At, 1, 1); PG8_STAGE(PG8_SA(1, 0), a3, voffA);
	s_add_u32 s24, s42, 0x80000
	s_addc_u32 s25, s43, 0
	s_add_i32 s27, s71, s47
	s_mov_b32 m0, s27
	s_nop 0
	global_load_lds_dwordx4 v130, s[24:25]
	s_add_i32 m0, s27, 0x2000
	s_nop 0
	global_load_lds_dwordx4 v134, s[24:25]
	s_waitcnt vmcnt(6)
	s_barrier
	s_setprio 1
	v_mfma_f32_16x16x32_bf16 v[56:59], v[198:201], v[166:169], v[56:59]
	v_mfma_f32_16x16x32_bf16 v[48:51], v[206:209], v[166:169], v[48:51]
	v_mfma_f32_16x16x32_bf16 v[40:43], v[198:201], v[174:177], v[40:43]
	v_mfma_f32_16x16x32_bf16 v[32:35], v[206:209], v[174:177], v[32:35]
	v_mfma_f32_16x16x32_bf16 v[24:27], v[198:201], v[182:185], v[24:27]
	v_mfma_f32_16x16x32_bf16 v[16:19], v[206:209], v[182:185], v[16:19]
	v_mfma_f32_16x16x32_bf16 v[8:11], v[198:201], v[190:193], v[8:11]
	v_mfma_f32_16x16x32_bf16 v[0:3], v[206:209], v[190:193], v[0:3]
	v_mfma_f32_16x16x32_bf16 v[56:59], v[202:205], v[170:173], v[56:59]
	v_mfma_f32_16x16x32_bf16 v[48:51], v[210:213], v[170:173], v[48:51]
	v_mfma_f32_16x16x32_bf16 v[40:43], v[202:205], v[178:181], v[40:43]
	v_mfma_f32_16x16x32_bf16 v[32:35], v[210:213], v[178:181], v[32:35]
	v_mfma_f32_16x16x32_bf16 v[24:27], v[202:205], v[186:189], v[24:27]
	v_mfma_f32_16x16x32_bf16 v[16:19], v[210:213], v[186:189], v[16:19]
	v_mfma_f32_16x16x32_bf16 v[8:11], v[202:205], v[194:197], v[8:11]
	v_mfma_f32_16x16x32_bf16 v[0:3], v[210:213], v[194:197], v[0:3]
	s_setprio 0
	s_add_i32 s27, 0, 0x18000
	v_add_u32_e32 v162, s27, v149
	s_barrier
	ds_read_b128 v[144:147], v162
	ds_read_b128 v[154:157], v162 offset:1024
	ds_read_b128 v[158:161], v162 offset:2048
	ds_read_b128 v[162:165], v162 offset:3072
	s_add_u32 s24, s44, 0x80000
	s_addc_u32 s25, s45, 0
	s_mov_b32 m0, s55
	ds_read_b128 v[166:169], v152 offset:32768
	ds_read_b128 v[170:173], v152 offset:33792
	ds_read_b128 v[174:177], v152 offset:34816
	ds_read_b128 v[178:181], v152 offset:35840
	ds_read_b128 v[182:185], v152 offset:36864
	ds_read_b128 v[186:189], v152 offset:37888
	ds_read_b128 v[190:193], v152 offset:38912
	ds_read_b128 v[194:197], v152 offset:39936
	global_load_lds_dwordx4 v128, s[24:25]
	s_mov_b32 m0, s60
	s_nop 0
	global_load_lds_dwordx4 v132, s[24:25]
	s_waitcnt lgkmcnt(8)
	s_barrier
	s_waitcnt lgkmcnt(0)
	s_setprio 1
	s_waitcnt lgkmcnt(0)
	v_mfma_f32_16x16x32_bf16 v[124:127], v[144:147], v[166:169], v[124:127]
	v_mfma_f32_16x16x32_bf16 v[116:119], v[158:161], v[166:169], v[116:119]
	v_mfma_f32_16x16x32_bf16 v[108:111], v[144:147], v[174:177], v[108:111]
	v_mfma_f32_16x16x32_bf16 v[100:103], v[158:161], v[174:177], v[100:103]
	v_mfma_f32_16x16x32_bf16 v[92:95], v[144:147], v[182:185], v[92:95]
	v_mfma_f32_16x16x32_bf16 v[84:87], v[158:161], v[182:185], v[84:87]
	v_mfma_f32_16x16x32_bf16 v[76:79], v[144:147], v[190:193], v[76:79]
	v_mfma_f32_16x16x32_bf16 v[68:71], v[158:161], v[190:193], v[68:71]
	v_mfma_f32_16x16x32_bf16 v[124:127], v[154:157], v[170:173], v[124:127]
	v_mfma_f32_16x16x32_bf16 v[116:119], v[162:165], v[170:173], v[116:119]
	v_mfma_f32_16x16x32_bf16 v[108:111], v[154:157], v[178:181], v[108:111]
	v_mfma_f32_16x16x32_bf16 v[100:103], v[162:165], v[178:181], v[100:103]
	v_mfma_f32_16x16x32_bf16 v[92:95], v[154:157], v[186:189], v[92:95]
	v_mfma_f32_16x16x32_bf16 v[84:87], v[162:165], v[186:189], v[84:87]
	v_mfma_f32_16x16x32_bf16 v[76:79], v[154:157], v[194:197], v[76:79]
	v_mfma_f32_16x16x32_bf16 v[68:71], v[162:165], v[194:197], v[68:71]
	s_setprio 0
	s_barrier
	s_add_i32 s44, 0, 0x1c000
	s_add_i32 s24, s27, s47
	v_add_u32_e32 v210, s44, v149
	v_lshl_add_u64 v[214:215], v[214:215], 0, s[6:7]
	s_mov_b32 m0, s24
	ds_read_b128 v[198:201], v210
	ds_read_b128 v[202:205], v210 offset:1024
	ds_read_b128 v[206:209], v210 offset:2048
	ds_read_b128 v[210:213], v210 offset:3072
	global_load_lds_dwordx4 v[214:215], off
	v_lshl_add_u64 v[214:215], v[216:217], 0, s[6:7]
	s_add_i32 m0, s24, 0x2000
	s_nop 0
	global_load_lds_dwordx4 v[214:215], off
	s_barrier
	s_waitcnt lgkmcnt(0)
	s_setprio 1
	s_waitcnt lgkmcnt(0)
	v_mfma_f32_16x16x32_bf16 v[120:123], v[198:201], v[166:169], v[120:123]
	v_mfma_f32_16x16x32_bf16 v[112:115], v[206:209], v[166:169], v[112:115]
	v_mfma_f32_16x16x32_bf16 v[104:107], v[198:201], v[174:177], v[104:107]
	v_mfma_f32_16x16x32_bf16 v[96:99], v[206:209], v[174:177], v[96:99]
	v_mfma_f32_16x16x32_bf16 v[88:91], v[198:201], v[182:185], v[88:91]
	v_mfma_f32_16x16x32_bf16 v[80:83], v[206:209], v[182:185], v[80:83]
	v_mfma_f32_16x16x32_bf16 v[72:75], v[198:201], v[190:193], v[72:75]
	v_mfma_f32_16x16x32_bf16 v[64:67], v[206:209], v[190:193], v[64:67]
	v_mfma_f32_16x16x32_bf16 v[120:123], v[202:205], v[170:173], v[120:123]
	v_mfma_f32_16x16x32_bf16 v[112:115], v[210:213], v[170:173], v[112:115]
	v_mfma_f32_16x16x32_bf16 v[104:107], v[202:205], v[178:181], v[104:107]
	v_mfma_f32_16x16x32_bf16 v[96:99], v[210:213], v[178:181], v[96:99]
	v_mfma_f32_16x16x32_bf16 v[88:91], v[202:205], v[186:189], v[88:91]
	v_mfma_f32_16x16x32_bf16 v[80:83], v[210:213], v[186:189], v[80:83]
	v_mfma_f32_16x16x32_bf16 v[72:75], v[202:205], v[194:197], v[72:75]
	v_mfma_f32_16x16x32_bf16 v[64:67], v[210:213], v[194:197], v[64:67]
	s_setprio 0
	s_mov_b32 m0, s67
	v_lshl_add_u64 v[214:215], v[218:219], 0, s[6:7]
	s_barrier
	ds_read_b128 v[166:169], v152 offset:49152
	ds_read_b128 v[170:173], v152 offset:50176
	ds_read_b128 v[174:177], v152 offset:51200
	ds_read_b128 v[178:181], v152 offset:52224
	ds_read_b128 v[182:185], v152 offset:53248
	ds_read_b128 v[186:189], v152 offset:54272
	ds_read_b128 v[190:193], v152 offset:55296
	ds_read_b128 v[194:197], v152 offset:56320
	global_load_lds_dwordx4 v[214:215], off
	v_lshl_add_u64 v[214:215], v[220:221], 0, s[6:7]
	s_mov_b32 m0, s68
	s_nop 0
	global_load_lds_dwordx4 v[214:215], off
	s_barrier
; __device__ __forceinline__ unsigned cvt_pk_bf16(float lo, float hi) { const f32x2 v = (f32x2){lo, hi}; const bf16v2 b = __builtin_convertvector(v, bf16v2); return __builtin_bit_cast(unsigned, b); }
; __device__ __forceinline__ float siluf(float x) { return x * sigm(x); }
; #define PG8_STAGE(bufoff, gbase, voff) do { _Pragma("unroll") for (int _i = 0; _i < 2; ++_i) \
;         __builtin_amdgcn_global_load_lds((const unsigned*)((const char*)(gbase) + (voff)[_i]), (LAS unsigned*)(lds + (bufoff) + ldsw + _i * 8192), 16, 0, 0); } while (0)
; #define PG8_MMA(ai, bj, At, Bt) do { __builtin_amdgcn_s_setprio(1); _Pragma("unroll") for (int m = 0; m < 4; ++m) _Pragma("unroll") for (int n = 0; n < 2; ++n) _Pragma("unroll") for (int k = 0; k < 2; ++k) \
;         acc[ai][bj][m][n] = __builtin_amdgcn_mfma_f32_16x16x32_bf16(Bt[n][k], At[m][k], acc[ai][bj][m][n], 0, 0, 0); __builtin_amdgcn_s_setprio(0); } while (0)
; #define PG8_WAIT_V(n) asm volatile("s_waitcnt vmcnt(" #n ")" ::: "memory")
; #define PG8_WAIT_L(n) asm volatile("s_waitcnt lgkmcnt(" #n ")" ::: "memory")
; #define PG8_BAR __builtin_amdgcn_s_barrier()
; #define PG8_SCHED __builtin_amdgcn_sched_barrier(0)
; template <class Epi, class Order>
; __device__ __forceinline__ void gemm_phase(LAS unsigned char* lds, const Gemm g, const Order& S, const Epi& E) {
;     ...
;             PG8_BAR; PG8_WAIT_L(0); PG8_MMA(1, 0, At, B0); PG8_BAR; PG8_SCHED;
;             PG8_STAGE(PG8_SB(1, 1), b3 + hstep, voffB);
;             PG8_WAIT_V(6); PG8_BAR; PG8_MMA(1, 1, At, B1); PG8_BAR;
;     __device__ __forceinline__ void operator()(const f32x4 (&acc)[2][2][4][2], const pg8::Unit& u, int wr, int wc, int fr, int fq) const {
;     ...
;                 bf16_t* rowp = O + (size_t)(row0 + ai * 128 + m * 16) * DFF + col0;
;                 const f32x4 g0 = acc[ai][0][m][0], g1 = acc[ai][0][m][1], u0 = acc[ai][1][m][0], u1 = acc[ai][1][m][1];
;                 u32x4 w;
;                 w.x = cvt_pk_bf16(siluf(g0[0]) * u0[0], siluf(g0[1]) * u0[1]); w.y = cvt_pk_bf16(siluf(g0[2]) * u0[2], siluf(g0[3]) * u0[3]);
;                 w.z = cvt_pk_bf16(siluf(g1[0]) * u1[0], siluf(g1[1]) * u1[1]); w.w = cvt_pk_bf16(siluf(g1[2]) * u1[2], siluf(g1[3]) * u1[3]);
;                 *(u32x4*)rowp = w;
	s_waitcnt lgkmcnt(0)
	s_setprio 1
	s_waitcnt lgkmcnt(0)
	v_mfma_f32_16x16x32_bf16 v[60:63], v[144:147], v[166:169], v[60:63]
	v_mfma_f32_16x16x32_bf16 v[52:55], v[158:161], v[166:169], v[52:55]
	v_mfma_f32_16x16x32_bf16 v[44:47], v[144:147], v[174:177], v[44:47]
	v_mfma_f32_16x16x32_bf16 v[36:39], v[158:161], v[174:177], v[36:39]
	v_mfma_f32_16x16x32_bf16 v[28:31], v[144:147], v[182:185], v[28:31]
	v_mfma_f32_16x16x32_bf16 v[20:23], v[158:161], v[182:185], v[20:23]
	v_mfma_f32_16x16x32_bf16 v[12:15], v[144:147], v[190:193], v[12:15]
	v_mfma_f32_16x16x32_bf16 v[4:7], v[158:161], v[190:193], v[4:7]
	v_mfma_f32_16x16x32_bf16 v[60:63], v[154:157], v[170:173], v[60:63]
	v_mfma_f32_16x16x32_bf16 v[52:55], v[162:165], v[170:173], v[52:55]
	v_mfma_f32_16x16x32_bf16 v[44:47], v[154:157], v[178:181], v[44:47]
	v_mfma_f32_16x16x32_bf16 v[36:39], v[162:165], v[178:181], v[36:39]
	v_mfma_f32_16x16x32_bf16 v[28:31], v[154:157], v[186:189], v[28:31]
	v_mfma_f32_16x16x32_bf16 v[20:23], v[162:165], v[186:189], v[20:23]
	v_mfma_f32_16x16x32_bf16 v[12:15], v[154:157], v[194:197], v[12:15]
	v_mfma_f32_16x16x32_bf16 v[4:7], v[162:165], v[194:197], v[4:7]
	s_setprio 0
	s_barrier
	s_add_u32 s24, s42, 0x80080
	s_addc_u32 s25, s43, 0
	s_add_i32 s27, s44, s47
	s_mov_b32 m0, s27
	s_nop 0
	global_load_lds_dwordx4 v130, s[24:25]
	v_lshl_add_u64 v[144:145], s[24:25], 0, v[134:135]
	s_add_i32 m0, s27, 0x2000
	s_nop 0
	global_load_lds_dwordx4 v[144:145], off
	s_waitcnt vmcnt(6)
	s_barrier
	s_setprio 1
	v_mfma_f32_16x16x32_bf16 v[56:59], v[198:201], v[166:169], v[56:59]
	v_mfma_f32_16x16x32_bf16 v[48:51], v[206:209], v[166:169], v[48:51]
	v_mfma_f32_16x16x32_bf16 v[40:43], v[198:201], v[174:177], v[40:43]
	v_mfma_f32_16x16x32_bf16 v[32:35], v[206:209], v[174:177], v[32:35]
	v_mfma_f32_16x16x32_bf16 v[24:27], v[198:201], v[182:185], v[24:27]
	v_mfma_f32_16x16x32_bf16 v[16:19], v[206:209], v[182:185], v[16:19]
	v_mfma_f32_16x16x32_bf16 v[8:11], v[198:201], v[190:193], v[8:11]
	v_mfma_f32_16x16x32_bf16 v[0:3], v[206:209], v[190:193], v[0:3]
	v_mfma_f32_16x16x32_bf16 v[56:59], v[202:205], v[170:173], v[56:59]
	v_mfma_f32_16x16x32_bf16 v[48:51], v[210:213], v[170:173], v[48:51]
	v_mfma_f32_16x16x32_bf16 v[40:43], v[202:205], v[178:181], v[40:43]
	v_mfma_f32_16x16x32_bf16 v[32:35], v[210:213], v[178:181], v[32:35]
	v_mfma_f32_16x16x32_bf16 v[24:27], v[202:205], v[186:189], v[24:27]
	v_mfma_f32_16x16x32_bf16 v[16:19], v[210:213], v[186:189], v[16:19]
	v_mfma_f32_16x16x32_bf16 v[8:11], v[202:205], v[194:197], v[8:11]
	v_mfma_f32_16x16x32_bf16 v[0:3], v[210:213], v[194:197], v[0:3]
	s_setprio 0
	s_add_i32 s95, s95, 2
	s_add_u32 s38, s38, 0x100
	s_addc_u32 s39, s39, 0
	s_add_u32 s85, s85, 0x100
	s_addc_u32 s94, s94, 0
	s_cmp_gt_u32 s95, 29
	s_barrier
	s_cbranch_scc0 .LBB0_222
	v_mul_f32_e32 v155, 0xbfb8aa3b, v124
	v_exp_f32_e32 v155, v155
	v_mul_f32_e32 v158, 0xbfb8aa3b, v125
	v_exp_f32_e32 v159, v158
	v_lshl_add_u32 v154, s22, 8, v148
	v_add_f32_e32 v155, 1.0, v155
	v_rcp_f32_e32 v158, v155
	v_add_f32_e32 v155, 1.0, v159
	v_mul_f32_e32 v159, 0xbfb8aa3b, v126
	v_exp_f32_e32 v160, v159
	v_mul_f32_e32 v159, 0xbfb8aa3b, v127
	v_exp_f32_e32 v161, v159
	v_rcp_f32_e32 v159, v155
	v_add_f32_e32 v155, 1.0, v160
	v_rcp_f32_e32 v160, v155
	v_add_f32_e32 v155, 1.0, v161
	v_rcp_f32_e32 v161, v155
	v_pk_mul_f32 v[124:125], v[124:125], v[158:159]
	v_lshl_or_b32 v144, s33, 7, v150
	v_pk_mul_f32 v[120:121], v[124:125], v[120:121]
	v_pk_mul_f32 v[124:125], v[126:127], v[160:161]
	v_cvt_pk_bf16_f32 v120, v120, v121
	v_mul_f32_e32 v121, 0xbfb8aa3b, v116
	v_pk_mul_f32 v[122:123], v[124:125], v[122:123]
	v_exp_f32_e32 v124, v121
	v_mul_f32_e32 v121, 0xbfb8aa3b, v117
	v_exp_f32_e32 v125, v121
	v_cvt_pk_bf16_f32 v121, v122, v123
	v_add_f32_e32 v122, 1.0, v124
	v_mul_f32_e32 v124, 0xbfb8aa3b, v118
	v_add_f32_e32 v123, 1.0, v125
	v_mul_f32_e32 v125, 0xbfb8aa3b, v119
	v_exp_f32_e32 v124, v124
	v_exp_f32_e32 v125, v125
	v_rcp_f32_e32 v122, v122
	v_rcp_f32_e32 v123, v123
	v_add_f32_e32 v124, 1.0, v124
	v_add_f32_e32 v125, 1.0, v125
	v_rcp_f32_e32 v124, v124
	v_rcp_f32_e32 v125, v125
	v_pk_mul_f32 v[116:117], v[116:117], v[122:123]
	v_ashrrev_i32_e32 v145, 31, v144
	v_pk_mul_f32 v[112:113], v[116:117], v[112:113]
	v_mul_f32_e32 v116, 0xbfb8aa3b, v110
	v_cvt_pk_bf16_f32 v122, v112, v113
	v_pk_mul_f32 v[112:113], v[118:119], v[124:125]
	v_mul_f32_e32 v117, 0xbfb8aa3b, v111
	v_pk_mul_f32 v[112:113], v[112:113], v[114:115]
	v_mul_f32_e32 v114, 0xbfb8aa3b, v108
	v_mul_f32_e32 v115, 0xbfb8aa3b, v109
	v_exp_f32_e32 v114, v114
	v_exp_f32_e32 v115, v115
	v_exp_f32_e32 v116, v116
	v_exp_f32_e32 v117, v117
	v_add_f32_e32 v114, 1.0, v114
	v_add_f32_e32 v115, 1.0, v115
	v_rcp_f32_e32 v114, v114
	v_rcp_f32_e32 v115, v115
	v_add_f32_e32 v116, 1.0, v116
	v_add_f32_e32 v117, 1.0, v117
	v_rcp_f32_e32 v116, v116
	v_rcp_f32_e32 v117, v117
	v_pk_mul_f32 v[108:109], v[108:109], v[114:115]
	v_mov_b64_e32 v[146:147], s[4:5]
	v_pk_mul_f32 v[104:105], v[108:109], v[104:105]
	v_pk_mul_f32 v[108:109], v[110:111], v[116:117]
	v_cvt_pk_bf16_f32 v104, v104, v105
	v_mul_f32_e32 v105, 0xbfb8aa3b, v100
	v_pk_mul_f32 v[106:107], v[108:109], v[106:107]
	v_exp_f32_e32 v108, v105
	v_mul_f32_e32 v105, 0xbfb8aa3b, v101
	v_exp_f32_e32 v109, v105
	v_cvt_pk_bf16_f32 v105, v106, v107
	v_add_f32_e32 v106, 1.0, v108
	v_mul_f32_e32 v108, 0xbfb8aa3b, v102
	v_add_f32_e32 v107, 1.0, v109
	v_mul_f32_e32 v109, 0xbfb8aa3b, v103
	v_exp_f32_e32 v108, v108
	v_exp_f32_e32 v109, v109
	v_rcp_f32_e32 v106, v106
	v_rcp_f32_e32 v107, v107
	v_add_f32_e32 v108, 1.0, v108
	v_add_f32_e32 v109, 1.0, v109
	v_rcp_f32_e32 v108, v108
	v_rcp_f32_e32 v109, v109
; __device__ __forceinline__ unsigned cvt_pk_bf16(float lo, float hi) { const f32x2 v = (f32x2){lo, hi}; const bf16v2 b = __builtin_convertvector(v, bf16v2); return __builtin_bit_cast(unsigned, b); }
; __device__ __forceinline__ float siluf(float x) { return x * sigm(x); }
;     __device__ __forceinline__ void operator()(const f32x4 (&acc)[2][2][4][2], const pg8::Unit& u, int wr, int wc, int fr, int fq) const {
;     ...
;                 bf16_t* rowp = O + (size_t)(row0 + ai * 128 + m * 16) * DFF + col0;
;                 const f32x4 g0 = acc[ai][0][m][0], g1 = acc[ai][0][m][1], u0 = acc[ai][1][m][0], u1 = acc[ai][1][m][1];
;                 u32x4 w;
;                 w.x = cvt_pk_bf16(siluf(g0[0]) * u0[0], siluf(g0[1]) * u0[1]); w.y = cvt_pk_bf16(siluf(g0[2]) * u0[2], siluf(g0[3]) * u0[3]);
;                 w.z = cvt_pk_bf16(siluf(g1[0]) * u1[0], siluf(g1[1]) * u1[1]); w.w = cvt_pk_bf16(siluf(g1[2]) * u1[2], siluf(g1[3]) * u1[3]);
;                 *(u32x4*)rowp = w;
	v_pk_mul_f32 v[100:101], v[100:101], v[106:107]
	v_cvt_pk_bf16_f32 v123, v112, v113
	v_pk_mul_f32 v[96:97], v[100:101], v[96:97]
	v_mul_f32_e32 v100, 0xbfb8aa3b, v94
	v_cvt_pk_bf16_f32 v106, v96, v97
	v_pk_mul_f32 v[96:97], v[102:103], v[108:109]
	v_mul_f32_e32 v101, 0xbfb8aa3b, v95
	v_pk_mul_f32 v[96:97], v[96:97], v[98:99]
	v_mul_f32_e32 v98, 0xbfb8aa3b, v92
	v_mul_f32_e32 v99, 0xbfb8aa3b, v93
	v_exp_f32_e32 v98, v98
	v_exp_f32_e32 v99, v99
	v_exp_f32_e32 v100, v100
	v_exp_f32_e32 v101, v101
	v_add_f32_e32 v98, 1.0, v98
	v_add_f32_e32 v99, 1.0, v99
	v_rcp_f32_e32 v98, v98
	v_rcp_f32_e32 v99, v99
	v_add_f32_e32 v100, 1.0, v100
	v_add_f32_e32 v101, 1.0, v101
	v_rcp_f32_e32 v100, v100
	v_rcp_f32_e32 v101, v101
	v_pk_mul_f32 v[92:93], v[92:93], v[98:99]
	v_or_b32_e32 v112, 16, v154
	v_pk_mul_f32 v[88:89], v[92:93], v[88:89]
	v_pk_mul_f32 v[92:93], v[94:95], v[100:101]
	v_cvt_pk_bf16_f32 v88, v88, v89
	v_mul_f32_e32 v89, 0xbfb8aa3b, v84
	v_pk_mul_f32 v[90:91], v[92:93], v[90:91]
	v_exp_f32_e32 v92, v89
	v_mul_f32_e32 v89, 0xbfb8aa3b, v85
	v_exp_f32_e32 v93, v89
	v_cvt_pk_bf16_f32 v89, v90, v91
	v_add_f32_e32 v90, 1.0, v92
	v_mul_f32_e32 v92, 0xbfb8aa3b, v86
	v_add_f32_e32 v91, 1.0, v93
	v_mul_f32_e32 v93, 0xbfb8aa3b, v87
	v_exp_f32_e32 v92, v92
	v_exp_f32_e32 v93, v93
	v_rcp_f32_e32 v90, v90
	v_rcp_f32_e32 v91, v91
	v_add_f32_e32 v92, 1.0, v92
	v_add_f32_e32 v93, 1.0, v93
	v_rcp_f32_e32 v92, v92
	v_rcp_f32_e32 v93, v93
	v_pk_mul_f32 v[84:85], v[84:85], v[90:91]
	v_cvt_pk_bf16_f32 v107, v96, v97
	v_pk_mul_f32 v[80:81], v[84:85], v[80:81]
	v_mul_f32_e32 v84, 0xbfb8aa3b, v78
	v_cvt_pk_bf16_f32 v90, v80, v81
	v_pk_mul_f32 v[80:81], v[86:87], v[92:93]
	v_mul_f32_e32 v85, 0xbfb8aa3b, v79
	v_pk_mul_f32 v[80:81], v[80:81], v[82:83]
	v_mul_f32_e32 v82, 0xbfb8aa3b, v76
	v_mul_f32_e32 v83, 0xbfb8aa3b, v77
	v_exp_f32_e32 v82, v82
	v_exp_f32_e32 v83, v83
	v_exp_f32_e32 v84, v84
	v_exp_f32_e32 v85, v85
	v_add_f32_e32 v82, 1.0, v82
	v_add_f32_e32 v83, 1.0, v83
	v_rcp_f32_e32 v82, v82
	v_rcp_f32_e32 v83, v83
	v_add_f32_e32 v84, 1.0, v84
	v_add_f32_e32 v85, 1.0, v85
	v_rcp_f32_e32 v84, v84
	v_rcp_f32_e32 v85, v85
	v_pk_mul_f32 v[76:77], v[76:77], v[82:83]
	v_or_b32_e32 v96, 32, v154
	v_pk_mul_f32 v[72:73], v[76:77], v[72:73]
	v_pk_mul_f32 v[76:77], v[78:79], v[84:85]
	v_cvt_pk_bf16_f32 v72, v72, v73
	v_mul_f32_e32 v73, 0xbfb8aa3b, v68
	v_pk_mul_f32 v[74:75], v[76:77], v[74:75]
	v_exp_f32_e32 v76, v73
	v_mul_f32_e32 v73, 0xbfb8aa3b, v69
	v_exp_f32_e32 v77, v73
	v_cvt_pk_bf16_f32 v73, v74, v75
	v_add_f32_e32 v74, 1.0, v76
	v_mul_f32_e32 v76, 0xbfb8aa3b, v70
	v_add_f32_e32 v75, 1.0, v77
	v_mul_f32_e32 v77, 0xbfb8aa3b, v71
	v_exp_f32_e32 v76, v76
	v_exp_f32_e32 v77, v77
	v_rcp_f32_e32 v74, v74
	v_rcp_f32_e32 v75, v75
	v_add_f32_e32 v76, 1.0, v76
	v_add_f32_e32 v77, 1.0, v77
	v_rcp_f32_e32 v76, v76
	v_rcp_f32_e32 v77, v77
	v_pk_mul_f32 v[68:69], v[68:69], v[74:75]
	v_cvt_pk_bf16_f32 v91, v80, v81
	v_pk_mul_f32 v[64:65], v[68:69], v[64:65]
	v_mul_f32_e32 v68, 0xbfb8aa3b, v62
	v_cvt_pk_bf16_f32 v74, v64, v65
	v_pk_mul_f32 v[64:65], v[70:71], v[76:77]
	v_mul_f32_e32 v69, 0xbfb8aa3b, v63
	v_pk_mul_f32 v[64:65], v[64:65], v[66:67]
	v_mul_f32_e32 v66, 0xbfb8aa3b, v60
	v_mul_f32_e32 v67, 0xbfb8aa3b, v61
	v_exp_f32_e32 v66, v66
	v_exp_f32_e32 v67, v67
	v_exp_f32_e32 v68, v68
	v_exp_f32_e32 v69, v69
	v_add_f32_e32 v66, 1.0, v66
	v_add_f32_e32 v67, 1.0, v67
	v_rcp_f32_e32 v66, v66
	v_rcp_f32_e32 v67, v67
	v_add_f32_e32 v68, 1.0, v68
	v_add_f32_e32 v69, 1.0, v69
	v_rcp_f32_e32 v68, v68
	v_rcp_f32_e32 v69, v69
	v_pk_mul_f32 v[60:61], v[60:61], v[66:67]
	v_or_b32_e32 v80, 48, v154
	v_pk_mul_f32 v[56:57], v[60:61], v[56:57]
	v_pk_mul_f32 v[60:61], v[62:63], v[68:69]
	v_cvt_pk_bf16_f32 v56, v56, v57
	v_mul_f32_e32 v57, 0xbfb8aa3b, v52
	v_pk_mul_f32 v[58:59], v[60:61], v[58:59]
	v_exp_f32_e32 v60, v57
	v_mul_f32_e32 v57, 0xbfb8aa3b, v53
	v_exp_f32_e32 v61, v57
	v_cvt_pk_bf16_f32 v57, v58, v59
	v_add_f32_e32 v58, 1.0, v60
	v_mul_f32_e32 v60, 0xbfb8aa3b, v54
	v_add_f32_e32 v59, 1.0, v61
	v_mul_f32_e32 v61, 0xbfb8aa3b, v55
	v_exp_f32_e32 v60, v60
	v_exp_f32_e32 v61, v61
	v_rcp_f32_e32 v58, v58
	v_rcp_f32_e32 v59, v59
	v_add_f32_e32 v60, 1.0, v60
	v_add_f32_e32 v61, 1.0, v61
	v_rcp_f32_e32 v60, v60
	v_rcp_f32_e32 v61, v61
	v_pk_mul_f32 v[52:53], v[52:53], v[58:59]
	v_cvt_pk_bf16_f32 v75, v64, v65
	v_pk_mul_f32 v[48:49], v[52:53], v[48:49]
	v_mul_f32_e32 v52, 0xbfb8aa3b, v46
	v_cvt_pk_bf16_f32 v58, v48, v49
	v_pk_mul_f32 v[48:49], v[54:55], v[60:61]
	v_mul_f32_e32 v53, 0xbfb8aa3b, v47
	v_pk_mul_f32 v[48:49], v[48:49], v[50:51]
	v_mul_f32_e32 v50, 0xbfb8aa3b, v44
	v_mul_f32_e32 v51, 0xbfb8aa3b, v45
	v_exp_f32_e32 v50, v50
	v_exp_f32_e32 v51, v51
	v_exp_f32_e32 v52, v52
	v_exp_f32_e32 v53, v53
	v_add_f32_e32 v50, 1.0, v50
	v_add_f32_e32 v51, 1.0, v51
	v_rcp_f32_e32 v50, v50
	v_rcp_f32_e32 v51, v51
	v_add_f32_e32 v52, 1.0, v52
	v_add_f32_e32 v53, 1.0, v53
	v_rcp_f32_e32 v52, v52
	v_rcp_f32_e32 v53, v53
	v_pk_mul_f32 v[44:45], v[44:45], v[50:51]
	v_add_u32_e32 v64, 0x80, v154
	v_pk_mul_f32 v[40:41], v[44:45], v[40:41]
	v_pk_mul_f32 v[44:45], v[46:47], v[52:53]
	v_cvt_pk_bf16_f32 v40, v40, v41
	v_mul_f32_e32 v41, 0xbfb8aa3b, v36
; __device__ __forceinline__ unsigned cvt_pk_bf16(float lo, float hi) { const f32x2 v = (f32x2){lo, hi}; const bf16v2 b = __builtin_convertvector(v, bf16v2); return __builtin_bit_cast(unsigned, b); }
; __device__ __forceinline__ float siluf(float x) { return x * sigm(x); }
; #define PG8_WAIT_V(n) asm volatile("s_waitcnt vmcnt(" #n ")" ::: "memory")
; #define PG8_BAR __builtin_amdgcn_s_barrier()
; template <class Epi, class Order>
; __device__ __forceinline__ void gemm_phase(LAS unsigned char* lds, const Gemm g, const Order& S, const Epi& E) {
;     ...
;         if (!has_next) break;
; #pragma unroll
;         for (int a = 0; a < 2; ++a)
; #pragma unroll
;             for (int b = 0; b < 2; ++b)
; #pragma unroll
;                 for (int m = 0; m < 4; ++m)
; #pragma unroll
;                     for (int n = 0; n < 2; ++n) acc[a][b][m][n] = (f32x4){0.f, 0.f, 0.f, 0.f};
;         cur = nxt; cA = nA; cB = nB; ++ui;
;     }
;     PG8_WAIT_V(0);
;     if (wr == 0) PG8_BAR;
;     PG8_BAR;
;     __device__ __forceinline__ void operator()(const f32x4 (&acc)[2][2][4][2], const pg8::Unit& u, int wr, int wc, int fr, int fq) const {
;     ...
;                 bf16_t* rowp = O + (size_t)(row0 + ai * 128 + m * 16) * DFF + col0;
;                 const f32x4 g0 = acc[ai][0][m][0], g1 = acc[ai][0][m][1], u0 = acc[ai][1][m][0], u1 = acc[ai][1][m][1];
;                 u32x4 w;
;                 w.x = cvt_pk_bf16(siluf(g0[0]) * u0[0], siluf(g0[1]) * u0[1]); w.y = cvt_pk_bf16(siluf(g0[2]) * u0[2], siluf(g0[3]) * u0[3]);
;                 w.z = cvt_pk_bf16(siluf(g1[0]) * u1[0], siluf(g1[1]) * u1[1]); w.w = cvt_pk_bf16(siluf(g1[2]) * u1[2], siluf(g1[3]) * u1[3]);
;                 *(u32x4*)rowp = w;
	v_pk_mul_f32 v[42:43], v[44:45], v[42:43]
	v_exp_f32_e32 v44, v41
	v_mul_f32_e32 v41, 0xbfb8aa3b, v37
	v_exp_f32_e32 v45, v41
	v_cvt_pk_bf16_f32 v41, v42, v43
	v_add_f32_e32 v42, 1.0, v44
	v_mul_f32_e32 v44, 0xbfb8aa3b, v38
	v_add_f32_e32 v43, 1.0, v45
	v_mul_f32_e32 v45, 0xbfb8aa3b, v39
	v_exp_f32_e32 v44, v44
	v_exp_f32_e32 v45, v45
	v_rcp_f32_e32 v42, v42
	v_rcp_f32_e32 v43, v43
	v_add_f32_e32 v44, 1.0, v44
	v_add_f32_e32 v45, 1.0, v45
	v_rcp_f32_e32 v44, v44
	v_rcp_f32_e32 v45, v45
	v_pk_mul_f32 v[36:37], v[36:37], v[42:43]
	v_cvt_pk_bf16_f32 v59, v48, v49
	v_pk_mul_f32 v[32:33], v[36:37], v[32:33]
	v_mul_f32_e32 v36, 0xbfb8aa3b, v30
	v_cvt_pk_bf16_f32 v42, v32, v33
	v_pk_mul_f32 v[32:33], v[38:39], v[44:45]
	v_mul_f32_e32 v37, 0xbfb8aa3b, v31
	v_pk_mul_f32 v[32:33], v[32:33], v[34:35]
	v_mul_f32_e32 v34, 0xbfb8aa3b, v28
	v_mul_f32_e32 v35, 0xbfb8aa3b, v29
	v_exp_f32_e32 v34, v34
	v_exp_f32_e32 v35, v35
	v_exp_f32_e32 v36, v36
	v_exp_f32_e32 v37, v37
	v_add_f32_e32 v34, 1.0, v34
	v_add_f32_e32 v35, 1.0, v35
	v_rcp_f32_e32 v34, v34
	v_rcp_f32_e32 v35, v35
	v_add_f32_e32 v36, 1.0, v36
	v_add_f32_e32 v37, 1.0, v37
	v_rcp_f32_e32 v36, v36
	v_rcp_f32_e32 v37, v37
	v_pk_mul_f32 v[28:29], v[28:29], v[34:35]
	v_add_u32_e32 v48, 0x90, v154
	v_pk_mul_f32 v[24:25], v[28:29], v[24:25]
	v_pk_mul_f32 v[28:29], v[30:31], v[36:37]
	v_cvt_pk_bf16_f32 v24, v24, v25
	v_mul_f32_e32 v25, 0xbfb8aa3b, v20
	v_pk_mul_f32 v[26:27], v[28:29], v[26:27]
	v_exp_f32_e32 v28, v25
	v_mul_f32_e32 v25, 0xbfb8aa3b, v21
	v_exp_f32_e32 v29, v25
	v_cvt_pk_bf16_f32 v25, v26, v27
	v_add_f32_e32 v26, 1.0, v28
	v_mul_f32_e32 v28, 0xbfb8aa3b, v22
	v_add_f32_e32 v27, 1.0, v29
	v_mul_f32_e32 v29, 0xbfb8aa3b, v23
	v_exp_f32_e32 v28, v28
	v_exp_f32_e32 v29, v29
	v_rcp_f32_e32 v26, v26
	v_rcp_f32_e32 v27, v27
	v_add_f32_e32 v28, 1.0, v28
	v_add_f32_e32 v29, 1.0, v29
	v_rcp_f32_e32 v28, v28
	v_rcp_f32_e32 v29, v29
	v_pk_mul_f32 v[20:21], v[20:21], v[26:27]
	v_cvt_pk_bf16_f32 v43, v32, v33
	v_pk_mul_f32 v[16:17], v[20:21], v[16:17]
	v_mul_f32_e32 v20, 0xbfb8aa3b, v14
	v_cvt_pk_bf16_f32 v26, v16, v17
	v_pk_mul_f32 v[16:17], v[22:23], v[28:29]
	v_mul_f32_e32 v21, 0xbfb8aa3b, v15
	v_pk_mul_f32 v[16:17], v[16:17], v[18:19]
	v_mul_f32_e32 v18, 0xbfb8aa3b, v12
	v_mul_f32_e32 v19, 0xbfb8aa3b, v13
	v_exp_f32_e32 v18, v18
	v_exp_f32_e32 v19, v19
	v_exp_f32_e32 v20, v20
	v_exp_f32_e32 v21, v21
	v_add_f32_e32 v18, 1.0, v18
	v_add_f32_e32 v19, 1.0, v19
	v_rcp_f32_e32 v18, v18
	v_rcp_f32_e32 v19, v19
	v_add_f32_e32 v20, 1.0, v20
	v_add_f32_e32 v21, 1.0, v21
	v_rcp_f32_e32 v20, v20
	v_rcp_f32_e32 v21, v21
	v_pk_mul_f32 v[12:13], v[12:13], v[18:19]
	v_add_u32_e32 v32, 0xa0, v154
	v_pk_mul_f32 v[8:9], v[12:13], v[8:9]
	v_pk_mul_f32 v[12:13], v[14:15], v[20:21]
	v_cvt_pk_bf16_f32 v8, v8, v9
	v_mul_f32_e32 v9, 0xbfb8aa3b, v4
	v_pk_mul_f32 v[10:11], v[12:13], v[10:11]
	v_exp_f32_e32 v12, v9
	v_mul_f32_e32 v9, 0xbfb8aa3b, v5
	v_exp_f32_e32 v13, v9
	v_cvt_pk_bf16_f32 v9, v10, v11
	v_add_f32_e32 v10, 1.0, v12
	v_mul_f32_e32 v12, 0xbfb8aa3b, v6
	v_add_f32_e32 v11, 1.0, v13
	v_mul_f32_e32 v13, 0xbfb8aa3b, v7
	v_exp_f32_e32 v12, v12
	v_exp_f32_e32 v13, v13
	v_rcp_f32_e32 v10, v10
	v_rcp_f32_e32 v11, v11
	v_add_f32_e32 v12, 1.0, v12
	v_add_f32_e32 v13, 1.0, v13
	v_rcp_f32_e32 v12, v12
	v_rcp_f32_e32 v13, v13
	v_pk_mul_f32 v[4:5], v[4:5], v[10:11]
	v_cvt_pk_bf16_f32 v27, v16, v17
	v_pk_mul_f32 v[0:1], v[4:5], v[0:1]
	v_add_u32_e32 v16, 0xb0, v154
	v_cvt_pk_bf16_f32 v10, v0, v1
	v_pk_mul_f32 v[0:1], v[6:7], v[12:13]
	v_mad_i64_i32 v[156:157], s[24:25], v154, s72, v[146:147]
	v_lshlrev_b64 v[144:145], 1, v[144:145]
	v_mad_i64_i32 v[112:113], s[24:25], v112, s72, v[146:147]
	v_mad_i64_i32 v[96:97], s[24:25], v96, s72, v[146:147]
	v_mad_i64_i32 v[80:81], s[24:25], v80, s72, v[146:147]
	v_mad_i64_i32 v[64:65], s[24:25], v64, s72, v[146:147]
	v_mad_i64_i32 v[48:49], s[24:25], v48, s72, v[146:147]
	v_mad_i64_i32 v[32:33], s[24:25], v32, s72, v[146:147]
	v_mad_i64_i32 v[16:17], s[24:25], v16, s72, v[146:147]
	v_pk_mul_f32 v[0:1], v[0:1], v[2:3]
	v_lshl_add_u64 v[156:157], v[156:157], 0, v[144:145]
	v_lshl_add_u64 v[112:113], v[112:113], 0, v[144:145]
	v_lshl_add_u64 v[96:97], v[96:97], 0, v[144:145]
	v_lshl_add_u64 v[80:81], v[80:81], 0, v[144:145]
	v_lshl_add_u64 v[64:65], v[64:65], 0, v[144:145]
	v_lshl_add_u64 v[48:49], v[48:49], 0, v[144:145]
	v_lshl_add_u64 v[32:33], v[32:33], 0, v[144:145]
	v_lshl_add_u64 v[16:17], v[16:17], 0, v[144:145]
	v_cvt_pk_bf16_f32 v11, v0, v1
	s_and_b64 vcc, exec, s[2:3]
	s_mov_b32 s33, s8
	s_mov_b32 s22, s10
	s_mov_b64 s[42:43], s[20:21]
	s_mov_b64 s[38:39], s[16:17]
	global_store_dwordx4 v[156:157], v[120:123], off
	global_store_dwordx4 v[112:113], v[104:107], off
	global_store_dwordx4 v[96:97], v[88:91], off
	global_store_dwordx4 v[80:81], v[72:75], off
	global_store_dwordx4 v[64:65], v[56:59], off
	global_store_dwordx4 v[48:49], v[40:43], off
	global_store_dwordx4 v[32:33], v[24:27], off
	global_store_dwordx4 v[16:17], v[8:11], off
	s_cbranch_vccz .LBB0_219
	s_waitcnt vmcnt(0)
	v_readlane_b32 s94, v254, 22
	s_cmpk_gt_u32 s31, 0xff
	v_readlane_b32 s95, v254, 23
	s_cbranch_scc1 .LBB0_226
	s_barrier

; #define PG8_STAGE(bufoff, gbase, voff) do { _Pragma("unroll") for (int _i = 0; _i < 2; ++_i) \
;         __builtin_amdgcn_global_load_lds((const unsigned*)((const char*)(gbase) + (voff)[_i]), (LAS unsigned*)(lds + (bufoff) + ldsw + _i * 8192), 16, 0, 0); } while (0)
; #define PG8_WAIT_V(n) asm volatile("s_waitcnt vmcnt(" #n ")" ::: "memory")
; #define PG8_BAR __builtin_amdgcn_s_barrier()
; template <class Epi, class Order>
; __device__ __forceinline__ void gemm_phase(LAS unsigned char* lds, const Gemm g, const Order& S, const Epi& E) {
;     ...
;     for (int i = 0; i < 2; ++i) { int R, C; stage_rc(tid * 16 + i * 8192, R, C); const int Rb = Epi::PERM ? ((R & ~31) + perm32(R & 31)) : R;
;         voffA[i] = (unsigned)(R * g.ld + C) * 2u; voffB[i] = (unsigned)(Rb * g.ld + C) * 2u; }
;     const size_t kstep = (size_t)(BK * 2);
;     const size_t hstep = (size_t)HALF * g.ld * 2;
;     const size_t sstep = (size_t)K * 2;
;     const size_t tstep = 2 * hstep;
;     const unsigned ldsw = (unsigned)wid * 1024u;
;     const int aoff = lds_byte(wr * 64 + fr, fq * 8), boff = lds_byte(wc * 32 + fr, fq * 8);
;     ...
;     PG8_STAGE(PG8_SB(1, 0), cB + kstep, voffB); PG8_STAGE(PG8_SA(1, 0), cA + kstep, voffA); PG8_STAGE(PG8_SB(1, 1), cB + hstep + kstep, voffB);
;     PG8_WAIT_V(6); PG8_BAR;
.LBB0_447:
	s_add_u32 s2, s88, 0xfe00000
	s_addc_u32 s3, s89, 0
	s_lshl_b32 s8, s8, 5
	s_and_b32 s20, s8, 0x60
	s_mov_b64 s[8:9], 0x80
	s_add_i32 m0, s5, 0x18000
	v_lshl_add_u64 v[6:7], v[6:7], 0, s[8:9]
	s_ashr_i32 s60, s28, 31
	s_ashr_i32 s61, s26, 31
	s_lshl_b32 s11, s10, 13
	s_lshl_b32 s21, s20, 7
	s_waitcnt vmcnt(4)
	s_barrier
	global_load_lds_dwordx4 v[6:7], off
	v_lshl_add_u64 v[4:5], v[4:5], 0, s[8:9]
	s_add_i32 m0, s5, 0x1a000
	s_add_i32 s66, s5, 0x8000
	s_add_i32 s67, s5, 0xa000
	global_load_lds_dwordx4 v[4:5], off
	v_lshl_add_u64 v[2:3], v[2:3], 0, s[8:9]
	s_mov_b32 m0, s66
	s_add_u32 s16, s44, 0x80080
	global_load_lds_dwordx4 v[2:3], off
	v_lshl_add_u64 v[0:1], v[0:1], 0, s[8:9]
	s_mov_b32 m0, s67
	s_addc_u32 s17, s45, 0
	global_load_lds_dwordx4 v[0:1], off
	s_add_i32 m0, s5, 0x1c000
	s_nop 0
	global_load_lds_dwordx4 v130, s[16:17]
	s_add_i32 m0, s5, 0x1e000
	v_lshlrev_b32_e32 v2, 6, v241
	global_load_lds_dwordx4 v134, s[16:17]
	v_and_b32_e32 v0, 15, v241
	v_lshlrev_b32_e32 v1, 1, v11
	s_movk_i32 s16, 0x3c0
	v_lshlrev_b32_e32 v3, 2, v241
	v_and_or_b32 v2, v2, s16, v1
	v_and_b32_e32 v3, 32, v3
	v_lshl_or_b32 v142, s10, 6, v0
	v_lshl_or_b32 v0, v0, 6, v1
	v_lshlrev_b32_e32 v1, 9, v241
	v_bitop3_b32 v143, s21, v2, v3 bitop3:0xf6
	v_and_b32_e32 v1, 0x70000, v1
	v_lshlrev_b32_e32 v2, 12, v10
	v_or3_b32 v1, v8, v1, v2
	v_add_u32_e32 v136, v1, v9
	v_lshlrev_b32_e32 v1, 5, v12
	s_waitcnt vmcnt(6)
	v_and_b32_e32 v1, 0xf0000, v1
	v_bitop3_b32 v0, v0, s11, v3 bitop3:0xde
	v_or3_b32 v1, v8, v1, v2
	s_add_i32 s70, 0, 0x10000
	s_add_i32 s71, 0, 0x14000
	s_mov_b32 s68, s28
	v_or_b32_e32 v144, s20, v11
	v_mov_b32_e32 v137, v131
	v_add_u32_e32 v138, v1, v9
	v_mov_b32_e32 v139, v131
	v_mov_b64_e32 v[140:141], 0xa7f
	s_movk_i32 s69, 0x151
	v_add_u32_e32 v145, s70, v143
	v_add_u32_e32 v146, 0, v0
	v_add_u32_e32 v147, s71, v143
	s_movk_i32 s72, 0x2a00
	s_barrier

; #define PG8_STAGE(bufoff, gbase, voff) do { _Pragma("unroll") for (int _i = 0; _i < 2; ++_i) \
;         __builtin_amdgcn_global_load_lds((const unsigned*)((const char*)(gbase) + (voff)[_i]), (LAS unsigned*)(lds + (bufoff) + ldsw + _i * 8192), 16, 0, 0); } while (0)
; #define PG8_LDA(dst, b, h) do { _Pragma("unroll") for (int m = 0; m < 4; ++m) _Pragma("unroll") for (int k = 0; k < 2; ++k) dst[m][k] = *(const LAS bf16x8*)(lds + PG8_SA(b, h) + aoff + m * 2048 + k * 1024); } while (0)
; #define PG8_LDB(dst, b, h) do { _Pragma("unroll") for (int n = 0; n < 2; ++n) _Pragma("unroll") for (int k = 0; k < 2; ++k) dst[n][k] = *(const LAS bf16x8*)(lds + PG8_SB(b, h) + boff + n * 2048 + k * 1024); } while (0)
; #define PG8_MMA(ai, bj, At, Bt) do { __builtin_amdgcn_s_setprio(1); _Pragma("unroll") for (int m = 0; m < 4; ++m) _Pragma("unroll") for (int n = 0; n < 2; ++n) _Pragma("unroll") for (int k = 0; k < 2; ++k) \
;         acc[ai][bj][m][n] = __builtin_amdgcn_mfma_f32_16x16x32_bf16(Bt[n][k], At[m][k], acc[ai][bj][m][n], 0, 0, 0); __builtin_amdgcn_s_setprio(0); } while (0)
; #define PG8_WAIT_L(n) asm volatile("s_waitcnt lgkmcnt(" #n ")" ::: "memory")
; #define PG8_BAR __builtin_amdgcn_s_barrier()
; #define PG8_SCHED __builtin_amdgcn_sched_barrier(0)
; template <class Epi, class Order>
; __device__ __forceinline__ void gemm_phase(LAS unsigned char* lds, const Gemm g, const Order& S, const Epi& E) {
;     ...
;             PG8_LDB(B0, 0, 0); PG8_SCHED; PG8_LDA(At, 0, 0); PG8_STAGE(PG8_SA(1, 1), a1 + hstep, voffA);
;             PG8_WAIT_L(8); PG8_BAR; PG8_WAIT_L(0); PG8_MMA(0, 0, At, B0); PG8_BAR; PG8_SCHED;
;             PG8_LDB(B1, 0, 1); PG8_STAGE(PG8_SB(0, 0), b2, voffB);
;             PG8_BAR; PG8_WAIT_L(0); PG8_MMA(0, 1, At, B1); PG8_BAR;
;             PG8_LDA(At, 0, 1); PG8_STAGE(PG8_SA(0, 0), a2, voffA);
;             PG8_BAR; PG8_WAIT_L(0); PG8_MMA(1, 0, At, B0); PG8_BAR; PG8_SCHED;
.LBB0_454:
	ds_read_b128 v[148:151], v145
	ds_read_b128 v[152:155], v145 offset:1024
	ds_read_b128 v[156:159], v145 offset:2048
	ds_read_b128 v[160:163], v145 offset:3072
	s_add_u32 s24, s42, 0xfff80080
	s_addc_u32 s25, s43, -1
	s_cmp_eq_u32 s95, 28
	s_cselect_b32 s47, s17, s25
	s_cselect_b32 s46, s73, s24
	s_cselect_b32 s45, s11, s94
	s_cselect_b32 s44, s84, s85
	v_lshl_add_u64 v[198:199], s[42:43], 0, v[136:137]
	s_add_i32 m0, s5, 0xc000
	ds_read_b128 v[164:167], v146
	ds_read_b128 v[168:171], v146 offset:1024
	ds_read_b128 v[172:175], v146 offset:2048
	ds_read_b128 v[176:179], v146 offset:3072
	ds_read_b128 v[182:185], v146 offset:4096
	ds_read_b128 v[186:189], v146 offset:5120
	ds_read_b128 v[190:193], v146 offset:6144
	ds_read_b128 v[194:197], v146 offset:7168
	global_load_lds_dwordx4 v[198:199], off
	v_lshl_add_u64 v[198:199], s[42:43], 0, v[138:139]
	s_add_i32 m0, s5, 0xe000
	s_nop 0
	global_load_lds_dwordx4 v[198:199], off
	s_waitcnt lgkmcnt(8)
	s_barrier
	s_waitcnt lgkmcnt(0)
	s_setprio 1
	s_waitcnt lgkmcnt(0)
	v_mfma_f32_16x16x32_bf16 v[124:127], v[148:151], v[164:167], v[124:127]
	v_mfma_f32_16x16x32_bf16 v[120:123], v[156:159], v[164:167], v[120:123]
	v_mfma_f32_16x16x32_bf16 v[116:119], v[148:151], v[172:175], v[116:119]
	v_mfma_f32_16x16x32_bf16 v[112:115], v[156:159], v[172:175], v[112:115]
	v_mfma_f32_16x16x32_bf16 v[100:103], v[148:151], v[182:185], v[100:103]
	v_mfma_f32_16x16x32_bf16 v[96:99], v[156:159], v[182:185], v[96:99]
	v_mfma_f32_16x16x32_bf16 v[84:87], v[148:151], v[190:193], v[84:87]
	v_mfma_f32_16x16x32_bf16 v[80:83], v[156:159], v[190:193], v[80:83]
	v_mfma_f32_16x16x32_bf16 v[124:127], v[152:155], v[168:171], v[124:127]
	v_mfma_f32_16x16x32_bf16 v[120:123], v[160:163], v[168:171], v[120:123]
	v_mfma_f32_16x16x32_bf16 v[116:119], v[152:155], v[176:179], v[116:119]
	v_mfma_f32_16x16x32_bf16 v[112:115], v[160:163], v[176:179], v[112:115]
	v_mfma_f32_16x16x32_bf16 v[100:103], v[152:155], v[186:189], v[100:103]
	v_mfma_f32_16x16x32_bf16 v[96:99], v[160:163], v[186:189], v[96:99]
	v_mfma_f32_16x16x32_bf16 v[84:87], v[152:155], v[194:197], v[84:87]
	v_mfma_f32_16x16x32_bf16 v[80:83], v[160:163], v[194:197], v[80:83]
	s_setprio 0
	s_barrier
	s_add_i32 s24, s70, s52
	v_lshl_add_u64 v[214:215], s[44:45], 0, v[130:131]
	s_mov_b32 m0, s24
	ds_read_b128 v[198:201], v147
	ds_read_b128 v[202:205], v147 offset:1024
	ds_read_b128 v[206:209], v147 offset:2048
	ds_read_b128 v[210:213], v147 offset:3072
	global_load_lds_dwordx4 v[214:215], off
	v_lshl_add_u64 v[216:217], s[44:45], 0, v[134:135]
	s_add_i32 m0, s24, 0x2000
	s_nop 0
	global_load_lds_dwordx4 v[216:217], off
	s_barrier
	s_waitcnt lgkmcnt(0)
	s_setprio 1
	s_waitcnt lgkmcnt(0)
	v_mfma_f32_16x16x32_bf16 v[108:111], v[198:201], v[164:167], v[108:111]
	v_mfma_f32_16x16x32_bf16 v[104:107], v[206:209], v[164:167], v[104:107]
	v_mfma_f32_16x16x32_bf16 v[92:95], v[198:201], v[172:175], v[92:95]
	v_mfma_f32_16x16x32_bf16 v[88:91], v[206:209], v[172:175], v[88:91]
	v_mfma_f32_16x16x32_bf16 v[76:79], v[198:201], v[182:185], v[76:79]
	v_mfma_f32_16x16x32_bf16 v[72:75], v[206:209], v[182:185], v[72:75]
	v_mfma_f32_16x16x32_bf16 v[68:71], v[198:201], v[190:193], v[68:71]
	v_mfma_f32_16x16x32_bf16 v[64:67], v[206:209], v[190:193], v[64:67]
	v_mfma_f32_16x16x32_bf16 v[108:111], v[202:205], v[168:171], v[108:111]
	v_mfma_f32_16x16x32_bf16 v[104:107], v[210:213], v[168:171], v[104:107]
	v_mfma_f32_16x16x32_bf16 v[92:95], v[202:205], v[176:179], v[92:95]
	v_mfma_f32_16x16x32_bf16 v[88:91], v[210:213], v[176:179], v[88:91]
	v_mfma_f32_16x16x32_bf16 v[76:79], v[202:205], v[186:189], v[76:79]
	v_mfma_f32_16x16x32_bf16 v[72:75], v[210:213], v[186:189], v[72:75]
	v_mfma_f32_16x16x32_bf16 v[68:71], v[202:205], v[194:197], v[68:71]
	v_mfma_f32_16x16x32_bf16 v[64:67], v[210:213], v[194:197], v[64:67]
	s_setprio 0
	s_mov_b32 m0, s5
	v_lshl_add_u64 v[218:219], s[46:47], 0, v[128:129]
	s_barrier
	ds_read_b128 v[164:167], v146 offset:16384
	ds_read_b128 v[168:171], v146 offset:17408
	ds_read_b128 v[172:175], v146 offset:18432
	ds_read_b128 v[176:179], v146 offset:19456
	ds_read_b128 v[182:185], v146 offset:20480
	ds_read_b128 v[186:189], v146 offset:21504
	ds_read_b128 v[190:193], v146 offset:22528
	ds_read_b128 v[194:197], v146 offset:23552
	global_load_lds_dwordx4 v[218:219], off
	v_lshl_add_u64 v[220:221], s[46:47], 0, v[132:133]
	s_mov_b32 m0, s7
	s_nop 0
	global_load_lds_dwordx4 v[220:221], off
	s_barrier
	s_waitcnt lgkmcnt(0)
	s_setprio 1
	s_waitcnt lgkmcnt(0)
	v_mfma_f32_16x16x32_bf16 v[60:63], v[148:151], v[164:167], v[60:63]
	v_mfma_f32_16x16x32_bf16 v[56:59], v[156:159], v[164:167], v[56:59]
	v_mfma_f32_16x16x32_bf16 v[52:55], v[148:151], v[172:175], v[52:55]
	v_mfma_f32_16x16x32_bf16 v[48:51], v[156:159], v[172:175], v[48:51]
	v_mfma_f32_16x16x32_bf16 v[36:39], v[148:151], v[182:185], v[36:39]
	v_mfma_f32_16x16x32_bf16 v[32:35], v[156:159], v[182:185], v[32:35]
	v_mfma_f32_16x16x32_bf16 v[20:23], v[148:151], v[190:193], v[20:23]
	v_mfma_f32_16x16x32_bf16 v[16:19], v[156:159], v[190:193], v[16:19]
	v_mfma_f32_16x16x32_bf16 v[60:63], v[152:155], v[168:171], v[60:63]
	v_mfma_f32_16x16x32_bf16 v[56:59], v[160:163], v[168:171], v[56:59]
	v_mfma_f32_16x16x32_bf16 v[52:55], v[152:155], v[176:179], v[52:55]
	v_mfma_f32_16x16x32_bf16 v[48:51], v[160:163], v[176:179], v[48:51]
	v_mfma_f32_16x16x32_bf16 v[36:39], v[152:155], v[186:189], v[36:39]
	v_mfma_f32_16x16x32_bf16 v[32:35], v[160:163], v[186:189], v[32:35]
	v_mfma_f32_16x16x32_bf16 v[20:23], v[152:155], v[194:197], v[20:23]
	v_mfma_f32_16x16x32_bf16 v[16:19], v[160:163], v[194:197], v[16:19]
	s_setprio 0
	s_barrier
; #define PG8_STAGE(bufoff, gbase, voff) do { _Pragma("unroll") for (int _i = 0; _i < 2; ++_i) \
;         __builtin_amdgcn_global_load_lds((const unsigned*)((const char*)(gbase) + (voff)[_i]), (LAS unsigned*)(lds + (bufoff) + ldsw + _i * 8192), 16, 0, 0); } while (0)
; #define PG8_LDA(dst, b, h) do { _Pragma("unroll") for (int m = 0; m < 4; ++m) _Pragma("unroll") for (int k = 0; k < 2; ++k) dst[m][k] = *(const LAS bf16x8*)(lds + PG8_SA(b, h) + aoff + m * 2048 + k * 1024); } while (0)
; #define PG8_LDB(dst, b, h) do { _Pragma("unroll") for (int n = 0; n < 2; ++n) _Pragma("unroll") for (int k = 0; k < 2; ++k) dst[n][k] = *(const LAS bf16x8*)(lds + PG8_SB(b, h) + boff + n * 2048 + k * 1024); } while (0)
; #define PG8_MMA(ai, bj, At, Bt) do { __builtin_amdgcn_s_setprio(1); _Pragma("unroll") for (int m = 0; m < 4; ++m) _Pragma("unroll") for (int n = 0; n < 2; ++n) _Pragma("unroll") for (int k = 0; k < 2; ++k) \
;         acc[ai][bj][m][n] = __builtin_amdgcn_mfma_f32_16x16x32_bf16(Bt[n][k], At[m][k], acc[ai][bj][m][n], 0, 0, 0); __builtin_amdgcn_s_setprio(0); } while (0)
; #define PG8_WAIT_V(n) asm volatile("s_waitcnt vmcnt(" #n ")" ::: "memory")
; #define PG8_WAIT_L(n) asm volatile("s_waitcnt lgkmcnt(" #n ")" ::: "memory")
; #define PG8_BAR __builtin_amdgcn_s_barrier()
; #define PG8_SCHED __builtin_amdgcn_sched_barrier(0)
; template <class Epi, class Order>
; __device__ __forceinline__ void gemm_phase(LAS unsigned char* lds, const Gemm g, const Order& S, const Epi& E) {
;     ...
;             PG8_STAGE(PG8_SB(0, 1), b2 + hstep, voffB);
;             PG8_WAIT_V(6); PG8_BAR; PG8_MMA(1, 1, At, B1); PG8_BAR;
;             PG8_LDB(B0, 1, 0); PG8_SCHED; PG8_LDA(At, 1, 0); PG8_STAGE(PG8_SA(0, 1), a2 + hstep, voffA);
;             PG8_WAIT_L(8); PG8_BAR; PG8_WAIT_L(0); PG8_MMA(0, 0, At, B0); PG8_BAR; PG8_SCHED;
;             PG8_LDB(B1, 1, 1); PG8_STAGE(PG8_SB(1, 0), b3, voffB);
;             PG8_BAR; PG8_WAIT_L(0); PG8_MMA(0, 1, At, B1); PG8_BAR;
;             PG8_LDA(At, 1, 1); PG8_STAGE(PG8_SA(1, 0), a3, voffA);
	s_add_u32 s24, s44, 0x80000
	s_addc_u32 s25, s45, 0
	s_add_i32 s27, s71, s52
	s_mov_b32 m0, s27
	s_nop 0
	global_load_lds_dwordx4 v130, s[24:25]
	s_add_i32 m0, s27, 0x2000
	s_nop 0
	global_load_lds_dwordx4 v134, s[24:25]
	s_waitcnt vmcnt(6)
	s_barrier
	s_setprio 1
	v_mfma_f32_16x16x32_bf16 v[44:47], v[198:201], v[164:167], v[44:47]
	v_mfma_f32_16x16x32_bf16 v[40:43], v[206:209], v[164:167], v[40:43]
	v_mfma_f32_16x16x32_bf16 v[28:31], v[198:201], v[172:175], v[28:31]
	v_mfma_f32_16x16x32_bf16 v[24:27], v[206:209], v[172:175], v[24:27]
	v_mfma_f32_16x16x32_bf16 v[12:15], v[198:201], v[182:185], v[12:15]
	v_mfma_f32_16x16x32_bf16 v[8:11], v[206:209], v[182:185], v[8:11]
	v_mfma_f32_16x16x32_bf16 v[4:7], v[198:201], v[190:193], v[4:7]
	v_mfma_f32_16x16x32_bf16 v[0:3], v[206:209], v[190:193], v[0:3]
	v_mfma_f32_16x16x32_bf16 v[44:47], v[202:205], v[168:171], v[44:47]
	v_mfma_f32_16x16x32_bf16 v[40:43], v[210:213], v[168:171], v[40:43]
	v_mfma_f32_16x16x32_bf16 v[28:31], v[202:205], v[176:179], v[28:31]
	v_mfma_f32_16x16x32_bf16 v[24:27], v[210:213], v[176:179], v[24:27]
	v_mfma_f32_16x16x32_bf16 v[12:15], v[202:205], v[186:189], v[12:15]
	v_mfma_f32_16x16x32_bf16 v[8:11], v[210:213], v[186:189], v[8:11]
	v_mfma_f32_16x16x32_bf16 v[4:7], v[202:205], v[194:197], v[4:7]
	v_mfma_f32_16x16x32_bf16 v[0:3], v[210:213], v[194:197], v[0:3]
	s_setprio 0
	s_add_i32 s27, 0, 0x18000
	v_add_u32_e32 v160, s27, v143
	s_barrier
	ds_read_b128 v[148:151], v160
	ds_read_b128 v[152:155], v160 offset:1024
	ds_read_b128 v[156:159], v160 offset:2048
	ds_read_b128 v[160:163], v160 offset:3072
	s_add_u32 s24, s46, 0x80000
	s_addc_u32 s25, s47, 0
	s_mov_b32 m0, s53
	ds_read_b128 v[164:167], v146 offset:32768
	ds_read_b128 v[168:171], v146 offset:33792
	ds_read_b128 v[172:175], v146 offset:34816
	ds_read_b128 v[176:179], v146 offset:35840
	ds_read_b128 v[182:185], v146 offset:36864
	ds_read_b128 v[186:189], v146 offset:37888
	ds_read_b128 v[190:193], v146 offset:38912
	ds_read_b128 v[194:197], v146 offset:39936
	global_load_lds_dwordx4 v128, s[24:25]
	s_mov_b32 m0, s54
	s_nop 0
	global_load_lds_dwordx4 v132, s[24:25]
	s_waitcnt lgkmcnt(8)
	s_barrier
	s_waitcnt lgkmcnt(0)
	s_setprio 1
	s_waitcnt lgkmcnt(0)
	v_mfma_f32_16x16x32_bf16 v[124:127], v[148:151], v[164:167], v[124:127]
	v_mfma_f32_16x16x32_bf16 v[120:123], v[156:159], v[164:167], v[120:123]
	v_mfma_f32_16x16x32_bf16 v[116:119], v[148:151], v[172:175], v[116:119]
	v_mfma_f32_16x16x32_bf16 v[112:115], v[156:159], v[172:175], v[112:115]
	v_mfma_f32_16x16x32_bf16 v[100:103], v[148:151], v[182:185], v[100:103]
	v_mfma_f32_16x16x32_bf16 v[96:99], v[156:159], v[182:185], v[96:99]
	v_mfma_f32_16x16x32_bf16 v[84:87], v[148:151], v[190:193], v[84:87]
	v_mfma_f32_16x16x32_bf16 v[80:83], v[156:159], v[190:193], v[80:83]
	v_mfma_f32_16x16x32_bf16 v[124:127], v[152:155], v[168:171], v[124:127]
	v_mfma_f32_16x16x32_bf16 v[120:123], v[160:163], v[168:171], v[120:123]
	v_mfma_f32_16x16x32_bf16 v[116:119], v[152:155], v[176:179], v[116:119]
	v_mfma_f32_16x16x32_bf16 v[112:115], v[160:163], v[176:179], v[112:115]
	v_mfma_f32_16x16x32_bf16 v[100:103], v[152:155], v[186:189], v[100:103]
	v_mfma_f32_16x16x32_bf16 v[96:99], v[160:163], v[186:189], v[96:99]
	v_mfma_f32_16x16x32_bf16 v[84:87], v[152:155], v[194:197], v[84:87]
	v_mfma_f32_16x16x32_bf16 v[80:83], v[160:163], v[194:197], v[80:83]
	s_setprio 0
	s_barrier
	s_add_i32 s46, 0, 0x1c000
	s_add_i32 s24, s27, s52
	v_add_u32_e32 v181, s46, v143
	v_lshl_add_u64 v[214:215], v[214:215], 0, s[8:9]
	s_mov_b32 m0, s24
	ds_read_b128 v[198:201], v181
	ds_read_b128 v[202:205], v181 offset:1024
	ds_read_b128 v[206:209], v181 offset:2048
	ds_read_b128 v[210:213], v181 offset:3072
	global_load_lds_dwordx4 v[214:215], off
	v_lshl_add_u64 v[214:215], v[216:217], 0, s[8:9]
	s_add_i32 m0, s24, 0x2000
	s_nop 0
	global_load_lds_dwordx4 v[214:215], off
	s_barrier
	s_waitcnt lgkmcnt(0)
	s_setprio 1
	s_waitcnt lgkmcnt(0)
	v_mfma_f32_16x16x32_bf16 v[108:111], v[198:201], v[164:167], v[108:111]
	v_mfma_f32_16x16x32_bf16 v[104:107], v[206:209], v[164:167], v[104:107]
	v_mfma_f32_16x16x32_bf16 v[92:95], v[198:201], v[172:175], v[92:95]
	v_mfma_f32_16x16x32_bf16 v[88:91], v[206:209], v[172:175], v[88:91]
	v_mfma_f32_16x16x32_bf16 v[76:79], v[198:201], v[182:185], v[76:79]
	v_mfma_f32_16x16x32_bf16 v[72:75], v[206:209], v[182:185], v[72:75]
	v_mfma_f32_16x16x32_bf16 v[68:71], v[198:201], v[190:193], v[68:71]
	v_mfma_f32_16x16x32_bf16 v[64:67], v[206:209], v[190:193], v[64:67]
	v_mfma_f32_16x16x32_bf16 v[108:111], v[202:205], v[168:171], v[108:111]
	v_mfma_f32_16x16x32_bf16 v[104:107], v[210:213], v[168:171], v[104:107]
	v_mfma_f32_16x16x32_bf16 v[92:95], v[202:205], v[176:179], v[92:95]
	v_mfma_f32_16x16x32_bf16 v[88:91], v[210:213], v[176:179], v[88:91]
	v_mfma_f32_16x16x32_bf16 v[76:79], v[202:205], v[186:189], v[76:79]
	v_mfma_f32_16x16x32_bf16 v[72:75], v[210:213], v[186:189], v[72:75]
	v_mfma_f32_16x16x32_bf16 v[68:71], v[202:205], v[194:197], v[68:71]
	v_mfma_f32_16x16x32_bf16 v[64:67], v[210:213], v[194:197], v[64:67]
	s_setprio 0
	s_mov_b32 m0, s66
	v_lshl_add_u64 v[214:215], v[218:219], 0, s[8:9]
	s_barrier
	ds_read_b128 v[164:167], v146 offset:49152
	ds_read_b128 v[168:171], v146 offset:50176
	ds_read_b128 v[172:175], v146 offset:51200
	ds_read_b128 v[176:179], v146 offset:52224
	ds_read_b128 v[182:185], v146 offset:53248
	ds_read_b128 v[186:189], v146 offset:54272
	ds_read_b128 v[190:193], v146 offset:55296
	ds_read_b128 v[194:197], v146 offset:56320
	global_load_lds_dwordx4 v[214:215], off
	v_lshl_add_u64 v[214:215], v[220:221], 0, s[8:9]
	s_mov_b32 m0, s67
	s_nop 0
	global_load_lds_dwordx4 v[214:215], off
	s_barrier
; #define PG8_STAGE(bufoff, gbase, voff) do { _Pragma("unroll") for (int _i = 0; _i < 2; ++_i) \
;         __builtin_amdgcn_global_load_lds((const unsigned*)((const char*)(gbase) + (voff)[_i]), (LAS unsigned*)(lds + (bufoff) + ldsw + _i * 8192), 16, 0, 0); } while (0)
; #define PG8_MMA(ai, bj, At, Bt) do { __builtin_amdgcn_s_setprio(1); _Pragma("unroll") for (int m = 0; m < 4; ++m) _Pragma("unroll") for (int n = 0; n < 2; ++n) _Pragma("unroll") for (int k = 0; k < 2; ++k) \
;         acc[ai][bj][m][n] = __builtin_amdgcn_mfma_f32_16x16x32_bf16(Bt[n][k], At[m][k], acc[ai][bj][m][n], 0, 0, 0); __builtin_amdgcn_s_setprio(0); } while (0)
; #define PG8_WAIT_V(n) asm volatile("s_waitcnt vmcnt(" #n ")" ::: "memory")
; #define PG8_WAIT_L(n) asm volatile("s_waitcnt lgkmcnt(" #n ")" ::: "memory")
; #define PG8_BAR __builtin_amdgcn_s_barrier()
; #define PG8_SCHED __builtin_amdgcn_sched_barrier(0)
; template <class Epi, class Order>
; __device__ __forceinline__ void gemm_phase(LAS unsigned char* lds, const Gemm g, const Order& S, const Epi& E) {
;     ...
;             PG8_BAR; PG8_WAIT_L(0); PG8_MMA(1, 0, At, B0); PG8_BAR; PG8_SCHED;
;             PG8_STAGE(PG8_SB(1, 1), b3 + hstep, voffB);
;             PG8_WAIT_V(6); PG8_BAR; PG8_MMA(1, 1, At, B1); PG8_BAR;
	s_waitcnt lgkmcnt(0)
	s_setprio 1
	s_waitcnt lgkmcnt(0)
	v_mfma_f32_16x16x32_bf16 v[60:63], v[148:151], v[164:167], v[60:63]
	v_mfma_f32_16x16x32_bf16 v[56:59], v[156:159], v[164:167], v[56:59]
	v_mfma_f32_16x16x32_bf16 v[52:55], v[148:151], v[172:175], v[52:55]
	v_mfma_f32_16x16x32_bf16 v[48:51], v[156:159], v[172:175], v[48:51]
	v_mfma_f32_16x16x32_bf16 v[36:39], v[148:151], v[182:185], v[36:39]
	v_mfma_f32_16x16x32_bf16 v[32:35], v[156:159], v[182:185], v[32:35]
	v_mfma_f32_16x16x32_bf16 v[20:23], v[148:151], v[190:193], v[20:23]
	v_mfma_f32_16x16x32_bf16 v[16:19], v[156:159], v[190:193], v[16:19]
	v_mfma_f32_16x16x32_bf16 v[60:63], v[152:155], v[168:171], v[60:63]
	v_mfma_f32_16x16x32_bf16 v[56:59], v[160:163], v[168:171], v[56:59]
	v_mfma_f32_16x16x32_bf16 v[52:55], v[152:155], v[176:179], v[52:55]
	v_mfma_f32_16x16x32_bf16 v[48:51], v[160:163], v[176:179], v[48:51]
	v_mfma_f32_16x16x32_bf16 v[36:39], v[152:155], v[186:189], v[36:39]
	v_mfma_f32_16x16x32_bf16 v[32:35], v[160:163], v[186:189], v[32:35]
	v_mfma_f32_16x16x32_bf16 v[20:23], v[152:155], v[194:197], v[20:23]
	v_mfma_f32_16x16x32_bf16 v[16:19], v[160:163], v[194:197], v[16:19]
	s_setprio 0
	s_barrier
	s_add_u32 s24, s44, 0x80080
	s_addc_u32 s25, s45, 0
	s_add_i32 s27, s46, s52
	s_mov_b32 m0, s27
	s_nop 0
	global_load_lds_dwordx4 v130, s[24:25]
	v_lshl_add_u64 v[148:149], s[24:25], 0, v[134:135]
	s_add_i32 m0, s27, 0x2000
	s_nop 0
	global_load_lds_dwordx4 v[148:149], off
	s_waitcnt vmcnt(6)
	s_barrier
	s_setprio 1
	v_mfma_f32_16x16x32_bf16 v[44:47], v[198:201], v[164:167], v[44:47]
	v_mfma_f32_16x16x32_bf16 v[40:43], v[206:209], v[164:167], v[40:43]
	v_mfma_f32_16x16x32_bf16 v[28:31], v[198:201], v[172:175], v[28:31]
	v_mfma_f32_16x16x32_bf16 v[24:27], v[206:209], v[172:175], v[24:27]
	v_mfma_f32_16x16x32_bf16 v[12:15], v[198:201], v[182:185], v[12:15]
	v_mfma_f32_16x16x32_bf16 v[8:11], v[206:209], v[182:185], v[8:11]
	v_mfma_f32_16x16x32_bf16 v[4:7], v[198:201], v[190:193], v[4:7]
	v_mfma_f32_16x16x32_bf16 v[0:3], v[206:209], v[190:193], v[0:3]
	v_mfma_f32_16x16x32_bf16 v[44:47], v[202:205], v[168:171], v[44:47]
	v_mfma_f32_16x16x32_bf16 v[40:43], v[210:213], v[168:171], v[40:43]
	v_mfma_f32_16x16x32_bf16 v[28:31], v[202:205], v[176:179], v[28:31]
	v_mfma_f32_16x16x32_bf16 v[24:27], v[210:213], v[176:179], v[24:27]
	v_mfma_f32_16x16x32_bf16 v[12:15], v[202:205], v[186:189], v[12:15]
	v_mfma_f32_16x16x32_bf16 v[8:11], v[210:213], v[186:189], v[8:11]
	v_mfma_f32_16x16x32_bf16 v[4:7], v[202:205], v[194:197], v[4:7]
	v_mfma_f32_16x16x32_bf16 v[0:3], v[210:213], v[194:197], v[0:3]
	s_setprio 0
	s_add_i32 s95, s95, 2
	s_add_u32 s42, s42, 0x100
	s_addc_u32 s43, s43, 0
	s_add_u32 s85, s85, 0x100
	s_addc_u32 s94, s94, 0
	s_cmp_gt_u32 s95, 29
	s_barrier
	s_cbranch_scc0 .LBB0_454
; #define PG8_WAIT_V(n) asm volatile("s_waitcnt vmcnt(" #n ")" ::: "memory")
; #define PG8_BAR __builtin_amdgcn_s_barrier()
; template <class Epi, class Order>
; __device__ __forceinline__ void gemm_phase(LAS unsigned char* lds, const Gemm g, const Order& S, const Epi& E) {
;     ...
;         if (!has_next) break;
; #pragma unroll
;         for (int a = 0; a < 2; ++a)
; #pragma unroll
;             for (int b = 0; b < 2; ++b)
; #pragma unroll
;                 for (int m = 0; m < 4; ++m)
; #pragma unroll
;                     for (int n = 0; n < 2; ++n) acc[a][b][m][n] = (f32x4){0.f, 0.f, 0.f, 0.f};
;         cur = nxt; cA = nA; cB = nB; ++ui;
;     }
;     PG8_WAIT_V(0);
;     if (wr == 0) PG8_BAR;
;     PG8_BAR;
;     __device__ __forceinline__ void operator()(const f32x4 (&acc)[2][2][4][2], const pg8::Unit& u, int wr, int wc, int fr, int fq) const {
;         const int row0 = u.pm * 256 + wr * 64 + fr, col0 = u.pn * 256 + wc * 32 + 8 * fq;
; #pragma unroll
;         for (int ai = 0; ai < 2; ++ai)
; #pragma unroll
;             for (int m = 0; m < 4; ++m) {
;                 f16_t* rowp = O + (size_t)(row0 + ai * 128 + m * 16) * ldc + col0;
; #pragma unroll
;                 for (int bj = 0; bj < 2; ++bj) { const f32x4 v0 = acc[ai][bj][m][0], v1 = acc[ai][bj][m][1];
;                     u32x4 w; w.x = pk_f16(v0[0], v0[1]); w.y = pk_f16(v0[2], v0[3]); w.z = pk_f16(v1[0], v1[1]); w.w = pk_f16(v1[2], v1[3]);
;                     *(u32x4*)(rowp + bj * 128) = w; }
	v_lshl_add_u32 v154, s6, 8, v142
	v_lshl_or_b32 v148, s4, 8, v144
	v_ashrrev_i32_e32 v149, 31, v148
	v_mov_b64_e32 v[150:151], s[2:3]
	v_cvt_pk_f16_f32 v68, v68, v69
	v_cvt_pk_f16_f32 v69, v70, v71
	v_cvt_pk_f16_f32 v70, v64, v65
	v_add_u32_e32 v64, 0x80, v154
	v_mad_i64_i32 v[152:153], s[24:25], v154, s72, v[150:151]
	v_lshlrev_b64 v[148:149], 1, v[148:149]
	v_cvt_pk_f16_f32 v108, v108, v109
	v_cvt_pk_f16_f32 v109, v110, v111
	v_cvt_pk_f16_f32 v110, v104, v105
	v_or_b32_e32 v104, 16, v154
	v_mad_i64_i32 v[64:65], s[24:25], v64, s72, v[150:151]
	v_cvt_pk_f16_f32 v44, v44, v45
	v_cvt_pk_f16_f32 v45, v46, v47
	v_cvt_pk_f16_f32 v46, v40, v41
	v_add_u32_e32 v40, 0x90, v154
	v_lshl_add_u64 v[152:153], v[152:153], 0, v[148:149]
	v_cvt_pk_f16_f32 v111, v106, v107
	v_mad_i64_i32 v[104:105], s[24:25], v104, s72, v[150:151]
	v_cvt_pk_f16_f32 v92, v92, v93
	v_cvt_pk_f16_f32 v93, v94, v95
	v_cvt_pk_f16_f32 v94, v88, v89
	v_or_b32_e32 v88, 32, v154
	v_lshl_add_u64 v[64:65], v[64:65], 0, v[148:149]
	v_cvt_pk_f16_f32 v47, v42, v43
	v_mad_i64_i32 v[40:41], s[24:25], v40, s72, v[150:151]
	v_cvt_pk_f16_f32 v28, v28, v29
	v_cvt_pk_f16_f32 v29, v30, v31
	v_cvt_pk_f16_f32 v30, v24, v25
	v_add_u32_e32 v24, 0xa0, v154
	global_store_dwordx4 v[152:153], v[108:111], off offset:256
	v_cvt_pk_f16_f32 v95, v90, v91
	v_mad_i64_i32 v[88:89], s[24:25], v88, s72, v[150:151]
	v_lshl_add_u64 v[108:109], v[104:105], 0, v[148:149]
	v_cvt_pk_f16_f32 v76, v76, v77
	v_cvt_pk_f16_f32 v77, v78, v79
	v_cvt_pk_f16_f32 v78, v72, v73
	v_or_b32_e32 v72, 48, v154
	global_store_dwordx4 v[64:65], v[44:47], off offset:256
	v_cvt_pk_f16_f32 v31, v26, v27
	v_mad_i64_i32 v[24:25], s[24:25], v24, s72, v[150:151]
	v_lshl_add_u64 v[44:45], v[40:41], 0, v[148:149]
	v_cvt_pk_f16_f32 v12, v12, v13
	v_cvt_pk_f16_f32 v13, v14, v15
	v_cvt_pk_f16_f32 v14, v8, v9
	v_add_u32_e32 v8, 0xb0, v154
	global_store_dwordx4 v[108:109], v[92:95], off offset:256
	v_cvt_pk_f16_f32 v79, v74, v75
	v_mad_i64_i32 v[72:73], s[24:25], v72, s72, v[150:151]
	v_lshl_add_u64 v[92:93], v[88:89], 0, v[148:149]
	global_store_dwordx4 v[44:45], v[28:31], off offset:256
	v_cvt_pk_f16_f32 v15, v10, v11
	v_mad_i64_i32 v[8:9], s[24:25], v8, s72, v[150:151]
	v_lshl_add_u64 v[28:29], v[24:25], 0, v[148:149]
	v_cvt_pk_f16_f32 v124, v124, v125
	v_cvt_pk_f16_f32 v125, v126, v127
	v_cvt_pk_f16_f32 v126, v120, v121
	v_cvt_pk_f16_f32 v127, v122, v123
	v_cvt_pk_f16_f32 v104, v116, v117
	v_cvt_pk_f16_f32 v105, v118, v119
	v_cvt_pk_f16_f32 v106, v112, v113
	v_cvt_pk_f16_f32 v107, v114, v115
	v_cvt_pk_f16_f32 v88, v100, v101
	v_cvt_pk_f16_f32 v89, v102, v103
	v_cvt_pk_f16_f32 v90, v96, v97
	v_cvt_pk_f16_f32 v91, v98, v99
	global_store_dwordx4 v[92:93], v[76:79], off offset:256
	v_cvt_pk_f16_f32 v74, v80, v81
	v_cvt_pk_f16_f32 v75, v82, v83
	v_lshl_add_u64 v[76:77], v[72:73], 0, v[148:149]
	v_cvt_pk_f16_f32 v72, v84, v85
	v_cvt_pk_f16_f32 v73, v86, v87
	v_cvt_pk_f16_f32 v71, v66, v67
	v_cvt_pk_f16_f32 v60, v60, v61
	v_cvt_pk_f16_f32 v61, v62, v63
	v_cvt_pk_f16_f32 v62, v56, v57
	v_cvt_pk_f16_f32 v63, v58, v59
	v_cvt_pk_f16_f32 v40, v52, v53
	v_cvt_pk_f16_f32 v41, v54, v55
	v_cvt_pk_f16_f32 v42, v48, v49
	v_cvt_pk_f16_f32 v43, v50, v51
	v_cvt_pk_f16_f32 v24, v36, v37
	v_cvt_pk_f16_f32 v25, v38, v39
	v_cvt_pk_f16_f32 v26, v32, v33
	v_cvt_pk_f16_f32 v27, v34, v35
	global_store_dwordx4 v[28:29], v[12:15], off offset:256
	v_cvt_pk_f16_f32 v10, v16, v17
	v_cvt_pk_f16_f32 v11, v18, v19
	v_lshl_add_u64 v[12:13], v[8:9], 0, v[148:149]
	v_cvt_pk_f16_f32 v8, v20, v21
	v_cvt_pk_f16_f32 v9, v22, v23
	v_cvt_pk_f16_f32 v4, v4, v5
	v_cvt_pk_f16_f32 v5, v6, v7
	v_cvt_pk_f16_f32 v6, v0, v1
	v_cvt_pk_f16_f32 v7, v2, v3
	s_and_b64 vcc, exec, s[22:23]
	s_mov_b32 s4, s10
	s_mov_b32 s6, s16
	s_mov_b64 s[44:45], s[36:37]
	s_mov_b64 s[42:43], s[20:21]
	global_store_dwordx4 v[152:153], v[124:127], off
	global_store_dwordx4 v[108:109], v[104:107], off
	global_store_dwordx4 v[92:93], v[88:91], off
	global_store_dwordx4 v[76:77], v[72:75], off
	global_store_dwordx4 v[76:77], v[68:71], off offset:256
	global_store_dwordx4 v[64:65], v[60:63], off
	global_store_dwordx4 v[44:45], v[40:43], off
	global_store_dwordx4 v[28:29], v[24:27], off
	global_store_dwordx4 v[12:13], v[8:11], off
	global_store_dwordx4 v[12:13], v[4:7], off offset:256
	s_cbranch_vccz .LBB0_448
	s_waitcnt vmcnt(0)
	v_readlane_b32 s94, v254, 22
	s_cmpk_gt_u32 s31, 0xff
	v_readlane_b32 s95, v254, 23
	s_cbranch_scc1 .LBB0_458
	s_barrier

; #define PG8_STAGE(bufoff, gbase, voff) do { _Pragma("unroll") for (int _i = 0; _i < 2; ++_i) \
;         __builtin_amdgcn_global_load_lds((const unsigned*)((const char*)(gbase) + (voff)[_i]), (LAS unsigned*)(lds + (bufoff) + ldsw + _i * 8192), 16, 0, 0); } while (0)
; #define PG8_WAIT_V(n) asm volatile("s_waitcnt vmcnt(" #n ")" ::: "memory")
; #define PG8_BAR __builtin_amdgcn_s_barrier()
; template <class Epi, class Order>
; __device__ __forceinline__ void gemm_phase(LAS unsigned char* lds, const Gemm g, const Order& S, const Epi& E) {
;     const int tid = threadIdx.x, wid = __builtin_amdgcn_readfirstlane(tid >> 6), lane = tid & 63, wr = wid >> 2, wc = wid & 3, fr = lane & 15, fq = lane >> 4;
;     int K = g.K; if (Order::OPAQUE_K) asm volatile("" : "+s"(K));
;     const int nt = K / BK;
;     unsigned voffA[2], voffB[2];
; #pragma unroll
;     for (int i = 0; i < 2; ++i) { int R, C; stage_rc(tid * 16 + i * 8192, R, C); const int Rb = Epi::PERM ? ((R & ~31) + perm32(R & 31)) : R;
;         voffA[i] = (unsigned)(R * g.ld + C) * 2u; voffB[i] = (unsigned)(Rb * g.ld + C) * 2u; }
;     const size_t kstep = (size_t)(BK * 2);
;     const size_t hstep = (size_t)HALF * g.ld * 2;
;     const size_t sstep = (size_t)K * 2;
;     const size_t tstep = 2 * hstep;
;     const unsigned ldsw = (unsigned)wid * 1024u;
;     const int aoff = lds_byte(wr * 64 + fr, fq * 8), boff = lds_byte(wc * 32 + fr, fq * 8);
;     ...
;     PG8_STAGE(PG8_SB(1, 0), cB + kstep, voffB); PG8_STAGE(PG8_SA(1, 0), cA + kstep, voffA); PG8_STAGE(PG8_SB(1, 1), cB + hstep + kstep, voffB);
;     PG8_WAIT_V(6); PG8_BAR;
.LBB0_693:
	s_add_u32 s60, s88, 0xfe00000
	s_addc_u32 s61, s89, 0
	s_add_u32 s62, s88, 0x680000
	s_addc_u32 s63, s89, 0
	s_lshr_b32 s1, s1, 26
	s_lshl_b32 s4, s4, 5
	s_mov_b64 s[10:11], 0x80
	s_add_i32 s1, s0, s1
	s_and_b32 s14, s4, 0x60
	s_add_i32 m0, s21, 0x18000
	v_lshl_add_u64 v[6:7], v[6:7], 0, s[10:11]
	s_ashr_i32 s66, s28, 31
	s_ashr_i32 s67, s1, 6
	s_lshl_b32 s1, s3, 13
	s_lshl_b32 s12, s14, 7
	s_waitcnt vmcnt(4)
	s_barrier
	global_load_lds_dwordx4 v[6:7], off
	v_lshl_add_u64 v[4:5], v[4:5], 0, s[10:11]
	s_add_i32 m0, s21, 0x1a000
	s_add_i32 s68, s21, 0x8000
	s_add_i32 s69, s21, 0xa000
	global_load_lds_dwordx4 v[4:5], off
	v_lshl_add_u64 v[2:3], v[2:3], 0, s[10:11]
	s_mov_b32 m0, s68
	s_add_u32 s4, s22, 0x10080
	global_load_lds_dwordx4 v[2:3], off
	v_lshl_add_u64 v[0:1], v[0:1], 0, s[10:11]
	s_mov_b32 m0, s69
	s_addc_u32 s5, s23, 0
	global_load_lds_dwordx4 v[0:1], off
	s_add_i32 m0, s21, 0x1c000
	s_nop 0
	global_load_lds_dwordx4 v146, s[4:5]
	s_add_i32 m0, s21, 0x1e000
	s_sext_i32_i16 s33, s2
	global_load_lds_dwordx4 v150, s[4:5]
	v_and_b32_e32 v0, 15, v241
	v_lshlrev_b32_e32 v1, 1, v11
	v_lshlrev_b32_e32 v2, 6, v241
	s_movk_i32 s2, 0x3c0
	v_and_or_b32 v3, v2, s2, v1
	v_lshl_or_b32 v164, s3, 6, v0
	v_lshl_or_b32 v0, v0, 6, v1
	v_and_b32_e32 v1, 0xe000, v2
	v_lshlrev_b32_e32 v2, 9, v10
	v_or3_b32 v1, v8, v1, v2
	v_lshlrev_b32_e32 v4, 2, v241
	v_add_u32_e32 v154, v1, v9
	v_lshlrev_b32_e32 v1, 2, v12
	v_and_b32_e32 v4, 32, v4
	s_waitcnt vmcnt(6)
	s_cmp_gt_i32 s0, 63
	v_and_b32_e32 v1, 0x1e000, v1
	v_bitop3_b32 v0, v0, s1, v4 bitop3:0xde
	v_bitop3_b32 v165, s12, v3, v4 bitop3:0xf6
	s_cselect_b64 s[12:13], -1, 0
	v_or3_b32 v1, v8, v1, v2
	s_add_i32 s73, 0, 0x10000
	s_add_i32 s84, 0, 0x14000
	s_mov_b32 s70, s28
	s_mov_b32 s71, 0x8000
	s_add_i32 s72, s67, -2
	v_or_b32_e32 v166, s14, v11
	v_mov_b32_e32 v155, v153
	v_add_u32_e32 v156, v1, v9
	v_mov_b32_e32 v157, v153
	v_mov_b64_e32 v[158:159], 0xaa0
	v_mov_b64_e32 v[160:161], 0xa9f
	v_add_u32_e32 v167, s73, v165
	v_add_u32_e32 v168, 0, v0
	v_add_u32_e32 v169, s84, v165
	s_mov_b32 s85, 0x40000
	s_mov_b32 s94, 0x48000
	s_mov_b32 s95, 0x50000
	s_mov_b32 s96, 0x58000
	v_mov_b32_e32 v170, 0x3f1b4598
	s_barrier
	s_branch .LBB0_695

; #define PG8_STAGE(bufoff, gbase, voff) do { _Pragma("unroll") for (int _i = 0; _i < 2; ++_i) \
;         __builtin_amdgcn_global_load_lds((const unsigned*)((const char*)(gbase) + (voff)[_i]), (LAS unsigned*)(lds + (bufoff) + ldsw + _i * 8192), 16, 0, 0); } while (0)
; #define PG8_LDA(dst, b, h) do { _Pragma("unroll") for (int m = 0; m < 4; ++m) _Pragma("unroll") for (int k = 0; k < 2; ++k) dst[m][k] = *(const LAS bf16x8*)(lds + PG8_SA(b, h) + aoff + m * 2048 + k * 1024); } while (0)
; #define PG8_LDB(dst, b, h) do { _Pragma("unroll") for (int n = 0; n < 2; ++n) _Pragma("unroll") for (int k = 0; k < 2; ++k) dst[n][k] = *(const LAS bf16x8*)(lds + PG8_SB(b, h) + boff + n * 2048 + k * 1024); } while (0)
; #define PG8_MMA(ai, bj, At, Bt) do { __builtin_amdgcn_s_setprio(1); _Pragma("unroll") for (int m = 0; m < 4; ++m) _Pragma("unroll") for (int n = 0; n < 2; ++n) _Pragma("unroll") for (int k = 0; k < 2; ++k) \
;         acc[ai][bj][m][n] = __builtin_amdgcn_mfma_f32_16x16x32_bf16(Bt[n][k], At[m][k], acc[ai][bj][m][n], 0, 0, 0); __builtin_amdgcn_s_setprio(0); } while (0)
; #define PG8_WAIT_L(n) asm volatile("s_waitcnt lgkmcnt(" #n ")" ::: "memory")
; #define PG8_BAR __builtin_amdgcn_s_barrier()
; #define PG8_SCHED __builtin_amdgcn_sched_barrier(0)
; template <class Epi, class Order>
; __device__ __forceinline__ void gemm_phase(LAS unsigned char* lds, const Gemm g, const Order& S, const Epi& E) {
;     ...
;             PG8_LDB(B0, 0, 0); PG8_SCHED; PG8_LDA(At, 0, 0); PG8_STAGE(PG8_SA(1, 1), a1 + hstep, voffA);
;             PG8_WAIT_L(8); PG8_BAR; PG8_WAIT_L(0); PG8_MMA(0, 0, At, B0); PG8_BAR; PG8_SCHED;
;             PG8_LDB(B1, 0, 1); PG8_STAGE(PG8_SB(0, 0), b2, voffB);
;             PG8_BAR; PG8_WAIT_L(0); PG8_MMA(0, 1, At, B1); PG8_BAR;
;             PG8_LDA(At, 0, 1); PG8_STAGE(PG8_SA(0, 0), a2, voffA);
;             PG8_BAR; PG8_WAIT_L(0); PG8_MMA(1, 0, At, B0); PG8_BAR; PG8_SCHED;
.LBB0_703:
	ds_read_b128 v[96:99], v167
	ds_read_b128 v[132:135], v167 offset:1024
	ds_read_b128 v[136:139], v167 offset:2048
	ds_read_b128 v[140:143], v167 offset:3072
	s_add_i32 s24, s22, 2
	s_add_u32 s23, s0, 0xffff0080
	s_addc_u32 s25, s1, -1
	s_cmp_eq_u32 s72, s22
	s_cselect_b32 s22, s4, s15
	s_cselect_b32 s37, s19, s25
	s_cselect_b32 s36, s18, s23
	s_cselect_b32 s23, s5, s17
	v_lshl_add_u64 v[162:163], s[0:1], 0, v[154:155]
	s_add_i32 m0, s21, 0xc000
	ds_read_b128 v[172:175], v168
	ds_read_b128 v[176:179], v168 offset:1024
	ds_read_b128 v[182:185], v168 offset:2048
	ds_read_b128 v[186:189], v168 offset:3072
	ds_read_b128 v[190:193], v168 offset:4096
	ds_read_b128 v[194:197], v168 offset:5120
	ds_read_b128 v[198:201], v168 offset:6144
	ds_read_b128 v[202:205], v168 offset:7168
	global_load_lds_dwordx4 v[162:163], off
	v_lshl_add_u64 v[162:163], s[0:1], 0, v[156:157]
	s_add_i32 m0, s21, 0xe000
	s_nop 0
	global_load_lds_dwordx4 v[162:163], off
	s_waitcnt lgkmcnt(8)
	s_barrier
	s_waitcnt lgkmcnt(0)
	s_setprio 1
	s_waitcnt lgkmcnt(0)
	v_mfma_f32_16x16x32_bf16 v[128:131], v[96:99], v[172:175], v[128:131]
	v_mfma_f32_16x16x32_bf16 v[92:95], v[136:139], v[172:175], v[92:95]
	v_mfma_f32_16x16x32_bf16 v[124:127], v[96:99], v[182:185], v[124:127]
	v_mfma_f32_16x16x32_bf16 v[88:91], v[136:139], v[182:185], v[88:91]
	v_mfma_f32_16x16x32_bf16 v[120:123], v[96:99], v[190:193], v[120:123]
	v_mfma_f32_16x16x32_bf16 v[84:87], v[136:139], v[190:193], v[84:87]
	v_mfma_f32_16x16x32_bf16 v[116:119], v[96:99], v[198:201], v[116:119]
	v_mfma_f32_16x16x32_bf16 v[80:83], v[136:139], v[198:201], v[80:83]
	v_mfma_f32_16x16x32_bf16 v[128:131], v[132:135], v[176:179], v[128:131]
	v_mfma_f32_16x16x32_bf16 v[92:95], v[140:143], v[176:179], v[92:95]
	v_mfma_f32_16x16x32_bf16 v[124:127], v[132:135], v[186:189], v[124:127]
	v_mfma_f32_16x16x32_bf16 v[88:91], v[140:143], v[186:189], v[88:91]
	v_mfma_f32_16x16x32_bf16 v[120:123], v[132:135], v[194:197], v[120:123]
	v_mfma_f32_16x16x32_bf16 v[84:87], v[140:143], v[194:197], v[84:87]
	v_mfma_f32_16x16x32_bf16 v[116:119], v[132:135], v[202:205], v[116:119]
	v_mfma_f32_16x16x32_bf16 v[80:83], v[140:143], v[202:205], v[80:83]
	s_setprio 0
	s_barrier
	s_add_i32 s25, s73, s45
	v_lshl_add_u64 v[162:163], s[22:23], 0, v[146:147]
	s_mov_b32 m0, s25
	ds_read_b128 v[206:209], v169
	ds_read_b128 v[210:213], v169 offset:1024
	ds_read_b128 v[214:217], v169 offset:2048
	ds_read_b128 v[218:221], v169 offset:3072
	global_load_lds_dwordx4 v[162:163], off
	v_lshl_add_u64 v[222:223], s[22:23], 0, v[150:151]
	s_add_i32 m0, s25, 0x2000
	s_nop 0
	global_load_lds_dwordx4 v[222:223], off
	s_barrier
	s_waitcnt lgkmcnt(0)
	s_setprio 1
	s_waitcnt lgkmcnt(0)
	v_mfma_f32_16x16x32_bf16 v[60:63], v[206:209], v[172:175], v[60:63]
	v_mfma_f32_16x16x32_bf16 v[28:31], v[214:217], v[172:175], v[28:31]
	v_mfma_f32_16x16x32_bf16 v[56:59], v[206:209], v[182:185], v[56:59]
	v_mfma_f32_16x16x32_bf16 v[24:27], v[214:217], v[182:185], v[24:27]
	v_mfma_f32_16x16x32_bf16 v[52:55], v[206:209], v[190:193], v[52:55]
	v_mfma_f32_16x16x32_bf16 v[20:23], v[214:217], v[190:193], v[20:23]
	v_mfma_f32_16x16x32_bf16 v[48:51], v[206:209], v[198:201], v[48:51]
	v_mfma_f32_16x16x32_bf16 v[16:19], v[214:217], v[198:201], v[16:19]
	v_mfma_f32_16x16x32_bf16 v[60:63], v[210:213], v[176:179], v[60:63]
	v_mfma_f32_16x16x32_bf16 v[28:31], v[218:221], v[176:179], v[28:31]
	v_mfma_f32_16x16x32_bf16 v[56:59], v[210:213], v[186:189], v[56:59]
	v_mfma_f32_16x16x32_bf16 v[24:27], v[218:221], v[186:189], v[24:27]
	v_mfma_f32_16x16x32_bf16 v[52:55], v[210:213], v[194:197], v[52:55]
	v_mfma_f32_16x16x32_bf16 v[20:23], v[218:221], v[194:197], v[20:23]
	v_mfma_f32_16x16x32_bf16 v[48:51], v[210:213], v[202:205], v[48:51]
	v_mfma_f32_16x16x32_bf16 v[16:19], v[218:221], v[202:205], v[16:19]
	s_setprio 0
	s_mov_b32 m0, s21
	v_lshl_add_u64 v[224:225], s[36:37], 0, v[144:145]
	s_barrier
	ds_read_b128 v[172:175], v168 offset:16384
	ds_read_b128 v[176:179], v168 offset:17408
	ds_read_b128 v[182:185], v168 offset:18432
	ds_read_b128 v[186:189], v168 offset:19456
	ds_read_b128 v[190:193], v168 offset:20480
	ds_read_b128 v[194:197], v168 offset:21504
	ds_read_b128 v[198:201], v168 offset:22528
	ds_read_b128 v[202:205], v168 offset:23552
	global_load_lds_dwordx4 v[224:225], off
	v_lshl_add_u64 v[226:227], s[36:37], 0, v[148:149]
	s_mov_b32 m0, s52
	s_nop 0
	global_load_lds_dwordx4 v[226:227], off
	s_barrier
	s_waitcnt lgkmcnt(0)
	s_setprio 1
	s_waitcnt lgkmcnt(0)
	v_mfma_f32_16x16x32_bf16 v[112:115], v[96:99], v[172:175], v[112:115]
	v_mfma_f32_16x16x32_bf16 v[76:79], v[136:139], v[172:175], v[76:79]
	v_mfma_f32_16x16x32_bf16 v[108:111], v[96:99], v[182:185], v[108:111]
	v_mfma_f32_16x16x32_bf16 v[72:75], v[136:139], v[182:185], v[72:75]
	v_mfma_f32_16x16x32_bf16 v[104:107], v[96:99], v[190:193], v[104:107]
	v_mfma_f32_16x16x32_bf16 v[68:71], v[136:139], v[190:193], v[68:71]
	v_mfma_f32_16x16x32_bf16 v[64:67], v[136:139], v[198:201], v[64:67]
	v_mfma_f32_16x16x32_bf16 v[112:115], v[132:135], v[176:179], v[112:115]
	v_mfma_f32_16x16x32_bf16 v[76:79], v[140:143], v[176:179], v[76:79]
	v_mfma_f32_16x16x32_bf16 v[108:111], v[132:135], v[186:189], v[108:111]
	v_mfma_f32_16x16x32_bf16 v[72:75], v[140:143], v[186:189], v[72:75]
	v_mfma_f32_16x16x32_bf16 v[104:107], v[132:135], v[194:197], v[104:107]
	v_mfma_f32_16x16x32_bf16 v[68:71], v[140:143], v[194:197], v[68:71]
	v_mfma_f32_16x16x32_bf16 v[96:99], v[96:99], v[198:201], v[100:103]
	v_mfma_f32_16x16x32_bf16 v[64:67], v[140:143], v[202:205], v[64:67]
	v_mfma_f32_16x16x32_bf16 v[96:99], v[132:135], v[202:205], v[96:99]
	s_setprio 0
	s_barrier
; #define PG8_STAGE(bufoff, gbase, voff) do { _Pragma("unroll") for (int _i = 0; _i < 2; ++_i) \
;         __builtin_amdgcn_global_load_lds((const unsigned*)((const char*)(gbase) + (voff)[_i]), (LAS unsigned*)(lds + (bufoff) + ldsw + _i * 8192), 16, 0, 0); } while (0)
; #define PG8_LDA(dst, b, h) do { _Pragma("unroll") for (int m = 0; m < 4; ++m) _Pragma("unroll") for (int k = 0; k < 2; ++k) dst[m][k] = *(const LAS bf16x8*)(lds + PG8_SA(b, h) + aoff + m * 2048 + k * 1024); } while (0)
; #define PG8_LDB(dst, b, h) do { _Pragma("unroll") for (int n = 0; n < 2; ++n) _Pragma("unroll") for (int k = 0; k < 2; ++k) dst[n][k] = *(const LAS bf16x8*)(lds + PG8_SB(b, h) + boff + n * 2048 + k * 1024); } while (0)
; #define PG8_MMA(ai, bj, At, Bt) do { __builtin_amdgcn_s_setprio(1); _Pragma("unroll") for (int m = 0; m < 4; ++m) _Pragma("unroll") for (int n = 0; n < 2; ++n) _Pragma("unroll") for (int k = 0; k < 2; ++k) \
;         acc[ai][bj][m][n] = __builtin_amdgcn_mfma_f32_16x16x32_bf16(Bt[n][k], At[m][k], acc[ai][bj][m][n], 0, 0, 0); __builtin_amdgcn_s_setprio(0); } while (0)
; #define PG8_WAIT_V(n) asm volatile("s_waitcnt vmcnt(" #n ")" ::: "memory")
; #define PG8_WAIT_L(n) asm volatile("s_waitcnt lgkmcnt(" #n ")" ::: "memory")
; #define PG8_BAR __builtin_amdgcn_s_barrier()
; #define PG8_SCHED __builtin_amdgcn_sched_barrier(0)
; template <class Epi, class Order>
; __device__ __forceinline__ void gemm_phase(LAS unsigned char* lds, const Gemm g, const Order& S, const Epi& E) {
;     ...
;             PG8_STAGE(PG8_SB(0, 1), b2 + hstep, voffB);
;             PG8_WAIT_V(6); PG8_BAR; PG8_MMA(1, 1, At, B1); PG8_BAR;
;             PG8_LDB(B0, 1, 0); PG8_SCHED; PG8_LDA(At, 1, 0); PG8_STAGE(PG8_SA(0, 1), a2 + hstep, voffA);
;             PG8_WAIT_L(8); PG8_BAR; PG8_WAIT_L(0); PG8_MMA(0, 0, At, B0); PG8_BAR; PG8_SCHED;
;             PG8_LDB(B1, 1, 1); PG8_STAGE(PG8_SB(1, 0), b3, voffB);
;             PG8_BAR; PG8_WAIT_L(0); PG8_MMA(0, 1, At, B1); PG8_BAR;
;             PG8_LDA(At, 1, 1); PG8_STAGE(PG8_SA(1, 0), a3, voffA);
	s_add_u32 s74, s22, 0x10000
	s_addc_u32 s75, s23, 0
	s_add_i32 s25, s84, s45
	s_mov_b32 m0, s25
	s_nop 0
	global_load_lds_dwordx4 v146, s[74:75]
	s_add_i32 m0, s25, 0x2000
	s_nop 0
	global_load_lds_dwordx4 v150, s[74:75]
	s_waitcnt vmcnt(6)
	s_barrier
	s_setprio 1
	v_mfma_f32_16x16x32_bf16 v[44:47], v[206:209], v[172:175], v[44:47]
	v_mfma_f32_16x16x32_bf16 v[12:15], v[214:217], v[172:175], v[12:15]
	v_mfma_f32_16x16x32_bf16 v[40:43], v[206:209], v[182:185], v[40:43]
	v_mfma_f32_16x16x32_bf16 v[8:11], v[214:217], v[182:185], v[8:11]
	v_mfma_f32_16x16x32_bf16 v[36:39], v[206:209], v[190:193], v[36:39]
	v_mfma_f32_16x16x32_bf16 v[4:7], v[214:217], v[190:193], v[4:7]
	v_mfma_f32_16x16x32_bf16 v[32:35], v[206:209], v[198:201], v[32:35]
	v_mfma_f32_16x16x32_bf16 v[0:3], v[214:217], v[198:201], v[0:3]
	v_mfma_f32_16x16x32_bf16 v[44:47], v[210:213], v[176:179], v[44:47]
	v_mfma_f32_16x16x32_bf16 v[12:15], v[218:221], v[176:179], v[12:15]
	v_mfma_f32_16x16x32_bf16 v[40:43], v[210:213], v[186:189], v[40:43]
	v_mfma_f32_16x16x32_bf16 v[8:11], v[218:221], v[186:189], v[8:11]
	v_mfma_f32_16x16x32_bf16 v[36:39], v[210:213], v[194:197], v[36:39]
	v_mfma_f32_16x16x32_bf16 v[4:7], v[218:221], v[194:197], v[4:7]
	v_mfma_f32_16x16x32_bf16 v[32:35], v[210:213], v[202:205], v[32:35]
	v_mfma_f32_16x16x32_bf16 v[0:3], v[218:221], v[202:205], v[0:3]
	s_setprio 0
	s_add_i32 s25, 0, 0x18000
	v_add_u32_e32 v140, s25, v165
	s_barrier
	ds_read_b128 v[100:103], v140
	ds_read_b128 v[132:135], v140 offset:1024
	ds_read_b128 v[136:139], v140 offset:2048
	ds_read_b128 v[140:143], v140 offset:3072
	s_add_u32 s36, s36, 0x10000
	s_addc_u32 s37, s37, 0
	s_mov_b32 m0, s53
	ds_read_b128 v[172:175], v168 offset:32768
	ds_read_b128 v[176:179], v168 offset:33792
	ds_read_b128 v[182:185], v168 offset:34816
	ds_read_b128 v[186:189], v168 offset:35840
	ds_read_b128 v[190:193], v168 offset:36864
	ds_read_b128 v[194:197], v168 offset:37888
	ds_read_b128 v[198:201], v168 offset:38912
	ds_read_b128 v[202:205], v168 offset:39936
	global_load_lds_dwordx4 v144, s[36:37]
	s_mov_b32 m0, s54
	s_nop 0
	global_load_lds_dwordx4 v148, s[36:37]
	s_waitcnt lgkmcnt(8)
	s_barrier
	s_waitcnt lgkmcnt(0)
	s_setprio 1
	s_waitcnt lgkmcnt(0)
	v_mfma_f32_16x16x32_bf16 v[128:131], v[100:103], v[172:175], v[128:131]
	v_mfma_f32_16x16x32_bf16 v[92:95], v[136:139], v[172:175], v[92:95]
	v_mfma_f32_16x16x32_bf16 v[124:127], v[100:103], v[182:185], v[124:127]
	v_mfma_f32_16x16x32_bf16 v[88:91], v[136:139], v[182:185], v[88:91]
	v_mfma_f32_16x16x32_bf16 v[120:123], v[100:103], v[190:193], v[120:123]
	v_mfma_f32_16x16x32_bf16 v[84:87], v[136:139], v[190:193], v[84:87]
	v_mfma_f32_16x16x32_bf16 v[116:119], v[100:103], v[198:201], v[116:119]
	v_mfma_f32_16x16x32_bf16 v[80:83], v[136:139], v[198:201], v[80:83]
	v_mfma_f32_16x16x32_bf16 v[128:131], v[132:135], v[176:179], v[128:131]
	v_mfma_f32_16x16x32_bf16 v[92:95], v[140:143], v[176:179], v[92:95]
	v_mfma_f32_16x16x32_bf16 v[124:127], v[132:135], v[186:189], v[124:127]
	v_mfma_f32_16x16x32_bf16 v[88:91], v[140:143], v[186:189], v[88:91]
	v_mfma_f32_16x16x32_bf16 v[120:123], v[132:135], v[194:197], v[120:123]
	v_mfma_f32_16x16x32_bf16 v[84:87], v[140:143], v[194:197], v[84:87]
	v_mfma_f32_16x16x32_bf16 v[116:119], v[132:135], v[202:205], v[116:119]
	v_mfma_f32_16x16x32_bf16 v[80:83], v[140:143], v[202:205], v[80:83]
	s_setprio 0
	s_barrier
	s_add_i32 s27, 0, 0x1c000
	s_add_i32 s25, s25, s45
	v_add_u32_e32 v152, s27, v165
	v_lshl_add_u64 v[162:163], v[162:163], 0, s[10:11]
	s_mov_b32 m0, s25
	ds_read_b128 v[206:209], v152
	ds_read_b128 v[210:213], v152 offset:1024
	ds_read_b128 v[214:217], v152 offset:2048
	ds_read_b128 v[218:221], v152 offset:3072
	global_load_lds_dwordx4 v[162:163], off
	v_lshl_add_u64 v[162:163], v[222:223], 0, s[10:11]
	s_add_i32 m0, s25, 0x2000
	s_nop 0
	global_load_lds_dwordx4 v[162:163], off
	s_barrier
; #define PG8_STAGE(bufoff, gbase, voff) do { _Pragma("unroll") for (int _i = 0; _i < 2; ++_i) \
;         __builtin_amdgcn_global_load_lds((const unsigned*)((const char*)(gbase) + (voff)[_i]), (LAS unsigned*)(lds + (bufoff) + ldsw + _i * 8192), 16, 0, 0); } while (0)
; #define PG8_MMA(ai, bj, At, Bt) do { __builtin_amdgcn_s_setprio(1); _Pragma("unroll") for (int m = 0; m < 4; ++m) _Pragma("unroll") for (int n = 0; n < 2; ++n) _Pragma("unroll") for (int k = 0; k < 2; ++k) \
;         acc[ai][bj][m][n] = __builtin_amdgcn_mfma_f32_16x16x32_bf16(Bt[n][k], At[m][k], acc[ai][bj][m][n], 0, 0, 0); __builtin_amdgcn_s_setprio(0); } while (0)
; #define PG8_WAIT_V(n) asm volatile("s_waitcnt vmcnt(" #n ")" ::: "memory")
; #define PG8_WAIT_L(n) asm volatile("s_waitcnt lgkmcnt(" #n ")" ::: "memory")
; #define PG8_BAR __builtin_amdgcn_s_barrier()
; #define PG8_SCHED __builtin_amdgcn_sched_barrier(0)
; template <class Epi, class Order>
; __device__ __forceinline__ void gemm_phase(LAS unsigned char* lds, const Gemm g, const Order& S, const Epi& E) {
;     ...
;             PG8_BAR; PG8_WAIT_L(0); PG8_MMA(1, 0, At, B0); PG8_BAR; PG8_SCHED;
;             PG8_STAGE(PG8_SB(1, 1), b3 + hstep, voffB);
;             PG8_WAIT_V(6); PG8_BAR; PG8_MMA(1, 1, At, B1); PG8_BAR;
	s_waitcnt lgkmcnt(0)
	s_setprio 1
	s_waitcnt lgkmcnt(0)
	v_mfma_f32_16x16x32_bf16 v[60:63], v[206:209], v[172:175], v[60:63]
	v_mfma_f32_16x16x32_bf16 v[28:31], v[214:217], v[172:175], v[28:31]
	v_mfma_f32_16x16x32_bf16 v[56:59], v[206:209], v[182:185], v[56:59]
	v_mfma_f32_16x16x32_bf16 v[24:27], v[214:217], v[182:185], v[24:27]
	v_mfma_f32_16x16x32_bf16 v[52:55], v[206:209], v[190:193], v[52:55]
	v_mfma_f32_16x16x32_bf16 v[20:23], v[214:217], v[190:193], v[20:23]
	v_mfma_f32_16x16x32_bf16 v[48:51], v[206:209], v[198:201], v[48:51]
	v_mfma_f32_16x16x32_bf16 v[16:19], v[214:217], v[198:201], v[16:19]
	v_mfma_f32_16x16x32_bf16 v[60:63], v[210:213], v[176:179], v[60:63]
	v_mfma_f32_16x16x32_bf16 v[28:31], v[218:221], v[176:179], v[28:31]
	v_mfma_f32_16x16x32_bf16 v[56:59], v[210:213], v[186:189], v[56:59]
	v_mfma_f32_16x16x32_bf16 v[24:27], v[218:221], v[186:189], v[24:27]
	v_mfma_f32_16x16x32_bf16 v[52:55], v[210:213], v[194:197], v[52:55]
	v_mfma_f32_16x16x32_bf16 v[20:23], v[218:221], v[194:197], v[20:23]
	v_mfma_f32_16x16x32_bf16 v[48:51], v[210:213], v[202:205], v[48:51]
	v_mfma_f32_16x16x32_bf16 v[16:19], v[218:221], v[202:205], v[16:19]
	s_setprio 0
	s_mov_b32 m0, s68
	v_lshl_add_u64 v[162:163], v[224:225], 0, s[10:11]
	s_barrier
	ds_read_b128 v[172:175], v168 offset:49152
	ds_read_b128 v[176:179], v168 offset:50176
	ds_read_b128 v[182:185], v168 offset:51200
	ds_read_b128 v[186:189], v168 offset:52224
	ds_read_b128 v[190:193], v168 offset:53248
	ds_read_b128 v[194:197], v168 offset:54272
	ds_read_b128 v[198:201], v168 offset:55296
	ds_read_b128 v[202:205], v168 offset:56320
	global_load_lds_dwordx4 v[162:163], off
	v_lshl_add_u64 v[162:163], v[226:227], 0, s[10:11]
	s_mov_b32 m0, s69
	s_nop 0
	global_load_lds_dwordx4 v[162:163], off
	s_barrier
	s_waitcnt lgkmcnt(0)
	s_setprio 1
	s_waitcnt lgkmcnt(0)
	v_mfma_f32_16x16x32_bf16 v[112:115], v[100:103], v[172:175], v[112:115]
	v_mfma_f32_16x16x32_bf16 v[76:79], v[136:139], v[172:175], v[76:79]
	v_mfma_f32_16x16x32_bf16 v[108:111], v[100:103], v[182:185], v[108:111]
	v_mfma_f32_16x16x32_bf16 v[72:75], v[136:139], v[182:185], v[72:75]
	v_mfma_f32_16x16x32_bf16 v[104:107], v[100:103], v[190:193], v[104:107]
	v_mfma_f32_16x16x32_bf16 v[68:71], v[136:139], v[190:193], v[68:71]
	v_mfma_f32_16x16x32_bf16 v[96:99], v[100:103], v[198:201], v[96:99]
	v_mfma_f32_16x16x32_bf16 v[64:67], v[136:139], v[198:201], v[64:67]
	v_mfma_f32_16x16x32_bf16 v[112:115], v[132:135], v[176:179], v[112:115]
	v_mfma_f32_16x16x32_bf16 v[76:79], v[140:143], v[176:179], v[76:79]
	v_mfma_f32_16x16x32_bf16 v[108:111], v[132:135], v[186:189], v[108:111]
	v_mfma_f32_16x16x32_bf16 v[72:75], v[140:143], v[186:189], v[72:75]
	v_mfma_f32_16x16x32_bf16 v[104:107], v[132:135], v[194:197], v[104:107]
	v_mfma_f32_16x16x32_bf16 v[68:71], v[140:143], v[194:197], v[68:71]
	v_mfma_f32_16x16x32_bf16 v[100:103], v[132:135], v[202:205], v[96:99]
	v_mfma_f32_16x16x32_bf16 v[64:67], v[140:143], v[202:205], v[64:67]
	s_setprio 0
	s_barrier
	s_add_u32 s22, s22, 0x10080
	s_addc_u32 s23, s23, 0
	s_add_i32 s25, s27, s45
	s_mov_b32 m0, s25
	s_nop 0
	global_load_lds_dwordx4 v146, s[22:23]
	v_lshl_add_u64 v[96:97], s[22:23], 0, v[150:151]
	s_add_i32 m0, s25, 0x2000
	s_nop 0
	global_load_lds_dwordx4 v[96:97], off
	s_waitcnt vmcnt(6)
	s_barrier
	s_setprio 1
	v_mfma_f32_16x16x32_bf16 v[44:47], v[206:209], v[172:175], v[44:47]
	v_mfma_f32_16x16x32_bf16 v[12:15], v[214:217], v[172:175], v[12:15]
	v_mfma_f32_16x16x32_bf16 v[40:43], v[206:209], v[182:185], v[40:43]
	v_mfma_f32_16x16x32_bf16 v[8:11], v[214:217], v[182:185], v[8:11]
	v_mfma_f32_16x16x32_bf16 v[36:39], v[206:209], v[190:193], v[36:39]
	v_mfma_f32_16x16x32_bf16 v[4:7], v[214:217], v[190:193], v[4:7]
	v_mfma_f32_16x16x32_bf16 v[32:35], v[206:209], v[198:201], v[32:35]
	v_mfma_f32_16x16x32_bf16 v[0:3], v[214:217], v[198:201], v[0:3]
	v_mfma_f32_16x16x32_bf16 v[44:47], v[210:213], v[176:179], v[44:47]
	v_mfma_f32_16x16x32_bf16 v[12:15], v[218:221], v[176:179], v[12:15]
	v_mfma_f32_16x16x32_bf16 v[40:43], v[210:213], v[186:189], v[40:43]
	v_mfma_f32_16x16x32_bf16 v[8:11], v[218:221], v[186:189], v[8:11]
	v_mfma_f32_16x16x32_bf16 v[36:39], v[210:213], v[194:197], v[36:39]
	v_mfma_f32_16x16x32_bf16 v[4:7], v[218:221], v[194:197], v[4:7]
	v_mfma_f32_16x16x32_bf16 v[32:35], v[210:213], v[202:205], v[32:35]
	v_mfma_f32_16x16x32_bf16 v[0:3], v[218:221], v[202:205], v[0:3]
	s_setprio 0
	s_add_u32 s0, s0, 0x100
	s_addc_u32 s1, s1, 0
	s_add_u32 s15, s15, 0x100
	s_addc_u32 s17, s17, 0
	s_cmp_ge_i32 s24, s67
	s_mov_b32 s22, s24
	s_barrier
	s_cbranch_scc0 .LBB0_703
	s_branch .LBB0_694

; #define PG8_STAGE(bufoff, gbase, voff) do { _Pragma("unroll") for (int _i = 0; _i < 2; ++_i) \
;         __builtin_amdgcn_global_load_lds((const unsigned*)((const char*)(gbase) + (voff)[_i]), (LAS unsigned*)(lds + (bufoff) + ldsw + _i * 8192), 16, 0, 0); } while (0)
; #define PG8_WAIT_V(n) asm volatile("s_waitcnt vmcnt(" #n ")" ::: "memory")
; #define PG8_BAR __builtin_amdgcn_s_barrier()
; template <class Epi, class Order>
; __device__ __forceinline__ void gemm_phase(LAS unsigned char* lds, const Gemm g, const Order& S, const Epi& E) {
;     const int tid = threadIdx.x, wid = __builtin_amdgcn_readfirstlane(tid >> 6), lane = tid & 63, wr = wid >> 2, wc = wid & 3, fr = lane & 15, fq = lane >> 4;
;     int K = g.K; if (Order::OPAQUE_K) asm volatile("" : "+s"(K));
;     const int nt = K / BK;
;     unsigned voffA[2], voffB[2];
; #pragma unroll
;     for (int i = 0; i < 2; ++i) { int R, C; stage_rc(tid * 16 + i * 8192, R, C); const int Rb = Epi::PERM ? ((R & ~31) + perm32(R & 31)) : R;
;         voffA[i] = (unsigned)(R * g.ld + C) * 2u; voffB[i] = (unsigned)(Rb * g.ld + C) * 2u; }
;     const size_t kstep = (size_t)(BK * 2);
;     const size_t hstep = (size_t)HALF * g.ld * 2;
;     const size_t sstep = (size_t)K * 2;
;     const size_t tstep = 2 * hstep;
;     const unsigned ldsw = (unsigned)wid * 1024u;
;     const int aoff = lds_byte(wr * 64 + fr, fq * 8), boff = lds_byte(wc * 32 + fr, fq * 8);
;     ...
;     PG8_STAGE(PG8_SB(1, 0), cB + kstep, voffB); PG8_STAGE(PG8_SA(1, 0), cA + kstep, voffA); PG8_STAGE(PG8_SB(1, 1), cB + hstep + kstep, voffB);
;     PG8_WAIT_V(6); PG8_BAR;
.LBB0_993:
	s_lshl_b32 s4, s4, 5
	s_and_b32 s11, s4, 0x60
	s_ashr_i32 s67, s28, 31
	s_lshl_b32 s10, s3, 13
	s_lshl_b32 s12, s11, 7
	s_add_u32 s4, s88, 0x200000
	s_mov_b64 s[6:7], 0x80
	s_addc_u32 s5, s89, 0
	s_add_i32 m0, s60, 0x18000
	v_lshl_add_u64 v[6:7], v[6:7], 0, s[6:7]
	s_waitcnt vmcnt(4)
	s_barrier
	global_load_lds_dwordx4 v[6:7], off
	v_lshl_add_u64 v[4:5], v[4:5], 0, s[6:7]
	s_add_i32 m0, s60, 0x1a000
	s_add_i32 s68, s60, 0x8000
	s_add_i32 s69, s60, 0xa000
	global_load_lds_dwordx4 v[4:5], off
	v_lshl_add_u64 v[2:3], v[2:3], 0, s[6:7]
	s_mov_b32 m0, s68
	s_add_u32 s8, s46, 0x80080
	global_load_lds_dwordx4 v[2:3], off
	v_lshl_add_u64 v[0:1], v[0:1], 0, s[6:7]
	s_mov_b32 m0, s69
	s_addc_u32 s9, s47, 0
	global_load_lds_dwordx4 v[0:1], off
	s_add_i32 m0, s60, 0x1c000
	s_nop 0
	global_load_lds_dwordx4 v182, s[8:9]
	s_add_i32 m0, s60, 0x1e000
	s_sext_i32_i8 s33, s2
	global_load_lds_dwordx4 v184, s[8:9]
	v_bfe_u32 v0, v241, 4, 2
	v_and_b32_e32 v1, 15, v241
	v_lshlrev_b32_e32 v2, 4, v0
	v_lshlrev_b32_e32 v3, 6, v241
	s_movk_i32 s2, 0x3c0
	v_lshl_or_b32 v243, v0, 2, s11
	v_lshlrev_b32_e32 v0, 9, v241
	v_and_or_b32 v3, v3, s2, v2
	v_lshl_or_b32 v181, s3, 6, v1
	v_lshl_or_b32 v1, v1, 6, v2
	v_and_b32_e32 v0, 0x70000, v0
	v_lshlrev_b32_e32 v2, 12, v10
	v_or3_b32 v0, v8, v0, v2
	v_lshlrev_b32_e32 v4, 2, v241
	v_add_u32_e32 v186, v0, v9
	v_lshlrev_b32_e32 v0, 5, v11
	v_and_b32_e32 v4, 32, v4
	s_waitcnt vmcnt(6)
	v_and_b32_e32 v0, 0xf0000, v0
	v_bitop3_b32 v1, v1, s10, v4 bitop3:0xde
	v_bitop3_b32 v242, s12, v3, v4 bitop3:0xf6
	v_or3_b32 v0, v8, v0, v2
	s_add_i32 s71, 0, 0x10000
	s_add_i32 s72, 0, 0x14000
	s_mov_b32 s70, s28
	v_mov_b32_e32 v187, v183
	v_add_u32_e32 v188, v0, v9
	v_mov_b32_e32 v189, v183
	v_mov_b64_e32 v[190:191], 0x400
	v_mov_b64_e32 v[192:193], 0x3ff
	v_add_u32_e32 v244, s71, v242
	v_add_u32_e32 v245, 0, v1
	v_add_u32_e32 v246, s72, v242
	s_mov_b64 s[8:9], 0x100000
	s_mov_b32 s73, 0x100000
	s_mov_b64 s[10:11], 0x120000
	s_mov_b32 s74, 0x120000
	s_mov_b64 s[12:13], 0x140000
	s_mov_b32 s75, 0x140000
	s_mov_b64 s[14:15], 0x160000
	s_mov_b32 s76, 0x160000
	s_mov_b32 s16, 0x3f9837f0
	s_barrier
	s_branch .LBB0_995

; #define PG8_STAGE(bufoff, gbase, voff) do { _Pragma("unroll") for (int _i = 0; _i < 2; ++_i) \
;         __builtin_amdgcn_global_load_lds((const unsigned*)((const char*)(gbase) + (voff)[_i]), (LAS unsigned*)(lds + (bufoff) + ldsw + _i * 8192), 16, 0, 0); } while (0)
; #define PG8_LDA(dst, b, h) do { _Pragma("unroll") for (int m = 0; m < 4; ++m) _Pragma("unroll") for (int k = 0; k < 2; ++k) dst[m][k] = *(const LAS bf16x8*)(lds + PG8_SA(b, h) + aoff + m * 2048 + k * 1024); } while (0)
; #define PG8_LDB(dst, b, h) do { _Pragma("unroll") for (int n = 0; n < 2; ++n) _Pragma("unroll") for (int k = 0; k < 2; ++k) dst[n][k] = *(const LAS bf16x8*)(lds + PG8_SB(b, h) + boff + n * 2048 + k * 1024); } while (0)
; #define PG8_MMA(ai, bj, At, Bt) do { __builtin_amdgcn_s_setprio(1); _Pragma("unroll") for (int m = 0; m < 4; ++m) _Pragma("unroll") for (int n = 0; n < 2; ++n) _Pragma("unroll") for (int k = 0; k < 2; ++k) \
;         acc[ai][bj][m][n] = __builtin_amdgcn_mfma_f32_16x16x32_bf16(Bt[n][k], At[m][k], acc[ai][bj][m][n], 0, 0, 0); __builtin_amdgcn_s_setprio(0); } while (0)
; #define PG8_WAIT_L(n) asm volatile("s_waitcnt lgkmcnt(" #n ")" ::: "memory")
; #define PG8_BAR __builtin_amdgcn_s_barrier()
; #define PG8_SCHED __builtin_amdgcn_sched_barrier(0)
; template <class Epi, class Order>
; __device__ __forceinline__ void gemm_phase(LAS unsigned char* lds, const Gemm g, const Order& S, const Epi& E) {
;     ...
;             PG8_LDB(B0, 0, 0); PG8_SCHED; PG8_LDA(At, 0, 0); PG8_STAGE(PG8_SA(1, 1), a1 + hstep, voffA);
;             PG8_WAIT_L(8); PG8_BAR; PG8_WAIT_L(0); PG8_MMA(0, 0, At, B0); PG8_BAR; PG8_SCHED;
;             PG8_LDB(B1, 0, 1); PG8_STAGE(PG8_SB(0, 0), b2, voffB);
;             PG8_BAR; PG8_WAIT_L(0); PG8_MMA(0, 1, At, B1); PG8_BAR;
;             PG8_LDA(At, 0, 1); PG8_STAGE(PG8_SA(0, 0), a2, voffA);
;             PG8_BAR; PG8_WAIT_L(0); PG8_MMA(1, 0, At, B0); PG8_BAR; PG8_SCHED;
.LBB0_1002:
	ds_read_b128 v[128:131], v244
	ds_read_b128 v[132:135], v244 offset:1024
	ds_read_b128 v[136:139], v244 offset:2048
	ds_read_b128 v[140:143], v244 offset:3072
	s_add_u32 s24, s44, 0xfff80080
	s_addc_u32 s25, s45, -1
	s_cmp_eq_u32 s80, 28
	s_cselect_b32 s53, s21, s25
	s_cselect_b32 s52, s43, s24
	s_cselect_b32 s47, s19, s79
	s_cselect_b32 s46, s77, s78
	v_lshl_add_u64 v[176:177], s[44:45], 0, v[186:187]
	s_add_i32 m0, s60, 0xc000
	ds_read_b128 v[144:147], v245
	ds_read_b128 v[148:151], v245 offset:1024
	ds_read_b128 v[152:155], v245 offset:2048
	ds_read_b128 v[156:159], v245 offset:3072
	ds_read_b128 v[160:163], v245 offset:4096
	ds_read_b128 v[164:167], v245 offset:5120
	ds_read_b128 v[168:171], v245 offset:6144
	ds_read_b128 v[172:175], v245 offset:7168
	global_load_lds_dwordx4 v[176:177], off
	v_lshl_add_u64 v[176:177], s[44:45], 0, v[188:189]
	s_add_i32 m0, s60, 0xe000
	s_nop 0
	global_load_lds_dwordx4 v[176:177], off
	s_waitcnt lgkmcnt(8)
	s_barrier
	s_waitcnt lgkmcnt(0)
	s_setprio 1
	s_waitcnt lgkmcnt(0)
	v_mfma_f32_16x16x32_bf16 v[124:127], v[128:131], v[144:147], v[124:127]
	v_mfma_f32_16x16x32_bf16 v[104:107], v[136:139], v[144:147], v[104:107]
	v_mfma_f32_16x16x32_bf16 v[120:123], v[128:131], v[152:155], v[120:123]
	v_mfma_f32_16x16x32_bf16 v[96:99], v[136:139], v[152:155], v[96:99]
	v_mfma_f32_16x16x32_bf16 v[116:119], v[128:131], v[160:163], v[116:119]
	v_mfma_f32_16x16x32_bf16 v[88:91], v[136:139], v[160:163], v[88:91]
	v_mfma_f32_16x16x32_bf16 v[112:115], v[128:131], v[168:171], v[112:115]
	v_mfma_f32_16x16x32_bf16 v[80:83], v[136:139], v[168:171], v[80:83]
	v_mfma_f32_16x16x32_bf16 v[124:127], v[132:135], v[148:151], v[124:127]
	v_mfma_f32_16x16x32_bf16 v[104:107], v[140:143], v[148:151], v[104:107]
	v_mfma_f32_16x16x32_bf16 v[120:123], v[132:135], v[156:159], v[120:123]
	v_mfma_f32_16x16x32_bf16 v[96:99], v[140:143], v[156:159], v[96:99]
	v_mfma_f32_16x16x32_bf16 v[116:119], v[132:135], v[164:167], v[116:119]
	v_mfma_f32_16x16x32_bf16 v[88:91], v[140:143], v[164:167], v[88:91]
	v_mfma_f32_16x16x32_bf16 v[112:115], v[132:135], v[172:175], v[112:115]
	v_mfma_f32_16x16x32_bf16 v[80:83], v[140:143], v[172:175], v[80:83]
	s_setprio 0
	s_barrier
	s_add_i32 s24, s71, s54
	v_lshl_add_u64 v[206:207], s[46:47], 0, v[182:183]
	s_mov_b32 m0, s24
	ds_read_b128 v[176:179], v246
	ds_read_b128 v[194:197], v246 offset:1024
	ds_read_b128 v[198:201], v246 offset:2048
	ds_read_b128 v[202:205], v246 offset:3072
	global_load_lds_dwordx4 v[206:207], off
	v_lshl_add_u64 v[208:209], s[46:47], 0, v[184:185]
	s_add_i32 m0, s24, 0x2000
	s_nop 0
	global_load_lds_dwordx4 v[208:209], off
	s_barrier
	s_waitcnt lgkmcnt(0)
	s_setprio 1
	s_waitcnt lgkmcnt(0)
	v_mfma_f32_16x16x32_bf16 v[68:71], v[176:179], v[144:147], v[68:71]
	v_mfma_f32_16x16x32_bf16 v[40:43], v[198:201], v[144:147], v[40:43]
	v_mfma_f32_16x16x32_bf16 v[60:63], v[176:179], v[152:155], v[60:63]
	v_mfma_f32_16x16x32_bf16 v[32:35], v[198:201], v[152:155], v[32:35]
	v_mfma_f32_16x16x32_bf16 v[52:55], v[176:179], v[160:163], v[52:55]
	v_mfma_f32_16x16x32_bf16 v[20:23], v[198:201], v[160:163], v[20:23]
	v_mfma_f32_16x16x32_bf16 v[48:51], v[176:179], v[168:171], v[48:51]
	v_mfma_f32_16x16x32_bf16 v[16:19], v[198:201], v[168:171], v[16:19]
	v_mfma_f32_16x16x32_bf16 v[68:71], v[194:197], v[148:151], v[68:71]
	v_mfma_f32_16x16x32_bf16 v[40:43], v[202:205], v[148:151], v[40:43]
	v_mfma_f32_16x16x32_bf16 v[60:63], v[194:197], v[156:159], v[60:63]
	v_mfma_f32_16x16x32_bf16 v[32:35], v[202:205], v[156:159], v[32:35]
	v_mfma_f32_16x16x32_bf16 v[52:55], v[194:197], v[164:167], v[52:55]
	v_mfma_f32_16x16x32_bf16 v[20:23], v[202:205], v[164:167], v[20:23]
	v_mfma_f32_16x16x32_bf16 v[48:51], v[194:197], v[172:175], v[48:51]
	v_mfma_f32_16x16x32_bf16 v[16:19], v[202:205], v[172:175], v[16:19]
	s_setprio 0
	s_mov_b32 m0, s60
	v_lshl_add_u64 v[210:211], s[52:53], 0, v[182:183]
	s_barrier
	ds_read_b128 v[144:147], v245 offset:16384
	ds_read_b128 v[148:151], v245 offset:17408
	ds_read_b128 v[152:155], v245 offset:18432
	ds_read_b128 v[156:159], v245 offset:19456
	ds_read_b128 v[160:163], v245 offset:20480
	ds_read_b128 v[164:167], v245 offset:21504
	ds_read_b128 v[168:171], v245 offset:22528
	ds_read_b128 v[172:175], v245 offset:23552
	global_load_lds_dwordx4 v[210:211], off
	v_lshl_add_u64 v[212:213], s[52:53], 0, v[184:185]
	s_mov_b32 m0, s61
	s_nop 0
	global_load_lds_dwordx4 v[212:213], off
	s_barrier
	s_waitcnt lgkmcnt(0)
	s_setprio 1
	s_waitcnt lgkmcnt(0)
	v_mfma_f32_16x16x32_bf16 v[108:111], v[128:131], v[144:147], v[108:111]
	v_mfma_f32_16x16x32_bf16 v[76:79], v[136:139], v[144:147], v[76:79]
	v_mfma_f32_16x16x32_bf16 v[100:103], v[128:131], v[152:155], v[100:103]
	v_mfma_f32_16x16x32_bf16 v[72:75], v[136:139], v[152:155], v[72:75]
	v_mfma_f32_16x16x32_bf16 v[92:95], v[128:131], v[160:163], v[92:95]
	v_mfma_f32_16x16x32_bf16 v[64:67], v[136:139], v[160:163], v[64:67]
	v_mfma_f32_16x16x32_bf16 v[84:87], v[128:131], v[168:171], v[84:87]
	v_mfma_f32_16x16x32_bf16 v[56:59], v[136:139], v[168:171], v[56:59]
	v_mfma_f32_16x16x32_bf16 v[108:111], v[132:135], v[148:151], v[108:111]
	v_mfma_f32_16x16x32_bf16 v[76:79], v[140:143], v[148:151], v[76:79]
	v_mfma_f32_16x16x32_bf16 v[100:103], v[132:135], v[156:159], v[100:103]
	v_mfma_f32_16x16x32_bf16 v[72:75], v[140:143], v[156:159], v[72:75]
	v_mfma_f32_16x16x32_bf16 v[92:95], v[132:135], v[164:167], v[92:95]
	v_mfma_f32_16x16x32_bf16 v[64:67], v[140:143], v[164:167], v[64:67]
	v_mfma_f32_16x16x32_bf16 v[84:87], v[132:135], v[172:175], v[84:87]
	v_mfma_f32_16x16x32_bf16 v[56:59], v[140:143], v[172:175], v[56:59]
	s_setprio 0
	s_barrier
; #define PG8_STAGE(bufoff, gbase, voff) do { _Pragma("unroll") for (int _i = 0; _i < 2; ++_i) \
;         __builtin_amdgcn_global_load_lds((const unsigned*)((const char*)(gbase) + (voff)[_i]), (LAS unsigned*)(lds + (bufoff) + ldsw + _i * 8192), 16, 0, 0); } while (0)
; #define PG8_LDA(dst, b, h) do { _Pragma("unroll") for (int m = 0; m < 4; ++m) _Pragma("unroll") for (int k = 0; k < 2; ++k) dst[m][k] = *(const LAS bf16x8*)(lds + PG8_SA(b, h) + aoff + m * 2048 + k * 1024); } while (0)
; #define PG8_LDB(dst, b, h) do { _Pragma("unroll") for (int n = 0; n < 2; ++n) _Pragma("unroll") for (int k = 0; k < 2; ++k) dst[n][k] = *(const LAS bf16x8*)(lds + PG8_SB(b, h) + boff + n * 2048 + k * 1024); } while (0)
; #define PG8_MMA(ai, bj, At, Bt) do { __builtin_amdgcn_s_setprio(1); _Pragma("unroll") for (int m = 0; m < 4; ++m) _Pragma("unroll") for (int n = 0; n < 2; ++n) _Pragma("unroll") for (int k = 0; k < 2; ++k) \
;         acc[ai][bj][m][n] = __builtin_amdgcn_mfma_f32_16x16x32_bf16(Bt[n][k], At[m][k], acc[ai][bj][m][n], 0, 0, 0); __builtin_amdgcn_s_setprio(0); } while (0)
; #define PG8_WAIT_V(n) asm volatile("s_waitcnt vmcnt(" #n ")" ::: "memory")
; #define PG8_WAIT_L(n) asm volatile("s_waitcnt lgkmcnt(" #n ")" ::: "memory")
; #define PG8_BAR __builtin_amdgcn_s_barrier()
; #define PG8_SCHED __builtin_amdgcn_sched_barrier(0)
; template <class Epi, class Order>
; __device__ __forceinline__ void gemm_phase(LAS unsigned char* lds, const Gemm g, const Order& S, const Epi& E) {
;     ...
;             PG8_STAGE(PG8_SB(0, 1), b2 + hstep, voffB);
;             PG8_WAIT_V(6); PG8_BAR; PG8_MMA(1, 1, At, B1); PG8_BAR;
;             PG8_LDB(B0, 1, 0); PG8_SCHED; PG8_LDA(At, 1, 0); PG8_STAGE(PG8_SA(0, 1), a2 + hstep, voffA);
;             PG8_WAIT_L(8); PG8_BAR; PG8_WAIT_L(0); PG8_MMA(0, 0, At, B0); PG8_BAR; PG8_SCHED;
;             PG8_LDB(B1, 1, 1); PG8_STAGE(PG8_SB(1, 0), b3, voffB);
;             PG8_BAR; PG8_WAIT_L(0); PG8_MMA(0, 1, At, B1); PG8_BAR;
;             PG8_LDA(At, 1, 1); PG8_STAGE(PG8_SA(1, 0), a3, voffA);
	s_add_u32 s24, s46, 0x80000
	s_addc_u32 s25, s47, 0
	s_add_i32 s27, s72, s54
	s_mov_b32 m0, s27
	s_nop 0
	global_load_lds_dwordx4 v182, s[24:25]
	s_add_i32 m0, s27, 0x2000
	s_nop 0
	global_load_lds_dwordx4 v184, s[24:25]
	s_waitcnt vmcnt(6)
	s_barrier
	s_setprio 1
	v_mfma_f32_16x16x32_bf16 v[44:47], v[176:179], v[144:147], v[44:47]
	v_mfma_f32_16x16x32_bf16 v[12:15], v[198:201], v[144:147], v[12:15]
	v_mfma_f32_16x16x32_bf16 v[36:39], v[176:179], v[152:155], v[36:39]
	v_mfma_f32_16x16x32_bf16 v[8:11], v[198:201], v[152:155], v[8:11]
	v_mfma_f32_16x16x32_bf16 v[28:31], v[176:179], v[160:163], v[28:31]
	v_mfma_f32_16x16x32_bf16 v[4:7], v[198:201], v[160:163], v[4:7]
	v_mfma_f32_16x16x32_bf16 v[24:27], v[176:179], v[168:171], v[24:27]
	v_mfma_f32_16x16x32_bf16 v[0:3], v[198:201], v[168:171], v[0:3]
	v_mfma_f32_16x16x32_bf16 v[44:47], v[194:197], v[148:151], v[44:47]
	v_mfma_f32_16x16x32_bf16 v[12:15], v[202:205], v[148:151], v[12:15]
	v_mfma_f32_16x16x32_bf16 v[36:39], v[194:197], v[156:159], v[36:39]
	v_mfma_f32_16x16x32_bf16 v[8:11], v[202:205], v[156:159], v[8:11]
	v_mfma_f32_16x16x32_bf16 v[28:31], v[194:197], v[164:167], v[28:31]
	v_mfma_f32_16x16x32_bf16 v[4:7], v[202:205], v[164:167], v[4:7]
	v_mfma_f32_16x16x32_bf16 v[24:27], v[194:197], v[172:175], v[24:27]
	v_mfma_f32_16x16x32_bf16 v[0:3], v[202:205], v[172:175], v[0:3]
	s_setprio 0
	s_add_i32 s27, 0, 0x18000
	v_add_u32_e32 v140, s27, v242
	s_barrier
	ds_read_b128 v[128:131], v140
	ds_read_b128 v[132:135], v140 offset:1024
	ds_read_b128 v[136:139], v140 offset:2048
	ds_read_b128 v[140:143], v140 offset:3072
	s_add_u32 s24, s52, 0x80000
	s_addc_u32 s25, s53, 0
	s_mov_b32 m0, s62
	ds_read_b128 v[144:147], v245 offset:32768
	ds_read_b128 v[148:151], v245 offset:33792
	ds_read_b128 v[152:155], v245 offset:34816
	ds_read_b128 v[156:159], v245 offset:35840
	ds_read_b128 v[160:163], v245 offset:36864
	ds_read_b128 v[164:167], v245 offset:37888
	ds_read_b128 v[168:171], v245 offset:38912
	ds_read_b128 v[172:175], v245 offset:39936
	global_load_lds_dwordx4 v182, s[24:25]
	s_mov_b32 m0, s63
	s_nop 0
	global_load_lds_dwordx4 v184, s[24:25]
	s_waitcnt lgkmcnt(8)
	s_barrier
	s_waitcnt lgkmcnt(0)
	s_setprio 1
	s_waitcnt lgkmcnt(0)
	v_mfma_f32_16x16x32_bf16 v[124:127], v[128:131], v[144:147], v[124:127]
	v_mfma_f32_16x16x32_bf16 v[104:107], v[136:139], v[144:147], v[104:107]
	v_mfma_f32_16x16x32_bf16 v[120:123], v[128:131], v[152:155], v[120:123]
	v_mfma_f32_16x16x32_bf16 v[96:99], v[136:139], v[152:155], v[96:99]
	v_mfma_f32_16x16x32_bf16 v[116:119], v[128:131], v[160:163], v[116:119]
	v_mfma_f32_16x16x32_bf16 v[88:91], v[136:139], v[160:163], v[88:91]
	v_mfma_f32_16x16x32_bf16 v[112:115], v[128:131], v[168:171], v[112:115]
	v_mfma_f32_16x16x32_bf16 v[80:83], v[136:139], v[168:171], v[80:83]
	v_mfma_f32_16x16x32_bf16 v[124:127], v[132:135], v[148:151], v[124:127]
	v_mfma_f32_16x16x32_bf16 v[104:107], v[140:143], v[148:151], v[104:107]
	v_mfma_f32_16x16x32_bf16 v[120:123], v[132:135], v[156:159], v[120:123]
	v_mfma_f32_16x16x32_bf16 v[96:99], v[140:143], v[156:159], v[96:99]
	v_mfma_f32_16x16x32_bf16 v[116:119], v[132:135], v[164:167], v[116:119]
	v_mfma_f32_16x16x32_bf16 v[88:91], v[140:143], v[164:167], v[88:91]
	v_mfma_f32_16x16x32_bf16 v[112:115], v[132:135], v[172:175], v[112:115]
	v_mfma_f32_16x16x32_bf16 v[80:83], v[140:143], v[172:175], v[80:83]
	s_setprio 0
	s_barrier
	s_add_i32 s52, 0, 0x1c000
	s_add_i32 s24, s27, s54
	v_add_u32_e32 v202, s52, v242
	v_lshl_add_u64 v[206:207], v[206:207], 0, s[6:7]
	s_mov_b32 m0, s24
	ds_read_b128 v[176:179], v202
	ds_read_b128 v[194:197], v202 offset:1024
	ds_read_b128 v[198:201], v202 offset:2048
	ds_read_b128 v[202:205], v202 offset:3072
	global_load_lds_dwordx4 v[206:207], off
	v_lshl_add_u64 v[206:207], v[208:209], 0, s[6:7]
	s_add_i32 m0, s24, 0x2000
	s_nop 0
	global_load_lds_dwordx4 v[206:207], off
	s_barrier
; #define PG8_STAGE(bufoff, gbase, voff) do { _Pragma("unroll") for (int _i = 0; _i < 2; ++_i) \
;         __builtin_amdgcn_global_load_lds((const unsigned*)((const char*)(gbase) + (voff)[_i]), (LAS unsigned*)(lds + (bufoff) + ldsw + _i * 8192), 16, 0, 0); } while (0)
; #define PG8_MMA(ai, bj, At, Bt) do { __builtin_amdgcn_s_setprio(1); _Pragma("unroll") for (int m = 0; m < 4; ++m) _Pragma("unroll") for (int n = 0; n < 2; ++n) _Pragma("unroll") for (int k = 0; k < 2; ++k) \
;         acc[ai][bj][m][n] = __builtin_amdgcn_mfma_f32_16x16x32_bf16(Bt[n][k], At[m][k], acc[ai][bj][m][n], 0, 0, 0); __builtin_amdgcn_s_setprio(0); } while (0)
; #define PG8_WAIT_V(n) asm volatile("s_waitcnt vmcnt(" #n ")" ::: "memory")
; #define PG8_WAIT_L(n) asm volatile("s_waitcnt lgkmcnt(" #n ")" ::: "memory")
; #define PG8_BAR __builtin_amdgcn_s_barrier()
; #define PG8_SCHED __builtin_amdgcn_sched_barrier(0)
; template <class Epi, class Order>
; __device__ __forceinline__ void gemm_phase(LAS unsigned char* lds, const Gemm g, const Order& S, const Epi& E) {
;     ...
;             PG8_BAR; PG8_WAIT_L(0); PG8_MMA(1, 0, At, B0); PG8_BAR; PG8_SCHED;
;             PG8_STAGE(PG8_SB(1, 1), b3 + hstep, voffB);
;             PG8_WAIT_V(6); PG8_BAR; PG8_MMA(1, 1, At, B1); PG8_BAR;
;     __device__ __forceinline__ void operator()(const f32x4 (&acc)[2][2][4][2], const pg8::Unit& u, int wr, int wc, int fr, int fq) const {
;         const bool isx = u.pm < (MX / 256);
;         const int mr = isx ? (u.pm >> 4) : 8;
;         const float* gate = modv + (size_t)mr * MODW + gslot * D;
;         const int lrow0 = (isx ? u.pm : u.pm - MX / 256) * 256 + wr * 64 + fr;
;         const float* src = isx ? Xx : Xc; float* dst = isx ? Yx : Yc;
	s_waitcnt lgkmcnt(0)
	s_setprio 1
	s_waitcnt lgkmcnt(0)
	v_mfma_f32_16x16x32_bf16 v[68:71], v[176:179], v[144:147], v[68:71]
	v_mfma_f32_16x16x32_bf16 v[40:43], v[198:201], v[144:147], v[40:43]
	v_mfma_f32_16x16x32_bf16 v[60:63], v[176:179], v[152:155], v[60:63]
	v_mfma_f32_16x16x32_bf16 v[32:35], v[198:201], v[152:155], v[32:35]
	v_mfma_f32_16x16x32_bf16 v[52:55], v[176:179], v[160:163], v[52:55]
	v_mfma_f32_16x16x32_bf16 v[20:23], v[198:201], v[160:163], v[20:23]
	v_mfma_f32_16x16x32_bf16 v[48:51], v[176:179], v[168:171], v[48:51]
	v_mfma_f32_16x16x32_bf16 v[16:19], v[198:201], v[168:171], v[16:19]
	v_mfma_f32_16x16x32_bf16 v[68:71], v[194:197], v[148:151], v[68:71]
	v_mfma_f32_16x16x32_bf16 v[40:43], v[202:205], v[148:151], v[40:43]
	v_mfma_f32_16x16x32_bf16 v[60:63], v[194:197], v[156:159], v[60:63]
	v_mfma_f32_16x16x32_bf16 v[32:35], v[202:205], v[156:159], v[32:35]
	v_mfma_f32_16x16x32_bf16 v[52:55], v[194:197], v[164:167], v[52:55]
	v_mfma_f32_16x16x32_bf16 v[20:23], v[202:205], v[164:167], v[20:23]
	v_mfma_f32_16x16x32_bf16 v[48:51], v[194:197], v[172:175], v[48:51]
	v_mfma_f32_16x16x32_bf16 v[16:19], v[202:205], v[172:175], v[16:19]
	s_setprio 0
	s_mov_b32 m0, s68
	v_lshl_add_u64 v[206:207], v[210:211], 0, s[6:7]
	s_barrier
	ds_read_b128 v[144:147], v245 offset:49152
	ds_read_b128 v[148:151], v245 offset:50176
	ds_read_b128 v[152:155], v245 offset:51200
	ds_read_b128 v[156:159], v245 offset:52224
	ds_read_b128 v[160:163], v245 offset:53248
	ds_read_b128 v[164:167], v245 offset:54272
	ds_read_b128 v[168:171], v245 offset:55296
	ds_read_b128 v[172:175], v245 offset:56320
	global_load_lds_dwordx4 v[206:207], off
	v_lshl_add_u64 v[206:207], v[212:213], 0, s[6:7]
	s_mov_b32 m0, s69
	s_nop 0
	global_load_lds_dwordx4 v[206:207], off
	s_barrier
	s_waitcnt lgkmcnt(0)
	s_setprio 1
	s_waitcnt lgkmcnt(0)
	v_mfma_f32_16x16x32_bf16 v[108:111], v[128:131], v[144:147], v[108:111]
	v_mfma_f32_16x16x32_bf16 v[76:79], v[136:139], v[144:147], v[76:79]
	v_mfma_f32_16x16x32_bf16 v[100:103], v[128:131], v[152:155], v[100:103]
	v_mfma_f32_16x16x32_bf16 v[72:75], v[136:139], v[152:155], v[72:75]
	v_mfma_f32_16x16x32_bf16 v[92:95], v[128:131], v[160:163], v[92:95]
	v_mfma_f32_16x16x32_bf16 v[64:67], v[136:139], v[160:163], v[64:67]
	v_mfma_f32_16x16x32_bf16 v[84:87], v[128:131], v[168:171], v[84:87]
	v_mfma_f32_16x16x32_bf16 v[56:59], v[136:139], v[168:171], v[56:59]
	v_mfma_f32_16x16x32_bf16 v[108:111], v[132:135], v[148:151], v[108:111]
	v_mfma_f32_16x16x32_bf16 v[76:79], v[140:143], v[148:151], v[76:79]
	v_mfma_f32_16x16x32_bf16 v[100:103], v[132:135], v[156:159], v[100:103]
	v_mfma_f32_16x16x32_bf16 v[72:75], v[140:143], v[156:159], v[72:75]
	v_mfma_f32_16x16x32_bf16 v[92:95], v[132:135], v[164:167], v[92:95]
	v_mfma_f32_16x16x32_bf16 v[64:67], v[140:143], v[164:167], v[64:67]
	v_mfma_f32_16x16x32_bf16 v[84:87], v[132:135], v[172:175], v[84:87]
	v_mfma_f32_16x16x32_bf16 v[56:59], v[140:143], v[172:175], v[56:59]
	s_setprio 0
	s_barrier
	s_add_u32 s24, s46, 0x80080
	s_addc_u32 s25, s47, 0
	s_add_i32 s27, s52, s54
	s_mov_b32 m0, s27
	s_nop 0
	global_load_lds_dwordx4 v182, s[24:25]
	v_lshl_add_u64 v[128:129], s[24:25], 0, v[184:185]
	s_add_i32 m0, s27, 0x2000
	s_nop 0
	global_load_lds_dwordx4 v[128:129], off
	s_waitcnt vmcnt(6)
	s_barrier
	s_setprio 1
	v_mfma_f32_16x16x32_bf16 v[44:47], v[176:179], v[144:147], v[44:47]
	v_mfma_f32_16x16x32_bf16 v[12:15], v[198:201], v[144:147], v[12:15]
	v_mfma_f32_16x16x32_bf16 v[36:39], v[176:179], v[152:155], v[36:39]
	v_mfma_f32_16x16x32_bf16 v[8:11], v[198:201], v[152:155], v[8:11]
	v_mfma_f32_16x16x32_bf16 v[28:31], v[176:179], v[160:163], v[28:31]
	v_mfma_f32_16x16x32_bf16 v[4:7], v[198:201], v[160:163], v[4:7]
	v_mfma_f32_16x16x32_bf16 v[24:27], v[176:179], v[168:171], v[24:27]
	v_mfma_f32_16x16x32_bf16 v[0:3], v[198:201], v[168:171], v[0:3]
	v_mfma_f32_16x16x32_bf16 v[44:47], v[194:197], v[148:151], v[44:47]
	v_mfma_f32_16x16x32_bf16 v[12:15], v[202:205], v[148:151], v[12:15]
	v_mfma_f32_16x16x32_bf16 v[36:39], v[194:197], v[156:159], v[36:39]
	v_mfma_f32_16x16x32_bf16 v[8:11], v[202:205], v[156:159], v[8:11]
	v_mfma_f32_16x16x32_bf16 v[28:31], v[194:197], v[164:167], v[28:31]
	v_mfma_f32_16x16x32_bf16 v[4:7], v[202:205], v[164:167], v[4:7]
	v_mfma_f32_16x16x32_bf16 v[24:27], v[194:197], v[172:175], v[24:27]
	v_mfma_f32_16x16x32_bf16 v[0:3], v[202:205], v[172:175], v[0:3]
	s_setprio 0
	s_add_i32 s80, s80, 2
	s_add_u32 s44, s44, 0x100
	s_addc_u32 s45, s45, 0
	s_add_u32 s78, s78, 0x100
	s_addc_u32 s79, s79, 0
	s_cmp_gt_u32 s80, 29
	s_barrier
	s_cbranch_scc0 .LBB0_1002
	s_cmpk_lt_i32 s42, 0x80
	s_mov_b64 s[46:47], 0x24000
	s_cselect_b64 s[52:53], -1, 0
	s_cmpk_gt_i32 s42, 0x7f
	s_mov_b64 s[44:45], s[38:39]
	s_cbranch_scc1 .LBB0_994
	s_ashr_i32 s19, s42, 4
	s_mul_hi_i32 s47, s19, 0x4800
	s_mul_i32 s46, s19, 0x4800
	s_mov_b64 s[44:45], s[86:87]
	s_branch .LBB0_994

; #define PG8_STAGE(bufoff, gbase, voff) do { _Pragma("unroll") for (int _i = 0; _i < 2; ++_i) \
;         __builtin_amdgcn_global_load_lds((const unsigned*)((const char*)(gbase) + (voff)[_i]), (LAS unsigned*)(lds + (bufoff) + ldsw + _i * 8192), 16, 0, 0); } while (0)
; #define PG8_WAIT_V(n) asm volatile("s_waitcnt vmcnt(" #n ")" ::: "memory")
; #define PG8_BAR __builtin_amdgcn_s_barrier()
; template <class Epi, class Order>
; __device__ __forceinline__ void gemm_phase(LAS unsigned char* lds, const Gemm g, const Order& S, const Epi& E) {
;     const int tid = threadIdx.x, wid = __builtin_amdgcn_readfirstlane(tid >> 6), lane = tid & 63, wr = wid >> 2, wc = wid & 3, fr = lane & 15, fq = lane >> 4;
;     int K = g.K; if (Order::OPAQUE_K) asm volatile("" : "+s"(K));
;     const int nt = K / BK;
;     unsigned voffA[2], voffB[2];
; #pragma unroll
;     for (int i = 0; i < 2; ++i) { int R, C; stage_rc(tid * 16 + i * 8192, R, C); const int Rb = Epi::PERM ? ((R & ~31) + perm32(R & 31)) : R;
;         voffA[i] = (unsigned)(R * g.ld + C) * 2u; voffB[i] = (unsigned)(Rb * g.ld + C) * 2u; }
;     const size_t kstep = (size_t)(BK * 2);
;     const size_t hstep = (size_t)HALF * g.ld * 2;
;     const size_t sstep = (size_t)K * 2;
;     const size_t tstep = 2 * hstep;
;     const unsigned ldsw = (unsigned)wid * 1024u;
;     const int aoff = lds_byte(wr * 64 + fr, fq * 8), boff = lds_byte(wc * 32 + fr, fq * 8);
;     ...
;     PG8_STAGE(PG8_SB(1, 0), cB + kstep, voffB); PG8_STAGE(PG8_SA(1, 0), cA + kstep, voffA); PG8_STAGE(PG8_SB(1, 1), cB + hstep + kstep, voffB);
;     PG8_WAIT_V(6); PG8_BAR;
.LBB0_1137:
	s_add_u32 s4, s88, 0xfe00000
	s_addc_u32 s5, s89, 0
	s_lshl_b32 s6, s6, 5
	s_and_b32 s11, s6, 0x60
	s_mov_b64 s[6:7], 0x80
	s_add_i32 m0, s17, 0x18000
	v_lshl_add_u64 v[6:7], v[6:7], 0, s[6:7]
	s_ashr_i32 s45, s28, 31
	s_lshl_b32 s10, s3, 13
	s_lshl_b32 s12, s11, 7
	s_waitcnt vmcnt(4)
	s_barrier
	global_load_lds_dwordx4 v[6:7], off
	v_lshl_add_u64 v[4:5], v[4:5], 0, s[6:7]
	s_add_i32 m0, s17, 0x1a000
	s_add_i32 s46, s17, 0x8000
	s_add_i32 s47, s17, 0xa000
	global_load_lds_dwordx4 v[4:5], off
	v_lshl_add_u64 v[2:3], v[2:3], 0, s[6:7]
	s_mov_b32 m0, s46
	s_add_u32 s8, s20, 0x80080
	global_load_lds_dwordx4 v[2:3], off
	v_lshl_add_u64 v[0:1], v[0:1], 0, s[6:7]
	s_mov_b32 m0, s47
	s_addc_u32 s9, s21, 0
	global_load_lds_dwordx4 v[0:1], off
	s_add_i32 m0, s17, 0x1c000
	s_nop 0
	global_load_lds_dwordx4 v130, s[8:9]
	s_add_i32 m0, s17, 0x1e000
	s_sext_i32_i16 s56, s2
	global_load_lds_dwordx4 v134, s[8:9]
	v_and_b32_e32 v0, 15, v241
	v_lshlrev_b32_e32 v1, 1, v11
	v_lshlrev_b32_e32 v2, 6, v241
	s_movk_i32 s2, 0x3c0
	v_lshlrev_b32_e32 v3, 2, v241
	v_and_or_b32 v2, v2, s2, v1
	v_and_b32_e32 v3, 32, v3
	v_lshl_or_b32 v148, s3, 6, v0
	v_lshl_or_b32 v0, v0, 6, v1
	v_lshlrev_b32_e32 v1, 9, v241
	v_bitop3_b32 v149, s12, v2, v3 bitop3:0xf6
	v_and_b32_e32 v1, 0x70000, v1
	v_lshlrev_b32_e32 v2, 12, v10
	v_or3_b32 v1, v8, v1, v2
	v_add_u32_e32 v136, v1, v9
	v_lshlrev_b32_e32 v1, 5, v12
	s_waitcnt vmcnt(6)
	v_and_b32_e32 v1, 0xf0000, v1
	v_bitop3_b32 v0, v0, s10, v3 bitop3:0xde
	v_or3_b32 v1, v8, v1, v2
	s_add_i32 s53, 0, 0x10000
	s_add_i32 s54, 0, 0x14000
	s_mov_b32 s52, s28
	v_or_b32_e32 v150, s11, v11
	v_mov_b32_e32 v137, v131
	v_add_u32_e32 v138, v1, v9
	v_mov_b32_e32 v139, v131
	v_mov_b64_e32 v[140:141], 0x1600
	v_mov_b64_e32 v[142:143], 0x15ff
	v_add_u32_e32 v151, s53, v149
	v_add_u32_e32 v152, 0, v0
	v_add_u32_e32 v153, s54, v149
	s_movk_i32 s55, 0x2c00
	s_barrier

; #define PG8_STAGE(bufoff, gbase, voff) do { _Pragma("unroll") for (int _i = 0; _i < 2; ++_i) \
;         __builtin_amdgcn_global_load_lds((const unsigned*)((const char*)(gbase) + (voff)[_i]), (LAS unsigned*)(lds + (bufoff) + ldsw + _i * 8192), 16, 0, 0); } while (0)
; #define PG8_LDA(dst, b, h) do { _Pragma("unroll") for (int m = 0; m < 4; ++m) _Pragma("unroll") for (int k = 0; k < 2; ++k) dst[m][k] = *(const LAS bf16x8*)(lds + PG8_SA(b, h) + aoff + m * 2048 + k * 1024); } while (0)
; #define PG8_LDB(dst, b, h) do { _Pragma("unroll") for (int n = 0; n < 2; ++n) _Pragma("unroll") for (int k = 0; k < 2; ++k) dst[n][k] = *(const LAS bf16x8*)(lds + PG8_SB(b, h) + boff + n * 2048 + k * 1024); } while (0)
; #define PG8_MMA(ai, bj, At, Bt) do { __builtin_amdgcn_s_setprio(1); _Pragma("unroll") for (int m = 0; m < 4; ++m) _Pragma("unroll") for (int n = 0; n < 2; ++n) _Pragma("unroll") for (int k = 0; k < 2; ++k) \
;         acc[ai][bj][m][n] = __builtin_amdgcn_mfma_f32_16x16x32_bf16(Bt[n][k], At[m][k], acc[ai][bj][m][n], 0, 0, 0); __builtin_amdgcn_s_setprio(0); } while (0)
; #define PG8_WAIT_L(n) asm volatile("s_waitcnt lgkmcnt(" #n ")" ::: "memory")
; #define PG8_BAR __builtin_amdgcn_s_barrier()
; #define PG8_SCHED __builtin_amdgcn_sched_barrier(0)
; template <class Epi, class Order>
; __device__ __forceinline__ void gemm_phase(LAS unsigned char* lds, const Gemm g, const Order& S, const Epi& E) {
;     ...
;             PG8_LDB(B0, 0, 0); PG8_SCHED; PG8_LDA(At, 0, 0); PG8_STAGE(PG8_SA(1, 1), a1 + hstep, voffA);
;             PG8_WAIT_L(8); PG8_BAR; PG8_WAIT_L(0); PG8_MMA(0, 0, At, B0); PG8_BAR; PG8_SCHED;
;             PG8_LDB(B1, 0, 1); PG8_STAGE(PG8_SB(0, 0), b2, voffB);
;             PG8_BAR; PG8_WAIT_L(0); PG8_MMA(0, 1, At, B1); PG8_BAR;
;             PG8_LDA(At, 0, 1); PG8_STAGE(PG8_SA(0, 0), a2, voffA);
;             PG8_BAR; PG8_WAIT_L(0); PG8_MMA(1, 0, At, B0); PG8_BAR; PG8_SCHED;
.LBB0_1141:
	ds_read_b128 v[144:147], v151
	ds_read_b128 v[154:157], v151 offset:1024
	ds_read_b128 v[158:161], v151 offset:2048
	ds_read_b128 v[162:165], v151 offset:3072
	s_add_u32 s20, s18, 0xfff80080
	s_addc_u32 s21, s19, -1
	s_cmp_eq_u32 s61, 28
	s_cselect_b32 s23, s11, s21
	s_cselect_b32 s22, s57, s20
	s_cselect_b32 s21, s9, s60
	s_cselect_b32 s20, s58, s59
	v_lshl_add_u64 v[178:179], s[18:19], 0, v[136:137]
	s_add_i32 m0, s17, 0xc000
	ds_read_b128 v[166:169], v152
	ds_read_b128 v[170:173], v152 offset:1024
	ds_read_b128 v[174:177], v152 offset:2048
	ds_read_b128 v[182:185], v152 offset:3072
	ds_read_b128 v[186:189], v152 offset:4096
	ds_read_b128 v[190:193], v152 offset:5120
	ds_read_b128 v[194:197], v152 offset:6144
	ds_read_b128 v[198:201], v152 offset:7168
	global_load_lds_dwordx4 v[178:179], off
	v_lshl_add_u64 v[178:179], s[18:19], 0, v[138:139]
	s_add_i32 m0, s17, 0xe000
	s_nop 0
	global_load_lds_dwordx4 v[178:179], off
	s_waitcnt lgkmcnt(8)
	s_barrier
	s_waitcnt lgkmcnt(0)
	s_setprio 1
	s_waitcnt lgkmcnt(0)
	v_mfma_f32_16x16x32_bf16 v[124:127], v[144:147], v[166:169], v[124:127]
	v_mfma_f32_16x16x32_bf16 v[116:119], v[158:161], v[166:169], v[116:119]
	v_mfma_f32_16x16x32_bf16 v[108:111], v[144:147], v[174:177], v[108:111]
	v_mfma_f32_16x16x32_bf16 v[100:103], v[158:161], v[174:177], v[100:103]
	v_mfma_f32_16x16x32_bf16 v[92:95], v[144:147], v[186:189], v[92:95]
	v_mfma_f32_16x16x32_bf16 v[84:87], v[158:161], v[186:189], v[84:87]
	v_mfma_f32_16x16x32_bf16 v[76:79], v[144:147], v[194:197], v[76:79]
	v_mfma_f32_16x16x32_bf16 v[68:71], v[158:161], v[194:197], v[68:71]
	v_mfma_f32_16x16x32_bf16 v[124:127], v[154:157], v[170:173], v[124:127]
	v_mfma_f32_16x16x32_bf16 v[116:119], v[162:165], v[170:173], v[116:119]
	v_mfma_f32_16x16x32_bf16 v[108:111], v[154:157], v[182:185], v[108:111]
	v_mfma_f32_16x16x32_bf16 v[100:103], v[162:165], v[182:185], v[100:103]
	v_mfma_f32_16x16x32_bf16 v[92:95], v[154:157], v[190:193], v[92:95]
	v_mfma_f32_16x16x32_bf16 v[84:87], v[162:165], v[190:193], v[84:87]
	v_mfma_f32_16x16x32_bf16 v[76:79], v[154:157], v[198:201], v[76:79]
	v_mfma_f32_16x16x32_bf16 v[68:71], v[162:165], v[198:201], v[68:71]
	s_setprio 0
	s_barrier
	s_add_i32 s24, s53, s36
	v_lshl_add_u64 v[178:179], s[20:21], 0, v[130:131]
	s_mov_b32 m0, s24
	ds_read_b128 v[202:205], v153
	ds_read_b128 v[206:209], v153 offset:1024
	ds_read_b128 v[210:213], v153 offset:2048
	ds_read_b128 v[214:217], v153 offset:3072
	global_load_lds_dwordx4 v[178:179], off
	v_lshl_add_u64 v[218:219], s[20:21], 0, v[134:135]
	s_add_i32 m0, s24, 0x2000
	s_nop 0
	global_load_lds_dwordx4 v[218:219], off
	s_barrier
	s_waitcnt lgkmcnt(0)
	s_setprio 1
	s_waitcnt lgkmcnt(0)
	v_mfma_f32_16x16x32_bf16 v[120:123], v[202:205], v[166:169], v[120:123]
	v_mfma_f32_16x16x32_bf16 v[112:115], v[210:213], v[166:169], v[112:115]
	v_mfma_f32_16x16x32_bf16 v[104:107], v[202:205], v[174:177], v[104:107]
	v_mfma_f32_16x16x32_bf16 v[96:99], v[210:213], v[174:177], v[96:99]
	v_mfma_f32_16x16x32_bf16 v[88:91], v[202:205], v[186:189], v[88:91]
	v_mfma_f32_16x16x32_bf16 v[80:83], v[210:213], v[186:189], v[80:83]
	v_mfma_f32_16x16x32_bf16 v[72:75], v[202:205], v[194:197], v[72:75]
	v_mfma_f32_16x16x32_bf16 v[64:67], v[210:213], v[194:197], v[64:67]
	v_mfma_f32_16x16x32_bf16 v[120:123], v[206:209], v[170:173], v[120:123]
	v_mfma_f32_16x16x32_bf16 v[112:115], v[214:217], v[170:173], v[112:115]
	v_mfma_f32_16x16x32_bf16 v[104:107], v[206:209], v[182:185], v[104:107]
	v_mfma_f32_16x16x32_bf16 v[96:99], v[214:217], v[182:185], v[96:99]
	v_mfma_f32_16x16x32_bf16 v[88:91], v[206:209], v[190:193], v[88:91]
	v_mfma_f32_16x16x32_bf16 v[80:83], v[214:217], v[190:193], v[80:83]
	v_mfma_f32_16x16x32_bf16 v[72:75], v[206:209], v[198:201], v[72:75]
	v_mfma_f32_16x16x32_bf16 v[64:67], v[214:217], v[198:201], v[64:67]
	s_setprio 0
	s_mov_b32 m0, s17
	v_lshl_add_u64 v[220:221], s[22:23], 0, v[128:129]
	s_barrier
	ds_read_b128 v[166:169], v152 offset:16384
	ds_read_b128 v[170:173], v152 offset:17408
	ds_read_b128 v[174:177], v152 offset:18432
	ds_read_b128 v[182:185], v152 offset:19456
	ds_read_b128 v[186:189], v152 offset:20480
	ds_read_b128 v[190:193], v152 offset:21504
	ds_read_b128 v[194:197], v152 offset:22528
	ds_read_b128 v[198:201], v152 offset:23552
	global_load_lds_dwordx4 v[220:221], off
	v_lshl_add_u64 v[222:223], s[22:23], 0, v[132:133]
	s_mov_b32 m0, s41
	s_nop 0
	global_load_lds_dwordx4 v[222:223], off
	s_barrier
	s_waitcnt lgkmcnt(0)
	s_setprio 1
	s_waitcnt lgkmcnt(0)
	v_mfma_f32_16x16x32_bf16 v[60:63], v[144:147], v[166:169], v[60:63]
	v_mfma_f32_16x16x32_bf16 v[52:55], v[158:161], v[166:169], v[52:55]
	v_mfma_f32_16x16x32_bf16 v[44:47], v[144:147], v[174:177], v[44:47]
	v_mfma_f32_16x16x32_bf16 v[36:39], v[158:161], v[174:177], v[36:39]
	v_mfma_f32_16x16x32_bf16 v[28:31], v[144:147], v[186:189], v[28:31]
	v_mfma_f32_16x16x32_bf16 v[20:23], v[158:161], v[186:189], v[20:23]
	v_mfma_f32_16x16x32_bf16 v[12:15], v[144:147], v[194:197], v[12:15]
	v_mfma_f32_16x16x32_bf16 v[4:7], v[158:161], v[194:197], v[4:7]
	v_mfma_f32_16x16x32_bf16 v[60:63], v[154:157], v[170:173], v[60:63]
	v_mfma_f32_16x16x32_bf16 v[52:55], v[162:165], v[170:173], v[52:55]
	v_mfma_f32_16x16x32_bf16 v[44:47], v[154:157], v[182:185], v[44:47]
	v_mfma_f32_16x16x32_bf16 v[36:39], v[162:165], v[182:185], v[36:39]
	v_mfma_f32_16x16x32_bf16 v[28:31], v[154:157], v[190:193], v[28:31]
	v_mfma_f32_16x16x32_bf16 v[20:23], v[162:165], v[190:193], v[20:23]
	v_mfma_f32_16x16x32_bf16 v[12:15], v[154:157], v[198:201], v[12:15]
	v_mfma_f32_16x16x32_bf16 v[4:7], v[162:165], v[198:201], v[4:7]
	s_setprio 0
	s_barrier
; #define PG8_STAGE(bufoff, gbase, voff) do { _Pragma("unroll") for (int _i = 0; _i < 2; ++_i) \
;         __builtin_amdgcn_global_load_lds((const unsigned*)((const char*)(gbase) + (voff)[_i]), (LAS unsigned*)(lds + (bufoff) + ldsw + _i * 8192), 16, 0, 0); } while (0)
; #define PG8_LDA(dst, b, h) do { _Pragma("unroll") for (int m = 0; m < 4; ++m) _Pragma("unroll") for (int k = 0; k < 2; ++k) dst[m][k] = *(const LAS bf16x8*)(lds + PG8_SA(b, h) + aoff + m * 2048 + k * 1024); } while (0)
; #define PG8_LDB(dst, b, h) do { _Pragma("unroll") for (int n = 0; n < 2; ++n) _Pragma("unroll") for (int k = 0; k < 2; ++k) dst[n][k] = *(const LAS bf16x8*)(lds + PG8_SB(b, h) + boff + n * 2048 + k * 1024); } while (0)
; #define PG8_MMA(ai, bj, At, Bt) do { __builtin_amdgcn_s_setprio(1); _Pragma("unroll") for (int m = 0; m < 4; ++m) _Pragma("unroll") for (int n = 0; n < 2; ++n) _Pragma("unroll") for (int k = 0; k < 2; ++k) \
;         acc[ai][bj][m][n] = __builtin_amdgcn_mfma_f32_16x16x32_bf16(Bt[n][k], At[m][k], acc[ai][bj][m][n], 0, 0, 0); __builtin_amdgcn_s_setprio(0); } while (0)
; #define PG8_WAIT_V(n) asm volatile("s_waitcnt vmcnt(" #n ")" ::: "memory")
; #define PG8_WAIT_L(n) asm volatile("s_waitcnt lgkmcnt(" #n ")" ::: "memory")
; #define PG8_BAR __builtin_amdgcn_s_barrier()
; #define PG8_SCHED __builtin_amdgcn_sched_barrier(0)
; template <class Epi, class Order>
; __device__ __forceinline__ void gemm_phase(LAS unsigned char* lds, const Gemm g, const Order& S, const Epi& E) {
;     ...
;             PG8_STAGE(PG8_SB(0, 1), b2 + hstep, voffB);
;             PG8_WAIT_V(6); PG8_BAR; PG8_MMA(1, 1, At, B1); PG8_BAR;
;             PG8_LDB(B0, 1, 0); PG8_SCHED; PG8_LDA(At, 1, 0); PG8_STAGE(PG8_SA(0, 1), a2 + hstep, voffA);
;             PG8_WAIT_L(8); PG8_BAR; PG8_WAIT_L(0); PG8_MMA(0, 0, At, B0); PG8_BAR; PG8_SCHED;
;             PG8_LDB(B1, 1, 1); PG8_STAGE(PG8_SB(1, 0), b3, voffB);
;             PG8_BAR; PG8_WAIT_L(0); PG8_MMA(0, 1, At, B1); PG8_BAR;
;             PG8_LDA(At, 1, 1); PG8_STAGE(PG8_SA(1, 0), a3, voffA);
	s_add_u32 s24, s20, 0x80000
	s_addc_u32 s25, s21, 0
	s_add_i32 s27, s54, s36
	s_mov_b32 m0, s27
	s_nop 0
	global_load_lds_dwordx4 v130, s[24:25]
	s_add_i32 m0, s27, 0x2000
	s_nop 0
	global_load_lds_dwordx4 v134, s[24:25]
	s_waitcnt vmcnt(6)
	s_barrier
	s_setprio 1
	v_mfma_f32_16x16x32_bf16 v[56:59], v[202:205], v[166:169], v[56:59]
	v_mfma_f32_16x16x32_bf16 v[48:51], v[210:213], v[166:169], v[48:51]
	v_mfma_f32_16x16x32_bf16 v[40:43], v[202:205], v[174:177], v[40:43]
	v_mfma_f32_16x16x32_bf16 v[32:35], v[210:213], v[174:177], v[32:35]
	v_mfma_f32_16x16x32_bf16 v[24:27], v[202:205], v[186:189], v[24:27]
	v_mfma_f32_16x16x32_bf16 v[16:19], v[210:213], v[186:189], v[16:19]
	v_mfma_f32_16x16x32_bf16 v[8:11], v[202:205], v[194:197], v[8:11]
	v_mfma_f32_16x16x32_bf16 v[0:3], v[210:213], v[194:197], v[0:3]
	v_mfma_f32_16x16x32_bf16 v[56:59], v[206:209], v[170:173], v[56:59]
	v_mfma_f32_16x16x32_bf16 v[48:51], v[214:217], v[170:173], v[48:51]
	v_mfma_f32_16x16x32_bf16 v[40:43], v[206:209], v[182:185], v[40:43]
	v_mfma_f32_16x16x32_bf16 v[32:35], v[214:217], v[182:185], v[32:35]
	v_mfma_f32_16x16x32_bf16 v[24:27], v[206:209], v[190:193], v[24:27]
	v_mfma_f32_16x16x32_bf16 v[16:19], v[214:217], v[190:193], v[16:19]
	v_mfma_f32_16x16x32_bf16 v[8:11], v[206:209], v[198:201], v[8:11]
	v_mfma_f32_16x16x32_bf16 v[0:3], v[214:217], v[198:201], v[0:3]
	s_setprio 0
	s_add_i32 s24, 0, 0x18000
	v_add_u32_e32 v162, s24, v149
	s_barrier
	ds_read_b128 v[144:147], v162
	ds_read_b128 v[154:157], v162 offset:1024
	ds_read_b128 v[158:161], v162 offset:2048
	ds_read_b128 v[162:165], v162 offset:3072
	s_add_u32 s22, s22, 0x80000
	s_addc_u32 s23, s23, 0
	s_mov_b32 m0, s42
	ds_read_b128 v[166:169], v152 offset:32768
	ds_read_b128 v[170:173], v152 offset:33792
	ds_read_b128 v[174:177], v152 offset:34816
	ds_read_b128 v[182:185], v152 offset:35840
	ds_read_b128 v[186:189], v152 offset:36864
	ds_read_b128 v[190:193], v152 offset:37888
	ds_read_b128 v[194:197], v152 offset:38912
	ds_read_b128 v[198:201], v152 offset:39936
	global_load_lds_dwordx4 v128, s[22:23]
	s_mov_b32 m0, s43
	s_nop 0
	global_load_lds_dwordx4 v132, s[22:23]
	s_waitcnt lgkmcnt(8)
	s_barrier
	s_waitcnt lgkmcnt(0)
	s_setprio 1
	s_waitcnt lgkmcnt(0)
	v_mfma_f32_16x16x32_bf16 v[124:127], v[144:147], v[166:169], v[124:127]
	v_mfma_f32_16x16x32_bf16 v[116:119], v[158:161], v[166:169], v[116:119]
	v_mfma_f32_16x16x32_bf16 v[108:111], v[144:147], v[174:177], v[108:111]
	v_mfma_f32_16x16x32_bf16 v[100:103], v[158:161], v[174:177], v[100:103]
	v_mfma_f32_16x16x32_bf16 v[92:95], v[144:147], v[186:189], v[92:95]
	v_mfma_f32_16x16x32_bf16 v[84:87], v[158:161], v[186:189], v[84:87]
	v_mfma_f32_16x16x32_bf16 v[76:79], v[144:147], v[194:197], v[76:79]
	v_mfma_f32_16x16x32_bf16 v[68:71], v[158:161], v[194:197], v[68:71]
	v_mfma_f32_16x16x32_bf16 v[124:127], v[154:157], v[170:173], v[124:127]
	v_mfma_f32_16x16x32_bf16 v[116:119], v[162:165], v[170:173], v[116:119]
	v_mfma_f32_16x16x32_bf16 v[108:111], v[154:157], v[182:185], v[108:111]
	v_mfma_f32_16x16x32_bf16 v[100:103], v[162:165], v[182:185], v[100:103]
	v_mfma_f32_16x16x32_bf16 v[92:95], v[154:157], v[190:193], v[92:95]
	v_mfma_f32_16x16x32_bf16 v[84:87], v[162:165], v[190:193], v[84:87]
	v_mfma_f32_16x16x32_bf16 v[76:79], v[154:157], v[198:201], v[76:79]
	v_mfma_f32_16x16x32_bf16 v[68:71], v[162:165], v[198:201], v[68:71]
	s_setprio 0
	s_barrier
	s_add_i32 s22, 0, 0x1c000
	s_add_i32 s23, s24, s36
	v_add_u32_e32 v181, s22, v149
	v_lshl_add_u64 v[178:179], v[178:179], 0, s[6:7]
	s_mov_b32 m0, s23
	ds_read_b128 v[202:205], v181
	ds_read_b128 v[206:209], v181 offset:1024
	ds_read_b128 v[210:213], v181 offset:2048
	ds_read_b128 v[214:217], v181 offset:3072
	global_load_lds_dwordx4 v[178:179], off
	v_lshl_add_u64 v[178:179], v[218:219], 0, s[6:7]
	s_add_i32 m0, s23, 0x2000
	s_nop 0
	global_load_lds_dwordx4 v[178:179], off
	s_barrier
	s_waitcnt lgkmcnt(0)
	s_setprio 1
	s_waitcnt lgkmcnt(0)
	v_mfma_f32_16x16x32_bf16 v[120:123], v[202:205], v[166:169], v[120:123]
	v_mfma_f32_16x16x32_bf16 v[112:115], v[210:213], v[166:169], v[112:115]
	v_mfma_f32_16x16x32_bf16 v[104:107], v[202:205], v[174:177], v[104:107]
	v_mfma_f32_16x16x32_bf16 v[96:99], v[210:213], v[174:177], v[96:99]
	v_mfma_f32_16x16x32_bf16 v[88:91], v[202:205], v[186:189], v[88:91]
	v_mfma_f32_16x16x32_bf16 v[80:83], v[210:213], v[186:189], v[80:83]
	v_mfma_f32_16x16x32_bf16 v[72:75], v[202:205], v[194:197], v[72:75]
	v_mfma_f32_16x16x32_bf16 v[64:67], v[210:213], v[194:197], v[64:67]
	v_mfma_f32_16x16x32_bf16 v[120:123], v[206:209], v[170:173], v[120:123]
	v_mfma_f32_16x16x32_bf16 v[112:115], v[214:217], v[170:173], v[112:115]
	v_mfma_f32_16x16x32_bf16 v[104:107], v[206:209], v[182:185], v[104:107]
	v_mfma_f32_16x16x32_bf16 v[96:99], v[214:217], v[182:185], v[96:99]
	v_mfma_f32_16x16x32_bf16 v[88:91], v[206:209], v[190:193], v[88:91]
	v_mfma_f32_16x16x32_bf16 v[80:83], v[214:217], v[190:193], v[80:83]
	v_mfma_f32_16x16x32_bf16 v[72:75], v[206:209], v[198:201], v[72:75]
	v_mfma_f32_16x16x32_bf16 v[64:67], v[214:217], v[198:201], v[64:67]
	s_setprio 0
	s_mov_b32 m0, s46
	v_lshl_add_u64 v[178:179], v[220:221], 0, s[6:7]
	s_barrier
	ds_read_b128 v[166:169], v152 offset:49152
	ds_read_b128 v[170:173], v152 offset:50176
	ds_read_b128 v[174:177], v152 offset:51200
	ds_read_b128 v[182:185], v152 offset:52224
	ds_read_b128 v[186:189], v152 offset:53248
	ds_read_b128 v[190:193], v152 offset:54272
	ds_read_b128 v[194:197], v152 offset:55296
	ds_read_b128 v[198:201], v152 offset:56320
	global_load_lds_dwordx4 v[178:179], off
	v_lshl_add_u64 v[178:179], v[222:223], 0, s[6:7]
	s_mov_b32 m0, s47
	s_nop 0
	global_load_lds_dwordx4 v[178:179], off
	s_barrier
; __device__ __forceinline__ unsigned cvt_pk_bf16(float lo, float hi) { const f32x2 v = (f32x2){lo, hi}; const bf16v2 b = __builtin_convertvector(v, bf16v2); return __builtin_bit_cast(unsigned, b); }
; __device__ __forceinline__ float siluf(float x) { return x * sigm(x); }
; #define PG8_STAGE(bufoff, gbase, voff) do { _Pragma("unroll") for (int _i = 0; _i < 2; ++_i) \
;         __builtin_amdgcn_global_load_lds((const unsigned*)((const char*)(gbase) + (voff)[_i]), (LAS unsigned*)(lds + (bufoff) + ldsw + _i * 8192), 16, 0, 0); } while (0)
; #define PG8_MMA(ai, bj, At, Bt) do { __builtin_amdgcn_s_setprio(1); _Pragma("unroll") for (int m = 0; m < 4; ++m) _Pragma("unroll") for (int n = 0; n < 2; ++n) _Pragma("unroll") for (int k = 0; k < 2; ++k) \
;         acc[ai][bj][m][n] = __builtin_amdgcn_mfma_f32_16x16x32_bf16(Bt[n][k], At[m][k], acc[ai][bj][m][n], 0, 0, 0); __builtin_amdgcn_s_setprio(0); } while (0)
; #define PG8_WAIT_V(n) asm volatile("s_waitcnt vmcnt(" #n ")" ::: "memory")
; #define PG8_WAIT_L(n) asm volatile("s_waitcnt lgkmcnt(" #n ")" ::: "memory")
; #define PG8_BAR __builtin_amdgcn_s_barrier()
; #define PG8_SCHED __builtin_amdgcn_sched_barrier(0)
; template <class Epi, class Order>
; __device__ __forceinline__ void gemm_phase(LAS unsigned char* lds, const Gemm g, const Order& S, const Epi& E) {
;     ...
;             PG8_BAR; PG8_WAIT_L(0); PG8_MMA(1, 0, At, B0); PG8_BAR; PG8_SCHED;
;             PG8_STAGE(PG8_SB(1, 1), b3 + hstep, voffB);
;             PG8_WAIT_V(6); PG8_BAR; PG8_MMA(1, 1, At, B1); PG8_BAR;
;         }
;         E(acc, cur, wr, wc, fr, fq);
;     __device__ __forceinline__ void operator()(const f32x4 (&acc)[2][2][4][2], const pg8::Unit& u, int wr, int wc, int fr, int fq) const {
;     ...
;                 bf16_t* rowp = O + (size_t)(row0 + ai * 128 + m * 16) * DFF + col0;
;                 const f32x4 g0 = acc[ai][0][m][0], g1 = acc[ai][0][m][1], u0 = acc[ai][1][m][0], u1 = acc[ai][1][m][1];
;                 u32x4 w;
;                 w.x = cvt_pk_bf16(siluf(g0[0]) * u0[0], siluf(g0[1]) * u0[1]); w.y = cvt_pk_bf16(siluf(g0[2]) * u0[2], siluf(g0[3]) * u0[3]);
;                 w.z = cvt_pk_bf16(siluf(g1[0]) * u1[0], siluf(g1[1]) * u1[1]); w.w = cvt_pk_bf16(siluf(g1[2]) * u1[2], siluf(g1[3]) * u1[3]);
;                 *(u32x4*)rowp = w;
	s_waitcnt lgkmcnt(0)
	s_setprio 1
	s_waitcnt lgkmcnt(0)
	v_mfma_f32_16x16x32_bf16 v[60:63], v[144:147], v[166:169], v[60:63]
	v_mfma_f32_16x16x32_bf16 v[52:55], v[158:161], v[166:169], v[52:55]
	v_mfma_f32_16x16x32_bf16 v[44:47], v[144:147], v[174:177], v[44:47]
	v_mfma_f32_16x16x32_bf16 v[36:39], v[158:161], v[174:177], v[36:39]
	v_mfma_f32_16x16x32_bf16 v[28:31], v[144:147], v[186:189], v[28:31]
	v_mfma_f32_16x16x32_bf16 v[20:23], v[158:161], v[186:189], v[20:23]
	v_mfma_f32_16x16x32_bf16 v[12:15], v[144:147], v[194:197], v[12:15]
	v_mfma_f32_16x16x32_bf16 v[4:7], v[158:161], v[194:197], v[4:7]
	v_mfma_f32_16x16x32_bf16 v[60:63], v[154:157], v[170:173], v[60:63]
	v_mfma_f32_16x16x32_bf16 v[52:55], v[162:165], v[170:173], v[52:55]
	v_mfma_f32_16x16x32_bf16 v[44:47], v[154:157], v[182:185], v[44:47]
	v_mfma_f32_16x16x32_bf16 v[36:39], v[162:165], v[182:185], v[36:39]
	v_mfma_f32_16x16x32_bf16 v[28:31], v[154:157], v[190:193], v[28:31]
	v_mfma_f32_16x16x32_bf16 v[20:23], v[162:165], v[190:193], v[20:23]
	v_mfma_f32_16x16x32_bf16 v[12:15], v[154:157], v[198:201], v[12:15]
	v_mfma_f32_16x16x32_bf16 v[4:7], v[162:165], v[198:201], v[4:7]
	s_setprio 0
	s_barrier
	s_add_u32 s20, s20, 0x80080
	s_addc_u32 s21, s21, 0
	s_add_i32 s22, s22, s36
	s_mov_b32 m0, s22
	s_nop 0
	global_load_lds_dwordx4 v130, s[20:21]
	v_lshl_add_u64 v[144:145], s[20:21], 0, v[134:135]
	s_add_i32 m0, s22, 0x2000
	s_nop 0
	global_load_lds_dwordx4 v[144:145], off
	s_waitcnt vmcnt(6)
	s_barrier
	s_setprio 1
	v_mfma_f32_16x16x32_bf16 v[56:59], v[202:205], v[166:169], v[56:59]
	v_mfma_f32_16x16x32_bf16 v[48:51], v[210:213], v[166:169], v[48:51]
	v_mfma_f32_16x16x32_bf16 v[40:43], v[202:205], v[174:177], v[40:43]
	v_mfma_f32_16x16x32_bf16 v[32:35], v[210:213], v[174:177], v[32:35]
	v_mfma_f32_16x16x32_bf16 v[24:27], v[202:205], v[186:189], v[24:27]
	v_mfma_f32_16x16x32_bf16 v[16:19], v[210:213], v[186:189], v[16:19]
	v_mfma_f32_16x16x32_bf16 v[8:11], v[202:205], v[194:197], v[8:11]
	v_mfma_f32_16x16x32_bf16 v[0:3], v[210:213], v[194:197], v[0:3]
	v_mfma_f32_16x16x32_bf16 v[56:59], v[206:209], v[170:173], v[56:59]
	v_mfma_f32_16x16x32_bf16 v[48:51], v[214:217], v[170:173], v[48:51]
	v_mfma_f32_16x16x32_bf16 v[40:43], v[206:209], v[182:185], v[40:43]
	v_mfma_f32_16x16x32_bf16 v[32:35], v[214:217], v[182:185], v[32:35]
	v_mfma_f32_16x16x32_bf16 v[24:27], v[206:209], v[190:193], v[24:27]
	v_mfma_f32_16x16x32_bf16 v[16:19], v[214:217], v[190:193], v[16:19]
	v_mfma_f32_16x16x32_bf16 v[8:11], v[206:209], v[198:201], v[8:11]
	v_mfma_f32_16x16x32_bf16 v[0:3], v[214:217], v[198:201], v[0:3]
	s_setprio 0
	s_add_i32 s61, s61, 2
	s_add_u32 s18, s18, 0x100
	s_addc_u32 s19, s19, 0
	s_add_u32 s59, s59, 0x100
	s_addc_u32 s60, s60, 0
	s_cmp_gt_u32 s61, 29
	s_barrier
	s_cbranch_scc0 .LBB0_1141
	v_mul_f32_e32 v155, 0xbfb8aa3b, v124
	v_exp_f32_e32 v155, v155
	v_mul_f32_e32 v158, 0xbfb8aa3b, v125
	v_exp_f32_e32 v159, v158
	v_lshl_add_u32 v154, s16, 8, v148
	v_add_f32_e32 v155, 1.0, v155
	v_rcp_f32_e32 v158, v155
	v_add_f32_e32 v155, 1.0, v159
	v_mul_f32_e32 v159, 0xbfb8aa3b, v126
	v_exp_f32_e32 v160, v159
	v_mul_f32_e32 v159, 0xbfb8aa3b, v127
	v_exp_f32_e32 v161, v159
	v_rcp_f32_e32 v159, v155
	v_add_f32_e32 v155, 1.0, v160
	v_rcp_f32_e32 v160, v155
	v_add_f32_e32 v155, 1.0, v161
	v_rcp_f32_e32 v161, v155
	v_pk_mul_f32 v[124:125], v[124:125], v[158:159]
	v_lshl_or_b32 v144, s56, 7, v150
	v_pk_mul_f32 v[120:121], v[124:125], v[120:121]
	v_pk_mul_f32 v[124:125], v[126:127], v[160:161]
	v_cvt_pk_bf16_f32 v120, v120, v121
	v_mul_f32_e32 v121, 0xbfb8aa3b, v116
	v_pk_mul_f32 v[122:123], v[124:125], v[122:123]
	v_exp_f32_e32 v124, v121
	v_mul_f32_e32 v121, 0xbfb8aa3b, v117
	v_exp_f32_e32 v125, v121
	v_cvt_pk_bf16_f32 v121, v122, v123
	v_add_f32_e32 v122, 1.0, v124
	v_mul_f32_e32 v124, 0xbfb8aa3b, v118
	v_add_f32_e32 v123, 1.0, v125
	v_mul_f32_e32 v125, 0xbfb8aa3b, v119
	v_exp_f32_e32 v124, v124
	v_exp_f32_e32 v125, v125
	v_rcp_f32_e32 v122, v122
	v_rcp_f32_e32 v123, v123
	v_add_f32_e32 v124, 1.0, v124
	v_add_f32_e32 v125, 1.0, v125
	v_rcp_f32_e32 v124, v124
	v_rcp_f32_e32 v125, v125
	v_pk_mul_f32 v[116:117], v[116:117], v[122:123]
	v_ashrrev_i32_e32 v145, 31, v144
	v_pk_mul_f32 v[112:113], v[116:117], v[112:113]
	v_mul_f32_e32 v116, 0xbfb8aa3b, v110
	v_cvt_pk_bf16_f32 v122, v112, v113
	v_pk_mul_f32 v[112:113], v[118:119], v[124:125]
	v_mul_f32_e32 v117, 0xbfb8aa3b, v111
	v_pk_mul_f32 v[112:113], v[112:113], v[114:115]
	v_mul_f32_e32 v114, 0xbfb8aa3b, v108
	v_mul_f32_e32 v115, 0xbfb8aa3b, v109
	v_exp_f32_e32 v114, v114
	v_exp_f32_e32 v115, v115
	v_exp_f32_e32 v116, v116
	v_exp_f32_e32 v117, v117
	v_add_f32_e32 v114, 1.0, v114
	v_add_f32_e32 v115, 1.0, v115
	v_rcp_f32_e32 v114, v114
	v_rcp_f32_e32 v115, v115
	v_add_f32_e32 v116, 1.0, v116
	v_add_f32_e32 v117, 1.0, v117
	v_rcp_f32_e32 v116, v116
	v_rcp_f32_e32 v117, v117
	v_pk_mul_f32 v[108:109], v[108:109], v[114:115]
	v_mov_b64_e32 v[146:147], s[4:5]
	v_pk_mul_f32 v[104:105], v[108:109], v[104:105]
	v_pk_mul_f32 v[108:109], v[110:111], v[116:117]
	v_cvt_pk_bf16_f32 v104, v104, v105
	v_mul_f32_e32 v105, 0xbfb8aa3b, v100
	v_pk_mul_f32 v[106:107], v[108:109], v[106:107]
	v_exp_f32_e32 v108, v105
	v_mul_f32_e32 v105, 0xbfb8aa3b, v101
	v_exp_f32_e32 v109, v105
	v_cvt_pk_bf16_f32 v105, v106, v107
	v_add_f32_e32 v106, 1.0, v108
	v_mul_f32_e32 v108, 0xbfb8aa3b, v102
	v_add_f32_e32 v107, 1.0, v109
	v_mul_f32_e32 v109, 0xbfb8aa3b, v103
	v_exp_f32_e32 v108, v108
	v_exp_f32_e32 v109, v109
	v_rcp_f32_e32 v106, v106
	v_rcp_f32_e32 v107, v107
	v_add_f32_e32 v108, 1.0, v108
	v_add_f32_e32 v109, 1.0, v109
	v_rcp_f32_e32 v108, v108
	v_rcp_f32_e32 v109, v109
; __device__ __forceinline__ unsigned cvt_pk_bf16(float lo, float hi) { const f32x2 v = (f32x2){lo, hi}; const bf16v2 b = __builtin_convertvector(v, bf16v2); return __builtin_bit_cast(unsigned, b); }
; __device__ __forceinline__ float siluf(float x) { return x * sigm(x); }
;     __device__ __forceinline__ void operator()(const f32x4 (&acc)[2][2][4][2], const pg8::Unit& u, int wr, int wc, int fr, int fq) const {
;     ...
;                 bf16_t* rowp = O + (size_t)(row0 + ai * 128 + m * 16) * DFF + col0;
;                 const f32x4 g0 = acc[ai][0][m][0], g1 = acc[ai][0][m][1], u0 = acc[ai][1][m][0], u1 = acc[ai][1][m][1];
;                 u32x4 w;
;                 w.x = cvt_pk_bf16(siluf(g0[0]) * u0[0], siluf(g0[1]) * u0[1]); w.y = cvt_pk_bf16(siluf(g0[2]) * u0[2], siluf(g0[3]) * u0[3]);
;                 w.z = cvt_pk_bf16(siluf(g1[0]) * u1[0], siluf(g1[1]) * u1[1]); w.w = cvt_pk_bf16(siluf(g1[2]) * u1[2], siluf(g1[3]) * u1[3]);
;                 *(u32x4*)rowp = w;
	v_pk_mul_f32 v[100:101], v[100:101], v[106:107]
	v_cvt_pk_bf16_f32 v123, v112, v113
	v_pk_mul_f32 v[96:97], v[100:101], v[96:97]
	v_mul_f32_e32 v100, 0xbfb8aa3b, v94
	v_cvt_pk_bf16_f32 v106, v96, v97
	v_pk_mul_f32 v[96:97], v[102:103], v[108:109]
	v_mul_f32_e32 v101, 0xbfb8aa3b, v95
	v_pk_mul_f32 v[96:97], v[96:97], v[98:99]
	v_mul_f32_e32 v98, 0xbfb8aa3b, v92
	v_mul_f32_e32 v99, 0xbfb8aa3b, v93
	v_exp_f32_e32 v98, v98
	v_exp_f32_e32 v99, v99
	v_exp_f32_e32 v100, v100
	v_exp_f32_e32 v101, v101
	v_add_f32_e32 v98, 1.0, v98
	v_add_f32_e32 v99, 1.0, v99
	v_rcp_f32_e32 v98, v98
	v_rcp_f32_e32 v99, v99
	v_add_f32_e32 v100, 1.0, v100
	v_add_f32_e32 v101, 1.0, v101
	v_rcp_f32_e32 v100, v100
	v_rcp_f32_e32 v101, v101
	v_pk_mul_f32 v[92:93], v[92:93], v[98:99]
	v_or_b32_e32 v112, 16, v154
	v_pk_mul_f32 v[88:89], v[92:93], v[88:89]
	v_pk_mul_f32 v[92:93], v[94:95], v[100:101]
	v_cvt_pk_bf16_f32 v88, v88, v89
	v_mul_f32_e32 v89, 0xbfb8aa3b, v84
	v_pk_mul_f32 v[90:91], v[92:93], v[90:91]
	v_exp_f32_e32 v92, v89
	v_mul_f32_e32 v89, 0xbfb8aa3b, v85
	v_exp_f32_e32 v93, v89
	v_cvt_pk_bf16_f32 v89, v90, v91
	v_add_f32_e32 v90, 1.0, v92
	v_mul_f32_e32 v92, 0xbfb8aa3b, v86
	v_add_f32_e32 v91, 1.0, v93
	v_mul_f32_e32 v93, 0xbfb8aa3b, v87
	v_exp_f32_e32 v92, v92
	v_exp_f32_e32 v93, v93
	v_rcp_f32_e32 v90, v90
	v_rcp_f32_e32 v91, v91
	v_add_f32_e32 v92, 1.0, v92
	v_add_f32_e32 v93, 1.0, v93
	v_rcp_f32_e32 v92, v92
	v_rcp_f32_e32 v93, v93
	v_pk_mul_f32 v[84:85], v[84:85], v[90:91]
	v_cvt_pk_bf16_f32 v107, v96, v97
	v_pk_mul_f32 v[80:81], v[84:85], v[80:81]
	v_mul_f32_e32 v84, 0xbfb8aa3b, v78
	v_cvt_pk_bf16_f32 v90, v80, v81
	v_pk_mul_f32 v[80:81], v[86:87], v[92:93]
	v_mul_f32_e32 v85, 0xbfb8aa3b, v79
	v_pk_mul_f32 v[80:81], v[80:81], v[82:83]
	v_mul_f32_e32 v82, 0xbfb8aa3b, v76
	v_mul_f32_e32 v83, 0xbfb8aa3b, v77
	v_exp_f32_e32 v82, v82
	v_exp_f32_e32 v83, v83
	v_exp_f32_e32 v84, v84
	v_exp_f32_e32 v85, v85
	v_add_f32_e32 v82, 1.0, v82
	v_add_f32_e32 v83, 1.0, v83
	v_rcp_f32_e32 v82, v82
	v_rcp_f32_e32 v83, v83
	v_add_f32_e32 v84, 1.0, v84
	v_add_f32_e32 v85, 1.0, v85
	v_rcp_f32_e32 v84, v84
	v_rcp_f32_e32 v85, v85
	v_pk_mul_f32 v[76:77], v[76:77], v[82:83]
	v_or_b32_e32 v96, 32, v154
	v_pk_mul_f32 v[72:73], v[76:77], v[72:73]
	v_pk_mul_f32 v[76:77], v[78:79], v[84:85]
	v_cvt_pk_bf16_f32 v72, v72, v73
	v_mul_f32_e32 v73, 0xbfb8aa3b, v68
	v_pk_mul_f32 v[74:75], v[76:77], v[74:75]
	v_exp_f32_e32 v76, v73
	v_mul_f32_e32 v73, 0xbfb8aa3b, v69
	v_exp_f32_e32 v77, v73
	v_cvt_pk_bf16_f32 v73, v74, v75
	v_add_f32_e32 v74, 1.0, v76
	v_mul_f32_e32 v76, 0xbfb8aa3b, v70
	v_add_f32_e32 v75, 1.0, v77
	v_mul_f32_e32 v77, 0xbfb8aa3b, v71
	v_exp_f32_e32 v76, v76
	v_exp_f32_e32 v77, v77
	v_rcp_f32_e32 v74, v74
	v_rcp_f32_e32 v75, v75
	v_add_f32_e32 v76, 1.0, v76
	v_add_f32_e32 v77, 1.0, v77
	v_rcp_f32_e32 v76, v76
	v_rcp_f32_e32 v77, v77
	v_pk_mul_f32 v[68:69], v[68:69], v[74:75]
	v_cvt_pk_bf16_f32 v91, v80, v81
	v_pk_mul_f32 v[64:65], v[68:69], v[64:65]
	v_mul_f32_e32 v68, 0xbfb8aa3b, v62
	v_cvt_pk_bf16_f32 v74, v64, v65
	v_pk_mul_f32 v[64:65], v[70:71], v[76:77]
	v_mul_f32_e32 v69, 0xbfb8aa3b, v63
	v_pk_mul_f32 v[64:65], v[64:65], v[66:67]
	v_mul_f32_e32 v66, 0xbfb8aa3b, v60
	v_mul_f32_e32 v67, 0xbfb8aa3b, v61
	v_exp_f32_e32 v66, v66
	v_exp_f32_e32 v67, v67
	v_exp_f32_e32 v68, v68
	v_exp_f32_e32 v69, v69
	v_add_f32_e32 v66, 1.0, v66
	v_add_f32_e32 v67, 1.0, v67
	v_rcp_f32_e32 v66, v66
	v_rcp_f32_e32 v67, v67
	v_add_f32_e32 v68, 1.0, v68
	v_add_f32_e32 v69, 1.0, v69
	v_rcp_f32_e32 v68, v68
	v_rcp_f32_e32 v69, v69
	v_pk_mul_f32 v[60:61], v[60:61], v[66:67]
	v_or_b32_e32 v80, 48, v154
	v_pk_mul_f32 v[56:57], v[60:61], v[56:57]
	v_pk_mul_f32 v[60:61], v[62:63], v[68:69]
	v_cvt_pk_bf16_f32 v56, v56, v57
	v_mul_f32_e32 v57, 0xbfb8aa3b, v52
	v_pk_mul_f32 v[58:59], v[60:61], v[58:59]
	v_exp_f32_e32 v60, v57
	v_mul_f32_e32 v57, 0xbfb8aa3b, v53
	v_exp_f32_e32 v61, v57
	v_cvt_pk_bf16_f32 v57, v58, v59
	v_add_f32_e32 v58, 1.0, v60
	v_mul_f32_e32 v60, 0xbfb8aa3b, v54
	v_add_f32_e32 v59, 1.0, v61
	v_mul_f32_e32 v61, 0xbfb8aa3b, v55
	v_exp_f32_e32 v60, v60
	v_exp_f32_e32 v61, v61
	v_rcp_f32_e32 v58, v58
	v_rcp_f32_e32 v59, v59
	v_add_f32_e32 v60, 1.0, v60
	v_add_f32_e32 v61, 1.0, v61
	v_rcp_f32_e32 v60, v60
	v_rcp_f32_e32 v61, v61
	v_pk_mul_f32 v[52:53], v[52:53], v[58:59]
	v_cvt_pk_bf16_f32 v75, v64, v65
	v_pk_mul_f32 v[48:49], v[52:53], v[48:49]
	v_mul_f32_e32 v52, 0xbfb8aa3b, v46
	v_cvt_pk_bf16_f32 v58, v48, v49
	v_pk_mul_f32 v[48:49], v[54:55], v[60:61]
	v_mul_f32_e32 v53, 0xbfb8aa3b, v47
	v_pk_mul_f32 v[48:49], v[48:49], v[50:51]
	v_mul_f32_e32 v50, 0xbfb8aa3b, v44
	v_mul_f32_e32 v51, 0xbfb8aa3b, v45
	v_exp_f32_e32 v50, v50
	v_exp_f32_e32 v51, v51
	v_exp_f32_e32 v52, v52
	v_exp_f32_e32 v53, v53
	v_add_f32_e32 v50, 1.0, v50
	v_add_f32_e32 v51, 1.0, v51
	v_rcp_f32_e32 v50, v50
	v_rcp_f32_e32 v51, v51
	v_add_f32_e32 v52, 1.0, v52
	v_add_f32_e32 v53, 1.0, v53
	v_rcp_f32_e32 v52, v52
	v_rcp_f32_e32 v53, v53
	v_pk_mul_f32 v[44:45], v[44:45], v[50:51]
	v_add_u32_e32 v64, 0x80, v154
	v_pk_mul_f32 v[40:41], v[44:45], v[40:41]
	v_pk_mul_f32 v[44:45], v[46:47], v[52:53]
	v_cvt_pk_bf16_f32 v40, v40, v41
; __device__ __forceinline__ unsigned cvt_pk_bf16(float lo, float hi) { const f32x2 v = (f32x2){lo, hi}; const bf16v2 b = __builtin_convertvector(v, bf16v2); return __builtin_bit_cast(unsigned, b); }
; __device__ __forceinline__ float siluf(float x) { return x * sigm(x); }
; #define PG8_WAIT_V(n) asm volatile("s_waitcnt vmcnt(" #n ")" ::: "memory")
; #define PG8_BAR __builtin_amdgcn_s_barrier()
; template <class Epi, class Order>
; __device__ __forceinline__ void gemm_phase(LAS unsigned char* lds, const Gemm g, const Order& S, const Epi& E) {
;     ...
;         if (!has_next) break;
; #pragma unroll
;         for (int a = 0; a < 2; ++a)
; #pragma unroll
;             for (int b = 0; b < 2; ++b)
; #pragma unroll
;                 for (int m = 0; m < 4; ++m)
; #pragma unroll
;                     for (int n = 0; n < 2; ++n) acc[a][b][m][n] = (f32x4){0.f, 0.f, 0.f, 0.f};
;         cur = nxt; cA = nA; cB = nB; ++ui;
;     }
;     PG8_WAIT_V(0);
;     if (wr == 0) PG8_BAR;
;     PG8_BAR;
;     __device__ __forceinline__ void operator()(const f32x4 (&acc)[2][2][4][2], const pg8::Unit& u, int wr, int wc, int fr, int fq) const {
;     ...
;                 bf16_t* rowp = O + (size_t)(row0 + ai * 128 + m * 16) * DFF + col0;
;                 const f32x4 g0 = acc[ai][0][m][0], g1 = acc[ai][0][m][1], u0 = acc[ai][1][m][0], u1 = acc[ai][1][m][1];
;                 u32x4 w;
;                 w.x = cvt_pk_bf16(siluf(g0[0]) * u0[0], siluf(g0[1]) * u0[1]); w.y = cvt_pk_bf16(siluf(g0[2]) * u0[2], siluf(g0[3]) * u0[3]);
;                 w.z = cvt_pk_bf16(siluf(g1[0]) * u1[0], siluf(g1[1]) * u1[1]); w.w = cvt_pk_bf16(siluf(g1[2]) * u1[2], siluf(g1[3]) * u1[3]);
;                 *(u32x4*)rowp = w;
	v_mul_f32_e32 v41, 0xbfb8aa3b, v36
	v_pk_mul_f32 v[42:43], v[44:45], v[42:43]
	v_exp_f32_e32 v44, v41
	v_mul_f32_e32 v41, 0xbfb8aa3b, v37
	v_exp_f32_e32 v45, v41
	v_cvt_pk_bf16_f32 v41, v42, v43
	v_add_f32_e32 v42, 1.0, v44
	v_mul_f32_e32 v44, 0xbfb8aa3b, v38
	v_add_f32_e32 v43, 1.0, v45
	v_mul_f32_e32 v45, 0xbfb8aa3b, v39
	v_exp_f32_e32 v44, v44
	v_exp_f32_e32 v45, v45
	v_rcp_f32_e32 v42, v42
	v_rcp_f32_e32 v43, v43
	v_add_f32_e32 v44, 1.0, v44
	v_add_f32_e32 v45, 1.0, v45
	v_rcp_f32_e32 v44, v44
	v_rcp_f32_e32 v45, v45
	v_pk_mul_f32 v[36:37], v[36:37], v[42:43]
	v_cvt_pk_bf16_f32 v59, v48, v49
	v_pk_mul_f32 v[32:33], v[36:37], v[32:33]
	v_mul_f32_e32 v36, 0xbfb8aa3b, v30
	v_cvt_pk_bf16_f32 v42, v32, v33
	v_pk_mul_f32 v[32:33], v[38:39], v[44:45]
	v_mul_f32_e32 v37, 0xbfb8aa3b, v31
	v_pk_mul_f32 v[32:33], v[32:33], v[34:35]
	v_mul_f32_e32 v34, 0xbfb8aa3b, v28
	v_mul_f32_e32 v35, 0xbfb8aa3b, v29
	v_exp_f32_e32 v34, v34
	v_exp_f32_e32 v35, v35
	v_exp_f32_e32 v36, v36
	v_exp_f32_e32 v37, v37
	v_add_f32_e32 v34, 1.0, v34
	v_add_f32_e32 v35, 1.0, v35
	v_rcp_f32_e32 v34, v34
	v_rcp_f32_e32 v35, v35
	v_add_f32_e32 v36, 1.0, v36
	v_add_f32_e32 v37, 1.0, v37
	v_rcp_f32_e32 v36, v36
	v_rcp_f32_e32 v37, v37
	v_pk_mul_f32 v[28:29], v[28:29], v[34:35]
	v_add_u32_e32 v48, 0x90, v154
	v_pk_mul_f32 v[24:25], v[28:29], v[24:25]
	v_pk_mul_f32 v[28:29], v[30:31], v[36:37]
	v_cvt_pk_bf16_f32 v24, v24, v25
	v_mul_f32_e32 v25, 0xbfb8aa3b, v20
	v_pk_mul_f32 v[26:27], v[28:29], v[26:27]
	v_exp_f32_e32 v28, v25
	v_mul_f32_e32 v25, 0xbfb8aa3b, v21
	v_exp_f32_e32 v29, v25
	v_cvt_pk_bf16_f32 v25, v26, v27
	v_add_f32_e32 v26, 1.0, v28
	v_mul_f32_e32 v28, 0xbfb8aa3b, v22
	v_add_f32_e32 v27, 1.0, v29
	v_mul_f32_e32 v29, 0xbfb8aa3b, v23
	v_exp_f32_e32 v28, v28
	v_exp_f32_e32 v29, v29
	v_rcp_f32_e32 v26, v26
	v_rcp_f32_e32 v27, v27
	v_add_f32_e32 v28, 1.0, v28
	v_add_f32_e32 v29, 1.0, v29
	v_rcp_f32_e32 v28, v28
	v_rcp_f32_e32 v29, v29
	v_pk_mul_f32 v[20:21], v[20:21], v[26:27]
	v_cvt_pk_bf16_f32 v43, v32, v33
	v_pk_mul_f32 v[16:17], v[20:21], v[16:17]
	v_mul_f32_e32 v20, 0xbfb8aa3b, v14
	v_cvt_pk_bf16_f32 v26, v16, v17
	v_pk_mul_f32 v[16:17], v[22:23], v[28:29]
	v_mul_f32_e32 v21, 0xbfb8aa3b, v15
	v_pk_mul_f32 v[16:17], v[16:17], v[18:19]
	v_mul_f32_e32 v18, 0xbfb8aa3b, v12
	v_mul_f32_e32 v19, 0xbfb8aa3b, v13
	v_exp_f32_e32 v18, v18
	v_exp_f32_e32 v19, v19
	v_exp_f32_e32 v20, v20
	v_exp_f32_e32 v21, v21
	v_add_f32_e32 v18, 1.0, v18
	v_add_f32_e32 v19, 1.0, v19
	v_rcp_f32_e32 v18, v18
	v_rcp_f32_e32 v19, v19
	v_add_f32_e32 v20, 1.0, v20
	v_add_f32_e32 v21, 1.0, v21
	v_rcp_f32_e32 v20, v20
	v_rcp_f32_e32 v21, v21
	v_pk_mul_f32 v[12:13], v[12:13], v[18:19]
	v_add_u32_e32 v32, 0xa0, v154
	v_pk_mul_f32 v[8:9], v[12:13], v[8:9]
	v_pk_mul_f32 v[12:13], v[14:15], v[20:21]
	v_cvt_pk_bf16_f32 v8, v8, v9
	v_mul_f32_e32 v9, 0xbfb8aa3b, v4
	v_pk_mul_f32 v[10:11], v[12:13], v[10:11]
	v_exp_f32_e32 v12, v9
	v_mul_f32_e32 v9, 0xbfb8aa3b, v5
	v_exp_f32_e32 v13, v9
	v_cvt_pk_bf16_f32 v9, v10, v11
	v_add_f32_e32 v10, 1.0, v12
	v_mul_f32_e32 v12, 0xbfb8aa3b, v6
	v_add_f32_e32 v11, 1.0, v13
	v_mul_f32_e32 v13, 0xbfb8aa3b, v7
	v_exp_f32_e32 v12, v12
	v_exp_f32_e32 v13, v13
	v_rcp_f32_e32 v10, v10
	v_rcp_f32_e32 v11, v11
	v_add_f32_e32 v12, 1.0, v12
	v_add_f32_e32 v13, 1.0, v13
	v_rcp_f32_e32 v12, v12
	v_rcp_f32_e32 v13, v13
	v_pk_mul_f32 v[4:5], v[4:5], v[10:11]
	v_cvt_pk_bf16_f32 v27, v16, v17
	v_pk_mul_f32 v[0:1], v[4:5], v[0:1]
	v_add_u32_e32 v16, 0xb0, v154
	v_cvt_pk_bf16_f32 v10, v0, v1
	v_pk_mul_f32 v[0:1], v[6:7], v[12:13]
	v_mad_i64_i32 v[156:157], s[18:19], v154, s55, v[146:147]
	v_lshlrev_b64 v[144:145], 1, v[144:145]
	v_mad_i64_i32 v[112:113], s[18:19], v112, s55, v[146:147]
	v_mad_i64_i32 v[96:97], s[18:19], v96, s55, v[146:147]
	v_mad_i64_i32 v[80:81], s[18:19], v80, s55, v[146:147]
	v_mad_i64_i32 v[64:65], s[18:19], v64, s55, v[146:147]
	v_mad_i64_i32 v[48:49], s[18:19], v48, s55, v[146:147]
	v_mad_i64_i32 v[32:33], s[18:19], v32, s55, v[146:147]
	v_mad_i64_i32 v[16:17], s[18:19], v16, s55, v[146:147]
	v_pk_mul_f32 v[0:1], v[0:1], v[2:3]
	v_lshl_add_u64 v[156:157], v[156:157], 0, v[144:145]
	v_lshl_add_u64 v[112:113], v[112:113], 0, v[144:145]
	v_lshl_add_u64 v[96:97], v[96:97], 0, v[144:145]
	v_lshl_add_u64 v[80:81], v[80:81], 0, v[144:145]
	v_lshl_add_u64 v[64:65], v[64:65], 0, v[144:145]
	v_lshl_add_u64 v[48:49], v[48:49], 0, v[144:145]
	v_lshl_add_u64 v[32:33], v[32:33], 0, v[144:145]
	v_lshl_add_u64 v[16:17], v[16:17], 0, v[144:145]
	v_cvt_pk_bf16_f32 v11, v0, v1
	s_and_b64 vcc, exec, s[2:3]
	s_mov_b32 s56, s8
	s_mov_b32 s16, s10
	s_mov_b64 s[20:21], s[14:15]
	s_mov_b64 s[18:19], s[12:13]
	global_store_dwordx4 v[156:157], v[120:123], off
	global_store_dwordx4 v[112:113], v[104:107], off
	global_store_dwordx4 v[96:97], v[88:91], off
	global_store_dwordx4 v[80:81], v[72:75], off
	global_store_dwordx4 v[64:65], v[56:59], off
	global_store_dwordx4 v[48:49], v[40:43], off
	global_store_dwordx4 v[32:33], v[24:27], off
	global_store_dwordx4 v[16:17], v[8:11], off
	s_cbranch_vccz .LBB0_1138
	s_waitcnt vmcnt(0)
	s_cmpk_gt_u32 s31, 0xff
	s_cbranch_scc1 .LBB0_1145
	s_barrier

; #define PG8_STAGE(bufoff, gbase, voff) do { _Pragma("unroll") for (int _i = 0; _i < 2; ++_i) \
;         __builtin_amdgcn_global_load_lds((const unsigned*)((const char*)(gbase) + (voff)[_i]), (LAS unsigned*)(lds + (bufoff) + ldsw + _i * 8192), 16, 0, 0); } while (0)
; #define PG8_WAIT_V(n) asm volatile("s_waitcnt vmcnt(" #n ")" ::: "memory")
; #define PG8_BAR __builtin_amdgcn_s_barrier()
; template <class Epi, class Order>
; __device__ __forceinline__ void gemm_phase(LAS unsigned char* lds, const Gemm g, const Order& S, const Epi& E) {
;     ...
;     PG8_STAGE(PG8_SB(0, 0), cB, voffB); PG8_STAGE(PG8_SA(0, 0), cA, voffA); PG8_STAGE(PG8_SB(0, 1), cB + hstep, voffB); PG8_STAGE(PG8_SA(0, 1), cA + hstep, voffA);
;     if (wr == 1) PG8_BAR;
;     PG8_WAIT_V(4); PG8_BAR;
;     PG8_STAGE(PG8_SB(1, 0), cB + kstep, voffB); PG8_STAGE(PG8_SA(1, 0), cA + kstep, voffA); PG8_STAGE(PG8_SB(1, 1), cB + hstep + kstep, voffB);
;     PG8_WAIT_V(6); PG8_BAR;
.LBB0_1204:
	s_add_u32 s10, s48, 0x2000
	s_addc_u32 s11, s49, 0
	s_add_u32 s12, s50, 0x2000
	s_addc_u32 s13, s51, 0
	s_lshl_b32 s2, s2, 5
	s_and_b32 s5, s2, 0x60
	s_ashr_i32 s58, s28, 31
	s_lshl_b32 s4, s0, 13
	s_lshl_b32 s18, s5, 7
	s_add_u32 s14, s88, 0x280000
	s_mov_b64 s[16:17], 0x80
	s_addc_u32 s15, s89, 0
	s_add_i32 m0, s53, 0x18000
	v_lshl_add_u64 v[6:7], v[6:7], 0, s[16:17]
	s_waitcnt vmcnt(4)
	s_barrier
	global_load_lds_dwordx4 v[6:7], off
	v_lshl_add_u64 v[4:5], v[4:5], 0, s[16:17]
	s_add_i32 m0, s53, 0x1a000
	s_add_i32 s59, s53, 0x8000
	s_add_i32 s60, s53, 0xa000
	global_load_lds_dwordx4 v[4:5], off
	v_lshl_add_u64 v[2:3], v[2:3], 0, s[16:17]
	s_mov_b32 m0, s59
	s_add_u32 s2, s42, 0x160080
	global_load_lds_dwordx4 v[2:3], off
	v_lshl_add_u64 v[0:1], v[0:1], 0, s[16:17]
	s_mov_b32 m0, s60
	s_addc_u32 s3, s43, 0
	global_load_lds_dwordx4 v[0:1], off
	s_add_i32 m0, s53, 0x1c000
	s_nop 0
	global_load_lds_dwordx4 v182, s[2:3]
	s_add_i32 m0, s53, 0x1e000
	s_sext_i32_i8 s71, s1
	global_load_lds_dwordx4 v184, s[2:3]
	v_bfe_u32 v0, v241, 4, 2
	v_and_b32_e32 v1, 15, v241
	v_lshlrev_b32_e32 v2, 4, v0
	v_lshlrev_b32_e32 v3, 6, v241
	s_movk_i32 s1, 0x3c0
	v_lshlrev_b32_e32 v4, 2, v241
	v_and_or_b32 v3, v3, s1, v2
	v_and_b32_e32 v4, 32, v4
	v_lshl_or_b32 v181, s0, 6, v1
	v_lshl_or_b32 v1, v1, 6, v2
	s_waitcnt vmcnt(6)
	v_bitop3_b32 v1, v1, s4, v4 bitop3:0xde
	v_bitop3_b32 v236, s18, v3, v4 bitop3:0xf6
	s_add_i32 s62, 0, 0x10000
	s_add_i32 s63, 0, 0x14000
	s_mov_b32 s61, s28
	v_lshl_or_b32 v237, v0, 2, s5
	v_add3_u32 v186, v10, v8, v9
	v_mov_b32_e32 v187, v183
	v_add3_u32 v188, v11, v8, v9
	v_mov_b32_e32 v189, v183
	v_mov_b64_e32 v[190:191], 0x400
	v_mov_b64_e32 v[192:193], 0x3ff
	v_add_u32_e32 v238, s62, v236
	v_add_u32_e32 v239, 0, v1
	v_add_u32_e32 v241, s63, v236
	s_mov_b64 s[18:19], 0x100000
	s_mov_b32 s64, 0x100000
	s_mov_b64 s[20:21], 0x120000
	s_mov_b32 s65, 0x120000
	s_mov_b64 s[22:23], 0x140000
	s_mov_b32 s66, 0x140000
	s_mov_b32 s67, 0x160000
	s_mov_b32 s36, 0x3f9837f0
	s_barrier
	s_branch .LBB0_1206

; #define PG8_STAGE(bufoff, gbase, voff) do { _Pragma("unroll") for (int _i = 0; _i < 2; ++_i) \
;         __builtin_amdgcn_global_load_lds((const unsigned*)((const char*)(gbase) + (voff)[_i]), (LAS unsigned*)(lds + (bufoff) + ldsw + _i * 8192), 16, 0, 0); } while (0)
; #define PG8_LDA(dst, b, h) do { _Pragma("unroll") for (int m = 0; m < 4; ++m) _Pragma("unroll") for (int k = 0; k < 2; ++k) dst[m][k] = *(const LAS bf16x8*)(lds + PG8_SA(b, h) + aoff + m * 2048 + k * 1024); } while (0)
; #define PG8_LDB(dst, b, h) do { _Pragma("unroll") for (int n = 0; n < 2; ++n) _Pragma("unroll") for (int k = 0; k < 2; ++k) dst[n][k] = *(const LAS bf16x8*)(lds + PG8_SB(b, h) + boff + n * 2048 + k * 1024); } while (0)
; #define PG8_MMA(ai, bj, At, Bt) do { __builtin_amdgcn_s_setprio(1); _Pragma("unroll") for (int m = 0; m < 4; ++m) _Pragma("unroll") for (int n = 0; n < 2; ++n) _Pragma("unroll") for (int k = 0; k < 2; ++k) \
;         acc[ai][bj][m][n] = __builtin_amdgcn_mfma_f32_16x16x32_bf16(Bt[n][k], At[m][k], acc[ai][bj][m][n], 0, 0, 0); __builtin_amdgcn_s_setprio(0); } while (0)
; #define PG8_WAIT_L(n) asm volatile("s_waitcnt lgkmcnt(" #n ")" ::: "memory")
; #define PG8_BAR __builtin_amdgcn_s_barrier()
; #define PG8_SCHED __builtin_amdgcn_sched_barrier(0)
; template <class Epi, class Order>
; __device__ __forceinline__ void gemm_phase(LAS unsigned char* lds, const Gemm g, const Order& S, const Epi& E) {
;     ...
;             PG8_LDB(B0, 0, 0); PG8_SCHED; PG8_LDA(At, 0, 0); PG8_STAGE(PG8_SA(1, 1), a1 + hstep, voffA);
;             PG8_WAIT_L(8); PG8_BAR; PG8_WAIT_L(0); PG8_MMA(0, 0, At, B0); PG8_BAR; PG8_SCHED;
;             PG8_LDB(B1, 0, 1); PG8_STAGE(PG8_SB(0, 0), b2, voffB);
;             PG8_BAR; PG8_WAIT_L(0); PG8_MMA(0, 1, At, B1); PG8_BAR;
;             PG8_LDA(At, 0, 1); PG8_STAGE(PG8_SA(0, 0), a2, voffA);
;             PG8_BAR; PG8_WAIT_L(0); PG8_MMA(1, 0, At, B0); PG8_BAR; PG8_SCHED;
.LBB0_1217:
	ds_read_b128 v[128:131], v238
	ds_read_b128 v[132:135], v238 offset:1024
	ds_read_b128 v[136:139], v238 offset:2048
	ds_read_b128 v[140:143], v238 offset:3072
	s_add_u32 s24, s40, 0xffea0080
	s_addc_u32 s25, s41, -1
	s_cmpk_eq_i32 s74, 0x54
	s_cselect_b32 s45, s1, s25
	s_cselect_b32 s44, s0, s24
	s_cselect_b32 s43, s5, s73
	s_cselect_b32 s42, s4, s72
	v_lshl_add_u64 v[176:177], s[40:41], 0, v[186:187]
	s_add_i32 m0, s53, 0xc000
	ds_read_b128 v[144:147], v239
	ds_read_b128 v[148:151], v239 offset:1024
	ds_read_b128 v[152:155], v239 offset:2048
	ds_read_b128 v[156:159], v239 offset:3072
	ds_read_b128 v[160:163], v239 offset:4096
	ds_read_b128 v[164:167], v239 offset:5120
	ds_read_b128 v[168:171], v239 offset:6144
	ds_read_b128 v[172:175], v239 offset:7168
	global_load_lds_dwordx4 v[176:177], off
	v_lshl_add_u64 v[176:177], s[40:41], 0, v[188:189]
	s_add_i32 m0, s53, 0xe000
	s_nop 0
	global_load_lds_dwordx4 v[176:177], off
	s_waitcnt lgkmcnt(8)
	s_barrier
	s_waitcnt lgkmcnt(0)
	s_setprio 1
	s_waitcnt lgkmcnt(0)
	v_mfma_f32_16x16x32_bf16 v[124:127], v[128:131], v[144:147], v[124:127]
	v_mfma_f32_16x16x32_bf16 v[104:107], v[136:139], v[144:147], v[104:107]
	v_mfma_f32_16x16x32_bf16 v[120:123], v[128:131], v[152:155], v[120:123]
	v_mfma_f32_16x16x32_bf16 v[96:99], v[136:139], v[152:155], v[96:99]
	v_mfma_f32_16x16x32_bf16 v[116:119], v[128:131], v[160:163], v[116:119]
	v_mfma_f32_16x16x32_bf16 v[88:91], v[136:139], v[160:163], v[88:91]
	v_mfma_f32_16x16x32_bf16 v[112:115], v[128:131], v[168:171], v[112:115]
	v_mfma_f32_16x16x32_bf16 v[80:83], v[136:139], v[168:171], v[80:83]
	v_mfma_f32_16x16x32_bf16 v[124:127], v[132:135], v[148:151], v[124:127]
	v_mfma_f32_16x16x32_bf16 v[104:107], v[140:143], v[148:151], v[104:107]
	v_mfma_f32_16x16x32_bf16 v[120:123], v[132:135], v[156:159], v[120:123]
	v_mfma_f32_16x16x32_bf16 v[96:99], v[140:143], v[156:159], v[96:99]
	v_mfma_f32_16x16x32_bf16 v[116:119], v[132:135], v[164:167], v[116:119]
	v_mfma_f32_16x16x32_bf16 v[88:91], v[140:143], v[164:167], v[88:91]
	v_mfma_f32_16x16x32_bf16 v[112:115], v[132:135], v[172:175], v[112:115]
	v_mfma_f32_16x16x32_bf16 v[80:83], v[140:143], v[172:175], v[80:83]
	s_setprio 0
	s_barrier
	s_add_i32 s24, s62, s47
	v_lshl_add_u64 v[206:207], s[42:43], 0, v[182:183]
	s_mov_b32 m0, s24
	ds_read_b128 v[176:179], v241
	ds_read_b128 v[194:197], v241 offset:1024
	ds_read_b128 v[198:201], v241 offset:2048
	ds_read_b128 v[202:205], v241 offset:3072
	global_load_lds_dwordx4 v[206:207], off
	v_lshl_add_u64 v[208:209], s[42:43], 0, v[184:185]
	s_add_i32 m0, s24, 0x2000
	s_nop 0
	global_load_lds_dwordx4 v[208:209], off
	s_barrier
	s_waitcnt lgkmcnt(0)
	s_setprio 1
	s_waitcnt lgkmcnt(0)
	v_mfma_f32_16x16x32_bf16 v[68:71], v[176:179], v[144:147], v[68:71]
	v_mfma_f32_16x16x32_bf16 v[40:43], v[198:201], v[144:147], v[40:43]
	v_mfma_f32_16x16x32_bf16 v[60:63], v[176:179], v[152:155], v[60:63]
	v_mfma_f32_16x16x32_bf16 v[28:31], v[198:201], v[152:155], v[28:31]
	v_mfma_f32_16x16x32_bf16 v[52:55], v[176:179], v[160:163], v[52:55]
	v_mfma_f32_16x16x32_bf16 v[20:23], v[198:201], v[160:163], v[20:23]
	v_mfma_f32_16x16x32_bf16 v[48:51], v[176:179], v[168:171], v[48:51]
	v_mfma_f32_16x16x32_bf16 v[16:19], v[198:201], v[168:171], v[16:19]
	v_mfma_f32_16x16x32_bf16 v[68:71], v[194:197], v[148:151], v[68:71]
	v_mfma_f32_16x16x32_bf16 v[40:43], v[202:205], v[148:151], v[40:43]
	v_mfma_f32_16x16x32_bf16 v[60:63], v[194:197], v[156:159], v[60:63]
	v_mfma_f32_16x16x32_bf16 v[28:31], v[202:205], v[156:159], v[28:31]
	v_mfma_f32_16x16x32_bf16 v[52:55], v[194:197], v[164:167], v[52:55]
	v_mfma_f32_16x16x32_bf16 v[20:23], v[202:205], v[164:167], v[20:23]
	v_mfma_f32_16x16x32_bf16 v[48:51], v[194:197], v[172:175], v[48:51]
	v_mfma_f32_16x16x32_bf16 v[16:19], v[202:205], v[172:175], v[16:19]
	s_setprio 0
	s_mov_b32 m0, s53
	v_lshl_add_u64 v[210:211], s[44:45], 0, v[182:183]
	s_barrier
	ds_read_b128 v[144:147], v239 offset:16384
	ds_read_b128 v[148:151], v239 offset:17408
	ds_read_b128 v[152:155], v239 offset:18432
	ds_read_b128 v[156:159], v239 offset:19456
	ds_read_b128 v[160:163], v239 offset:20480
	ds_read_b128 v[164:167], v239 offset:21504
	ds_read_b128 v[168:171], v239 offset:22528
	ds_read_b128 v[172:175], v239 offset:23552
	global_load_lds_dwordx4 v[210:211], off
	v_lshl_add_u64 v[212:213], s[44:45], 0, v[184:185]
	s_mov_b32 m0, s54
	s_nop 0
	global_load_lds_dwordx4 v[212:213], off
	s_barrier
	s_waitcnt lgkmcnt(0)
	s_setprio 1
	s_waitcnt lgkmcnt(0)
	v_mfma_f32_16x16x32_bf16 v[108:111], v[128:131], v[144:147], v[108:111]
	v_mfma_f32_16x16x32_bf16 v[76:79], v[136:139], v[144:147], v[76:79]
	v_mfma_f32_16x16x32_bf16 v[100:103], v[128:131], v[152:155], v[100:103]
	v_mfma_f32_16x16x32_bf16 v[72:75], v[136:139], v[152:155], v[72:75]
	v_mfma_f32_16x16x32_bf16 v[92:95], v[128:131], v[160:163], v[92:95]
	v_mfma_f32_16x16x32_bf16 v[64:67], v[136:139], v[160:163], v[64:67]
	v_mfma_f32_16x16x32_bf16 v[84:87], v[128:131], v[168:171], v[84:87]
	v_mfma_f32_16x16x32_bf16 v[56:59], v[136:139], v[168:171], v[56:59]
	v_mfma_f32_16x16x32_bf16 v[108:111], v[132:135], v[148:151], v[108:111]
	v_mfma_f32_16x16x32_bf16 v[76:79], v[140:143], v[148:151], v[76:79]
	v_mfma_f32_16x16x32_bf16 v[100:103], v[132:135], v[156:159], v[100:103]
	v_mfma_f32_16x16x32_bf16 v[72:75], v[140:143], v[156:159], v[72:75]
	v_mfma_f32_16x16x32_bf16 v[92:95], v[132:135], v[164:167], v[92:95]
	v_mfma_f32_16x16x32_bf16 v[64:67], v[140:143], v[164:167], v[64:67]
	v_mfma_f32_16x16x32_bf16 v[84:87], v[132:135], v[172:175], v[84:87]
	v_mfma_f32_16x16x32_bf16 v[56:59], v[140:143], v[172:175], v[56:59]
	s_setprio 0
	s_barrier
; #define PG8_STAGE(bufoff, gbase, voff) do { _Pragma("unroll") for (int _i = 0; _i < 2; ++_i) \
;         __builtin_amdgcn_global_load_lds((const unsigned*)((const char*)(gbase) + (voff)[_i]), (LAS unsigned*)(lds + (bufoff) + ldsw + _i * 8192), 16, 0, 0); } while (0)
; #define PG8_LDA(dst, b, h) do { _Pragma("unroll") for (int m = 0; m < 4; ++m) _Pragma("unroll") for (int k = 0; k < 2; ++k) dst[m][k] = *(const LAS bf16x8*)(lds + PG8_SA(b, h) + aoff + m * 2048 + k * 1024); } while (0)
; #define PG8_LDB(dst, b, h) do { _Pragma("unroll") for (int n = 0; n < 2; ++n) _Pragma("unroll") for (int k = 0; k < 2; ++k) dst[n][k] = *(const LAS bf16x8*)(lds + PG8_SB(b, h) + boff + n * 2048 + k * 1024); } while (0)
; #define PG8_MMA(ai, bj, At, Bt) do { __builtin_amdgcn_s_setprio(1); _Pragma("unroll") for (int m = 0; m < 4; ++m) _Pragma("unroll") for (int n = 0; n < 2; ++n) _Pragma("unroll") for (int k = 0; k < 2; ++k) \
;         acc[ai][bj][m][n] = __builtin_amdgcn_mfma_f32_16x16x32_bf16(Bt[n][k], At[m][k], acc[ai][bj][m][n], 0, 0, 0); __builtin_amdgcn_s_setprio(0); } while (0)
; #define PG8_WAIT_V(n) asm volatile("s_waitcnt vmcnt(" #n ")" ::: "memory")
; #define PG8_WAIT_L(n) asm volatile("s_waitcnt lgkmcnt(" #n ")" ::: "memory")
; #define PG8_BAR __builtin_amdgcn_s_barrier()
; #define PG8_SCHED __builtin_amdgcn_sched_barrier(0)
; template <class Epi, class Order>
; __device__ __forceinline__ void gemm_phase(LAS unsigned char* lds, const Gemm g, const Order& S, const Epi& E) {
;     ...
;             PG8_STAGE(PG8_SB(0, 1), b2 + hstep, voffB);
;             PG8_WAIT_V(6); PG8_BAR; PG8_MMA(1, 1, At, B1); PG8_BAR;
;             PG8_LDB(B0, 1, 0); PG8_SCHED; PG8_LDA(At, 1, 0); PG8_STAGE(PG8_SA(0, 1), a2 + hstep, voffA);
;             PG8_WAIT_L(8); PG8_BAR; PG8_WAIT_L(0); PG8_MMA(0, 0, At, B0); PG8_BAR; PG8_SCHED;
;             PG8_LDB(B1, 1, 1); PG8_STAGE(PG8_SB(1, 0), b3, voffB);
;             PG8_BAR; PG8_WAIT_L(0); PG8_MMA(0, 1, At, B1); PG8_BAR;
;             PG8_LDA(At, 1, 1); PG8_STAGE(PG8_SA(1, 0), a3, voffA);
	s_add_u32 s24, s42, 0x160000
	s_addc_u32 s25, s43, 0
	s_add_i32 s27, s63, s47
	s_mov_b32 m0, s27
	s_nop 0
	global_load_lds_dwordx4 v182, s[24:25]
	s_add_i32 m0, s27, 0x2000
	s_nop 0
	global_load_lds_dwordx4 v184, s[24:25]
	s_waitcnt vmcnt(6)
	s_barrier
	s_setprio 1
	v_mfma_f32_16x16x32_bf16 v[44:47], v[176:179], v[144:147], v[44:47]
	v_mfma_f32_16x16x32_bf16 v[12:15], v[198:201], v[144:147], v[12:15]
	v_mfma_f32_16x16x32_bf16 v[36:39], v[176:179], v[152:155], v[36:39]
	v_mfma_f32_16x16x32_bf16 v[8:11], v[198:201], v[152:155], v[8:11]
	v_mfma_f32_16x16x32_bf16 v[32:35], v[176:179], v[160:163], v[32:35]
	v_mfma_f32_16x16x32_bf16 v[4:7], v[198:201], v[160:163], v[4:7]
	v_mfma_f32_16x16x32_bf16 v[24:27], v[176:179], v[168:171], v[24:27]
	v_mfma_f32_16x16x32_bf16 v[0:3], v[198:201], v[168:171], v[0:3]
	v_mfma_f32_16x16x32_bf16 v[44:47], v[194:197], v[148:151], v[44:47]
	v_mfma_f32_16x16x32_bf16 v[12:15], v[202:205], v[148:151], v[12:15]
	v_mfma_f32_16x16x32_bf16 v[36:39], v[194:197], v[156:159], v[36:39]
	v_mfma_f32_16x16x32_bf16 v[8:11], v[202:205], v[156:159], v[8:11]
	v_mfma_f32_16x16x32_bf16 v[32:35], v[194:197], v[164:167], v[32:35]
	v_mfma_f32_16x16x32_bf16 v[4:7], v[202:205], v[164:167], v[4:7]
	v_mfma_f32_16x16x32_bf16 v[24:27], v[194:197], v[172:175], v[24:27]
	v_mfma_f32_16x16x32_bf16 v[0:3], v[202:205], v[172:175], v[0:3]
	s_setprio 0
	s_add_i32 s27, 0, 0x18000
	v_add_u32_e32 v140, s27, v236
	s_barrier
	ds_read_b128 v[128:131], v140
	ds_read_b128 v[132:135], v140 offset:1024
	ds_read_b128 v[136:139], v140 offset:2048
	ds_read_b128 v[140:143], v140 offset:3072
	s_add_u32 s24, s44, 0x160000
	s_addc_u32 s25, s45, 0
	s_mov_b32 m0, s55
	ds_read_b128 v[144:147], v239 offset:32768
	ds_read_b128 v[148:151], v239 offset:33792
	ds_read_b128 v[152:155], v239 offset:34816
	ds_read_b128 v[156:159], v239 offset:35840
	ds_read_b128 v[160:163], v239 offset:36864
	ds_read_b128 v[164:167], v239 offset:37888
	ds_read_b128 v[168:171], v239 offset:38912
	ds_read_b128 v[172:175], v239 offset:39936
	global_load_lds_dwordx4 v182, s[24:25]
	s_mov_b32 m0, s56
	s_nop 0
	global_load_lds_dwordx4 v184, s[24:25]
	s_waitcnt lgkmcnt(8)
	s_barrier
	s_waitcnt lgkmcnt(0)
	s_setprio 1
	s_waitcnt lgkmcnt(0)
	v_mfma_f32_16x16x32_bf16 v[124:127], v[128:131], v[144:147], v[124:127]
	v_mfma_f32_16x16x32_bf16 v[104:107], v[136:139], v[144:147], v[104:107]
	v_mfma_f32_16x16x32_bf16 v[120:123], v[128:131], v[152:155], v[120:123]
	v_mfma_f32_16x16x32_bf16 v[96:99], v[136:139], v[152:155], v[96:99]
	v_mfma_f32_16x16x32_bf16 v[116:119], v[128:131], v[160:163], v[116:119]
	v_mfma_f32_16x16x32_bf16 v[88:91], v[136:139], v[160:163], v[88:91]
	v_mfma_f32_16x16x32_bf16 v[112:115], v[128:131], v[168:171], v[112:115]
	v_mfma_f32_16x16x32_bf16 v[80:83], v[136:139], v[168:171], v[80:83]
	v_mfma_f32_16x16x32_bf16 v[124:127], v[132:135], v[148:151], v[124:127]
	v_mfma_f32_16x16x32_bf16 v[104:107], v[140:143], v[148:151], v[104:107]
	v_mfma_f32_16x16x32_bf16 v[120:123], v[132:135], v[156:159], v[120:123]
	v_mfma_f32_16x16x32_bf16 v[96:99], v[140:143], v[156:159], v[96:99]
	v_mfma_f32_16x16x32_bf16 v[116:119], v[132:135], v[164:167], v[116:119]
	v_mfma_f32_16x16x32_bf16 v[88:91], v[140:143], v[164:167], v[88:91]
	v_mfma_f32_16x16x32_bf16 v[112:115], v[132:135], v[172:175], v[112:115]
	v_mfma_f32_16x16x32_bf16 v[80:83], v[140:143], v[172:175], v[80:83]
	s_setprio 0
	s_barrier
	s_add_i32 s44, 0, 0x1c000
	s_add_i32 s24, s27, s47
	v_add_u32_e32 v202, s44, v236
	v_lshl_add_u64 v[206:207], v[206:207], 0, s[16:17]
	s_mov_b32 m0, s24
	ds_read_b128 v[176:179], v202
	ds_read_b128 v[194:197], v202 offset:1024
	ds_read_b128 v[198:201], v202 offset:2048
	ds_read_b128 v[202:205], v202 offset:3072
	global_load_lds_dwordx4 v[206:207], off
	v_lshl_add_u64 v[206:207], v[208:209], 0, s[16:17]
	s_add_i32 m0, s24, 0x2000
	s_nop 0
	global_load_lds_dwordx4 v[206:207], off
	s_barrier
; #define PG8_STAGE(bufoff, gbase, voff) do { _Pragma("unroll") for (int _i = 0; _i < 2; ++_i) \
;         __builtin_amdgcn_global_load_lds((const unsigned*)((const char*)(gbase) + (voff)[_i]), (LAS unsigned*)(lds + (bufoff) + ldsw + _i * 8192), 16, 0, 0); } while (0)
; #define PG8_MMA(ai, bj, At, Bt) do { __builtin_amdgcn_s_setprio(1); _Pragma("unroll") for (int m = 0; m < 4; ++m) _Pragma("unroll") for (int n = 0; n < 2; ++n) _Pragma("unroll") for (int k = 0; k < 2; ++k) \
;         acc[ai][bj][m][n] = __builtin_amdgcn_mfma_f32_16x16x32_bf16(Bt[n][k], At[m][k], acc[ai][bj][m][n], 0, 0, 0); __builtin_amdgcn_s_setprio(0); } while (0)
; #define PG8_WAIT_V(n) asm volatile("s_waitcnt vmcnt(" #n ")" ::: "memory")
; #define PG8_WAIT_L(n) asm volatile("s_waitcnt lgkmcnt(" #n ")" ::: "memory")
; #define PG8_BAR __builtin_amdgcn_s_barrier()
; #define PG8_SCHED __builtin_amdgcn_sched_barrier(0)
; template <class Epi, class Order>
; __device__ __forceinline__ void gemm_phase(LAS unsigned char* lds, const Gemm g, const Order& S, const Epi& E) {
;     ...
;             PG8_BAR; PG8_WAIT_L(0); PG8_MMA(1, 0, At, B0); PG8_BAR; PG8_SCHED;
;             PG8_STAGE(PG8_SB(1, 1), b3 + hstep, voffB);
;             PG8_WAIT_V(6); PG8_BAR; PG8_MMA(1, 1, At, B1); PG8_BAR;
;         }
;         E(acc, cur, wr, wc, fr, fq);
;     __device__ __forceinline__ void operator()(const f32x4 (&acc)[2][2][4][2], const pg8::Unit& u, int wr, int wc, int fr, int fq) const {
;         const bool isx = u.pm < (MX / 256);
;         const int mr = isx ? (u.pm >> 4) : 8;
;         const float* gate = modv + (size_t)mr * MODW + gslot * D;
	s_waitcnt lgkmcnt(0)
	s_setprio 1
	s_waitcnt lgkmcnt(0)
	v_mfma_f32_16x16x32_bf16 v[68:71], v[176:179], v[144:147], v[68:71]
	v_mfma_f32_16x16x32_bf16 v[40:43], v[198:201], v[144:147], v[40:43]
	v_mfma_f32_16x16x32_bf16 v[60:63], v[176:179], v[152:155], v[60:63]
	v_mfma_f32_16x16x32_bf16 v[28:31], v[198:201], v[152:155], v[28:31]
	v_mfma_f32_16x16x32_bf16 v[52:55], v[176:179], v[160:163], v[52:55]
	v_mfma_f32_16x16x32_bf16 v[20:23], v[198:201], v[160:163], v[20:23]
	v_mfma_f32_16x16x32_bf16 v[48:51], v[176:179], v[168:171], v[48:51]
	v_mfma_f32_16x16x32_bf16 v[16:19], v[198:201], v[168:171], v[16:19]
	v_mfma_f32_16x16x32_bf16 v[68:71], v[194:197], v[148:151], v[68:71]
	v_mfma_f32_16x16x32_bf16 v[40:43], v[202:205], v[148:151], v[40:43]
	v_mfma_f32_16x16x32_bf16 v[60:63], v[194:197], v[156:159], v[60:63]
	v_mfma_f32_16x16x32_bf16 v[28:31], v[202:205], v[156:159], v[28:31]
	v_mfma_f32_16x16x32_bf16 v[52:55], v[194:197], v[164:167], v[52:55]
	v_mfma_f32_16x16x32_bf16 v[20:23], v[202:205], v[164:167], v[20:23]
	v_mfma_f32_16x16x32_bf16 v[48:51], v[194:197], v[172:175], v[48:51]
	v_mfma_f32_16x16x32_bf16 v[16:19], v[202:205], v[172:175], v[16:19]
	s_setprio 0
	s_mov_b32 m0, s59
	v_lshl_add_u64 v[206:207], v[210:211], 0, s[16:17]
	s_barrier
	ds_read_b128 v[144:147], v239 offset:49152
	ds_read_b128 v[148:151], v239 offset:50176
	ds_read_b128 v[152:155], v239 offset:51200
	ds_read_b128 v[156:159], v239 offset:52224
	ds_read_b128 v[160:163], v239 offset:53248
	ds_read_b128 v[164:167], v239 offset:54272
	ds_read_b128 v[168:171], v239 offset:55296
	ds_read_b128 v[172:175], v239 offset:56320
	global_load_lds_dwordx4 v[206:207], off
	v_lshl_add_u64 v[206:207], v[212:213], 0, s[16:17]
	s_mov_b32 m0, s60
	s_nop 0
	global_load_lds_dwordx4 v[206:207], off
	s_barrier
	s_waitcnt lgkmcnt(0)
	s_setprio 1
	s_waitcnt lgkmcnt(0)
	v_mfma_f32_16x16x32_bf16 v[108:111], v[128:131], v[144:147], v[108:111]
	v_mfma_f32_16x16x32_bf16 v[76:79], v[136:139], v[144:147], v[76:79]
	v_mfma_f32_16x16x32_bf16 v[100:103], v[128:131], v[152:155], v[100:103]
	v_mfma_f32_16x16x32_bf16 v[72:75], v[136:139], v[152:155], v[72:75]
	v_mfma_f32_16x16x32_bf16 v[92:95], v[128:131], v[160:163], v[92:95]
	v_mfma_f32_16x16x32_bf16 v[64:67], v[136:139], v[160:163], v[64:67]
	v_mfma_f32_16x16x32_bf16 v[84:87], v[128:131], v[168:171], v[84:87]
	v_mfma_f32_16x16x32_bf16 v[56:59], v[136:139], v[168:171], v[56:59]
	v_mfma_f32_16x16x32_bf16 v[108:111], v[132:135], v[148:151], v[108:111]
	v_mfma_f32_16x16x32_bf16 v[76:79], v[140:143], v[148:151], v[76:79]
	v_mfma_f32_16x16x32_bf16 v[100:103], v[132:135], v[156:159], v[100:103]
	v_mfma_f32_16x16x32_bf16 v[72:75], v[140:143], v[156:159], v[72:75]
	v_mfma_f32_16x16x32_bf16 v[92:95], v[132:135], v[164:167], v[92:95]
	v_mfma_f32_16x16x32_bf16 v[64:67], v[140:143], v[164:167], v[64:67]
	v_mfma_f32_16x16x32_bf16 v[84:87], v[132:135], v[172:175], v[84:87]
	v_mfma_f32_16x16x32_bf16 v[56:59], v[140:143], v[172:175], v[56:59]
	s_setprio 0
	s_barrier
	s_add_u32 s24, s42, 0x160080
	s_addc_u32 s25, s43, 0
	s_add_i32 s27, s44, s47
	s_mov_b32 m0, s27
	s_nop 0
	global_load_lds_dwordx4 v182, s[24:25]
	v_lshl_add_u64 v[128:129], s[24:25], 0, v[184:185]
	s_add_i32 m0, s27, 0x2000
	s_nop 0
	global_load_lds_dwordx4 v[128:129], off
	s_waitcnt vmcnt(6)
	s_barrier
	s_setprio 1
	v_mfma_f32_16x16x32_bf16 v[44:47], v[176:179], v[144:147], v[44:47]
	v_mfma_f32_16x16x32_bf16 v[12:15], v[198:201], v[144:147], v[12:15]
	v_mfma_f32_16x16x32_bf16 v[36:39], v[176:179], v[152:155], v[36:39]
	v_mfma_f32_16x16x32_bf16 v[8:11], v[198:201], v[152:155], v[8:11]
	v_mfma_f32_16x16x32_bf16 v[32:35], v[176:179], v[160:163], v[32:35]
	v_mfma_f32_16x16x32_bf16 v[4:7], v[198:201], v[160:163], v[4:7]
	v_mfma_f32_16x16x32_bf16 v[24:27], v[176:179], v[168:171], v[24:27]
	v_mfma_f32_16x16x32_bf16 v[0:3], v[198:201], v[168:171], v[0:3]
	v_mfma_f32_16x16x32_bf16 v[44:47], v[194:197], v[148:151], v[44:47]
	v_mfma_f32_16x16x32_bf16 v[12:15], v[202:205], v[148:151], v[12:15]
	v_mfma_f32_16x16x32_bf16 v[36:39], v[194:197], v[156:159], v[36:39]
	v_mfma_f32_16x16x32_bf16 v[8:11], v[202:205], v[156:159], v[8:11]
	v_mfma_f32_16x16x32_bf16 v[32:35], v[194:197], v[164:167], v[32:35]
	v_mfma_f32_16x16x32_bf16 v[4:7], v[202:205], v[164:167], v[4:7]
	v_mfma_f32_16x16x32_bf16 v[24:27], v[194:197], v[172:175], v[24:27]
	v_mfma_f32_16x16x32_bf16 v[0:3], v[202:205], v[172:175], v[0:3]
	s_setprio 0
	s_add_i32 s74, s74, 2
	s_add_u32 s40, s40, 0x100
	s_addc_u32 s41, s41, 0
	s_add_u32 s72, s72, 0x100
	s_addc_u32 s73, s73, 0
	s_cmpk_gt_u32 s74, 0x55
	s_barrier
	s_cbranch_scc0 .LBB0_1217
	s_cmpk_lt_i32 s70, 0x80
	s_mov_b64 s[40:41], 0x24000
	s_cselect_b64 s[44:45], -1, 0
	s_cmpk_gt_i32 s70, 0x7f
	s_mov_b64 s[42:43], s[38:39]
	s_cbranch_scc1 .LBB0_1205
	s_ashr_i32 s24, s70, 4
	s_mul_hi_i32 s41, s24, 0x4800
	s_mul_i32 s40, s24, 0x4800
	s_mov_b64 s[42:43], s[86:87]
	s_branch .LBB0_1205
